# GEMM tiles: accumulators initialised by the first MFMA of each tile (C operand = 0) instead of 154 v_mov per tile; the all-zero carried-fragment MFMA group of the first K-step removed
# baseline (speedup 1.0000x reference)
.Lgin0_tile:
	s_mov_b32 s46, 0x40000
	s_mov_b32 s47, 0x80000
	s_mov_b32 s58, 0xc0000
	s_waitcnt vmcnt(8)
	ds_write_b128 v170, v[216:219] offset:0
	ds_write_b128 v170, v[220:223] offset:9216
	ds_write_b128 v170, v[224:227] offset:18432
	ds_write_b128 v170, v[228:231] offset:27648
	ds_write_b128 v171, v[232:235] offset:0
	ds_write_b128 v171, v[236:239] offset:9216
	ds_write_b128 v171, v[152:155] offset:18432
	ds_write_b128 v171, v[156:159] offset:27648
	buffer_load_dwordx4 v[216:219], v160, s[48:51], 0 offen
	buffer_load_dwordx4 v[220:223], v160, s[48:51], s46 offen
	buffer_load_dwordx4 v[224:227], v160, s[48:51], s47 offen
	buffer_load_dwordx4 v[228:231], v160, s[48:51], s58 offen
	buffer_load_dwordx4 v[232:235], v160, s[52:55], 0 offen
	buffer_load_dwordx4 v[236:239], v160, s[52:55], s46 offen
	buffer_load_dwordx4 v[152:155], v160, s[52:55], s47 offen
	buffer_load_dwordx4 v[156:159], v160, s[52:55], s58 offen
	v_add_u32_e32 v160, 0x80, v160
	s_waitcnt lgkmcnt(0)
	s_barrier
	ds_read_b128 v[144:147], v254 offset:0
	ds_read_b128 v[148:151], v254 offset:4608
	ds_read_b128 v[128:131], v175 offset:0
	ds_read_b128 v[132:135], v175 offset:4608
	ds_read_b128 v[136:139], v175 offset:9216
	ds_read_b128 v[140:143], v175 offset:13824
	s_waitcnt vmcnt(8)
	ds_write_b128 v170, v[162:165] offset:36864
	ds_write_b128 v170, v[166:169] offset:46080
	ds_write_b128 v170, v[176:179] offset:55296
	ds_write_b128 v170, v[180:183] offset:64512
	ds_write_b128 v171, v[184:187] offset:36864
	ds_write_b128 v171, v[242:245] offset:46080
	ds_write_b128 v171, v[246:249] offset:55296
	ds_write_b128 v171, v[250:253] offset:64512
	s_waitcnt lgkmcnt(8)
	v_mfma_f32_32x32x16_bf16 v[112:127], v[128:131], v[144:147], 0
	ds_read_b128 v[208:211], v254 offset:32
	v_mfma_f32_32x32x16_bf16 v[96:111], v[128:131], v[148:151], 0
	ds_read_b128 v[212:215], v254 offset:4640
	ds_read_b128 v[192:195], v175 offset:32
	v_mfma_f32_32x32x16_bf16 v[80:95], v[132:135], v[144:147], 0
	ds_read_b128 v[196:199], v175 offset:4640
	ds_read_b128 v[200:203], v175 offset:9248
	v_mfma_f32_32x32x16_bf16 v[64:79], v[132:135], v[148:151], 0
	ds_read_b128 v[204:207], v175 offset:13856
	buffer_load_dwordx4 v[162:165], v160, s[48:51], 0 offen
	v_mfma_f32_32x32x16_bf16 v[48:63], v[136:139], v[144:147], 0
	buffer_load_dwordx4 v[166:169], v160, s[48:51], s46 offen
	buffer_load_dwordx4 v[176:179], v160, s[48:51], s47 offen
	v_mfma_f32_32x32x16_bf16 v[32:47], v[136:139], v[148:151], 0
	buffer_load_dwordx4 v[180:183], v160, s[48:51], s58 offen
	buffer_load_dwordx4 v[184:187], v160, s[52:55], 0 offen
	v_mfma_f32_32x32x16_bf16 v[16:31], v[140:143], v[144:147], 0
	buffer_load_dwordx4 v[242:245], v160, s[52:55], s46 offen
	buffer_load_dwordx4 v[246:249], v160, s[52:55], s47 offen
	v_mfma_f32_32x32x16_bf16 v[0:15], v[140:143], v[148:151], 0
	buffer_load_dwordx4 v[250:253], v160, s[52:55], s58 offen
	v_add_u32_e32 v160, 0x80, v160
	s_waitcnt lgkmcnt(0)
	v_mfma_f32_32x32x16_bf16 v[112:127], v[192:195], v[208:211], v[112:127]
	v_mfma_f32_32x32x16_bf16 v[96:111], v[192:195], v[212:215], v[96:111]
	ds_read_b128 v[144:147], v254 offset:64
	v_mfma_f32_32x32x16_bf16 v[80:95], v[196:199], v[208:211], v[80:95]
	ds_read_b128 v[148:151], v254 offset:4672
	v_mfma_f32_32x32x16_bf16 v[64:79], v[196:199], v[212:215], v[64:79]
	ds_read_b128 v[128:131], v175 offset:64
	v_mfma_f32_32x32x16_bf16 v[48:63], v[200:203], v[208:211], v[48:63]
	v_mfma_f32_32x32x16_bf16 v[32:47], v[200:203], v[212:215], v[32:47]
	ds_read_b128 v[132:135], v175 offset:4672
	v_mfma_f32_32x32x16_bf16 v[16:31], v[204:207], v[208:211], v[16:31]
	ds_read_b128 v[136:139], v175 offset:9280
	v_mfma_f32_32x32x16_bf16 v[0:15], v[204:207], v[212:215], v[0:15]
	ds_read_b128 v[140:143], v175 offset:13888
	s_waitcnt lgkmcnt(0)
	v_mfma_f32_32x32x16_bf16 v[112:127], v[128:131], v[144:147], v[112:127]
	v_mfma_f32_32x32x16_bf16 v[96:111], v[128:131], v[148:151], v[96:111]
	ds_read_b128 v[208:211], v254 offset:96
	v_mfma_f32_32x32x16_bf16 v[80:95], v[132:135], v[144:147], v[80:95]
	ds_read_b128 v[212:215], v254 offset:4704
	v_mfma_f32_32x32x16_bf16 v[64:79], v[132:135], v[148:151], v[64:79]
	ds_read_b128 v[192:195], v175 offset:96
	v_mfma_f32_32x32x16_bf16 v[48:63], v[136:139], v[144:147], v[48:63]
	v_mfma_f32_32x32x16_bf16 v[32:47], v[136:139], v[148:151], v[32:47]
	ds_read_b128 v[196:199], v175 offset:4704
	v_mfma_f32_32x32x16_bf16 v[16:31], v[140:143], v[144:147], v[16:31]
	ds_read_b128 v[200:203], v175 offset:9312
	v_mfma_f32_32x32x16_bf16 v[0:15], v[140:143], v[148:151], v[0:15]
	ds_read_b128 v[204:207], v175 offset:13920
	s_waitcnt lgkmcnt(0)
	s_barrier
	ds_read_b128 v[144:147], v254 offset:36864
	ds_read_b128 v[148:151], v254 offset:41472
	ds_read_b128 v[128:131], v175 offset:36864
	ds_read_b128 v[132:135], v175 offset:41472
	ds_read_b128 v[136:139], v175 offset:46080
	ds_read_b128 v[140:143], v175 offset:50688
	v_mfma_f32_32x32x16_bf16 v[112:127], v[192:195], v[208:211], v[112:127]
	s_waitcnt vmcnt(8)
	v_mfma_f32_32x32x16_bf16 v[96:111], v[192:195], v[212:215], v[96:111]
	ds_write_b128 v170, v[216:219] offset:0
	v_mfma_f32_32x32x16_bf16 v[80:95], v[196:199], v[208:211], v[80:95]
	ds_write_b128 v170, v[220:223] offset:9216
	v_mfma_f32_32x32x16_bf16 v[64:79], v[196:199], v[212:215], v[64:79]
	ds_write_b128 v170, v[224:227] offset:18432
	v_mfma_f32_32x32x16_bf16 v[48:63], v[200:203], v[208:211], v[48:63]
	ds_write_b128 v170, v[228:231] offset:27648
	v_mfma_f32_32x32x16_bf16 v[32:47], v[200:203], v[212:215], v[32:47]
	ds_write_b128 v171, v[232:235] offset:0
	v_mfma_f32_32x32x16_bf16 v[16:31], v[204:207], v[208:211], v[16:31]
	ds_write_b128 v171, v[236:239] offset:9216
	v_mfma_f32_32x32x16_bf16 v[0:15], v[204:207], v[212:215], v[0:15]
	ds_write_b128 v171, v[152:155] offset:18432
	ds_write_b128 v171, v[156:159] offset:27648
	s_waitcnt lgkmcnt(8)
	v_mfma_f32_32x32x16_bf16 v[112:127], v[128:131], v[144:147], v[112:127]
	ds_read_b128 v[208:211], v254 offset:36896
	v_mfma_f32_32x32x16_bf16 v[96:111], v[128:131], v[148:151], v[96:111]
	ds_read_b128 v[212:215], v254 offset:41504
	ds_read_b128 v[192:195], v175 offset:36896
	v_mfma_f32_32x32x16_bf16 v[80:95], v[132:135], v[144:147], v[80:95]
	ds_read_b128 v[196:199], v175 offset:41504
	ds_read_b128 v[200:203], v175 offset:46112
	v_mfma_f32_32x32x16_bf16 v[64:79], v[132:135], v[148:151], v[64:79]
	ds_read_b128 v[204:207], v175 offset:50720
	buffer_load_dwordx4 v[216:219], v160, s[48:51], 0 offen
	v_mfma_f32_32x32x16_bf16 v[48:63], v[136:139], v[144:147], v[48:63]
	buffer_load_dwordx4 v[220:223], v160, s[48:51], s46 offen
	buffer_load_dwordx4 v[224:227], v160, s[48:51], s47 offen
	v_mfma_f32_32x32x16_bf16 v[32:47], v[136:139], v[148:151], v[32:47]
	buffer_load_dwordx4 v[228:231], v160, s[48:51], s58 offen
	buffer_load_dwordx4 v[232:235], v160, s[52:55], 0 offen
	v_mfma_f32_32x32x16_bf16 v[16:31], v[140:143], v[144:147], v[16:31]
	buffer_load_dwordx4 v[236:239], v160, s[52:55], s46 offen
	buffer_load_dwordx4 v[152:155], v160, s[52:55], s47 offen
	v_mfma_f32_32x32x16_bf16 v[0:15], v[140:143], v[148:151], v[0:15]
	buffer_load_dwordx4 v[156:159], v160, s[52:55], s58 offen
	v_add_u32_e32 v160, 0x80, v160
	s_waitcnt lgkmcnt(0)
	v_mfma_f32_32x32x16_bf16 v[112:127], v[192:195], v[208:211], v[112:127]
	v_mfma_f32_32x32x16_bf16 v[96:111], v[192:195], v[212:215], v[96:111]
	ds_read_b128 v[144:147], v254 offset:36928
	v_mfma_f32_32x32x16_bf16 v[80:95], v[196:199], v[208:211], v[80:95]
	ds_read_b128 v[148:151], v254 offset:41536
	v_mfma_f32_32x32x16_bf16 v[64:79], v[196:199], v[212:215], v[64:79]
	ds_read_b128 v[128:131], v175 offset:36928
	v_mfma_f32_32x32x16_bf16 v[48:63], v[200:203], v[208:211], v[48:63]
	v_mfma_f32_32x32x16_bf16 v[32:47], v[200:203], v[212:215], v[32:47]
	ds_read_b128 v[132:135], v175 offset:41536
	v_mfma_f32_32x32x16_bf16 v[16:31], v[204:207], v[208:211], v[16:31]
	ds_read_b128 v[136:139], v175 offset:46144
	v_mfma_f32_32x32x16_bf16 v[0:15], v[204:207], v[212:215], v[0:15]
	ds_read_b128 v[140:143], v175 offset:50752
	s_waitcnt lgkmcnt(0)
	v_mfma_f32_32x32x16_bf16 v[112:127], v[128:131], v[144:147], v[112:127]
	v_mfma_f32_32x32x16_bf16 v[96:111], v[128:131], v[148:151], v[96:111]
	ds_read_b128 v[208:211], v254 offset:36960
	v_mfma_f32_32x32x16_bf16 v[80:95], v[132:135], v[144:147], v[80:95]
	ds_read_b128 v[212:215], v254 offset:41568
	v_mfma_f32_32x32x16_bf16 v[64:79], v[132:135], v[148:151], v[64:79]
	ds_read_b128 v[192:195], v175 offset:36960
	v_mfma_f32_32x32x16_bf16 v[48:63], v[136:139], v[144:147], v[48:63]
	v_mfma_f32_32x32x16_bf16 v[32:47], v[136:139], v[148:151], v[32:47]
	ds_read_b128 v[196:199], v175 offset:41568
	v_mfma_f32_32x32x16_bf16 v[16:31], v[140:143], v[144:147], v[16:31]
	ds_read_b128 v[200:203], v175 offset:46176
	v_mfma_f32_32x32x16_bf16 v[0:15], v[140:143], v[148:151], v[0:15]
	ds_read_b128 v[204:207], v175 offset:50784
	s_waitcnt lgkmcnt(0)
	s_barrier
	s_movk_i32 s59, 13

.LBB0_786:
.Lgout0_tile:
	s_bfe_u32 s20, s5, 0x30005
	s_and_b32 s21, s5, 31
	s_lshr_b32 s7, s5, 8
	s_lshl_b32 s6, s7, 5
	s_lshr_b32 s7, s20, 3
	s_lshl_b32 s7, s7, 5
	s_add_u32 s6, s6, s7
	s_lshr_b32 s7, s21, 0
	s_add_u32 s6, s6, s7
	s_and_b32 s7, s20, 7
	s_lshl_b32 s7, s7, 0
	s_and_b32 s21, s21, 0
	s_add_u32 s7, s7, s21
	s_lshl_b32 s6, s6, 8
	s_lshl_b32 s7, s7, 8
	s_lshl_b32 s20, s6, 12
	s_add_u32 s20, s20, 0xe224000
	s_add_u32 s8, s92, s20
	s_addc_u32 s9, s93, 0
	s_and_b32 s9, s9, 0xffff
	s_mov_b32 s10, 0x100000
	s_mov_b32 s11, 0x20000
	s_lshl_b32 s20, s7, 12
	s_add_u32 s20, s20, 0x1380000
	s_add_u32 s24, s92, s20
	s_addc_u32 s25, s93, 0
	s_and_b32 s25, s25, 0xffff
	s_sub_u32 s20, 0x800, s7
	s_min_u32 s20, s20, 0x100
	s_lshl_b32 s26, s20, 12
	s_mov_b32 s27, 0x20000
	s_mov_b32 s28, 0x40000
	s_mov_b32 s29, 0x80000
	s_mov_b32 s30, 0xc0000
	v_lshrrev_b32_e32 v128, 3, v190
	v_and_b32_e32 v129, 7, v190
	v_lshlrev_b32_e32 v129, 4, v129
	v_lshl_add_u32 v160, v128, 12, v129
	v_mul_u32_u24_e32 v130, 0x90, v128
	v_add_u32_e32 v170, v130, v129
	v_add_u32_e32 v171, 0x12000, v170
	v_and_b32_e32 v131, 31, v190
	v_bfe_u32 v132, v190, 5, 1
	v_bfe_u32 v133, v190, 6, 2
	v_bfe_u32 v134, v190, 8, 1
	v_lshl_add_u32 v135, v134, 7, v131
	v_mul_u32_u24_e32 v135, 0x90, v135
	v_lshl_add_u32 v175, v132, 4, v135
	v_lshl_add_u32 v136, v133, 6, v131
	v_mul_u32_u24_e32 v136, 0x90, v136
	v_lshl_add_u32 v136, v132, 4, v136
	v_add_u32_e32 v254, 0x12000, v136
	buffer_load_dwordx4 v[216:219], v160, s[8:11], 0 offen
	buffer_load_dwordx4 v[220:223], v160, s[8:11], s28 offen
	buffer_load_dwordx4 v[224:227], v160, s[8:11], s29 offen
	buffer_load_dwordx4 v[228:231], v160, s[8:11], s30 offen
	buffer_load_dwordx4 v[232:235], v160, s[24:27], 0 offen
	buffer_load_dwordx4 v[236:239], v160, s[24:27], s28 offen
	buffer_load_dwordx4 v[152:155], v160, s[24:27], s29 offen
	buffer_load_dwordx4 v[156:159], v160, s[24:27], s30 offen
	v_add_u32_e32 v160, 0x80, v160
	buffer_load_dwordx4 v[162:165], v160, s[8:11], 0 offen
	buffer_load_dwordx4 v[166:169], v160, s[8:11], s28 offen
	buffer_load_dwordx4 v[176:179], v160, s[8:11], s29 offen
	buffer_load_dwordx4 v[180:183], v160, s[8:11], s30 offen
	buffer_load_dwordx4 v[184:187], v160, s[24:27], 0 offen
	buffer_load_dwordx4 v[242:245], v160, s[24:27], s28 offen
	buffer_load_dwordx4 v[246:249], v160, s[24:27], s29 offen
	buffer_load_dwordx4 v[250:253], v160, s[24:27], s30 offen
	v_add_u32_e32 v160, 0x80, v160
	s_waitcnt vmcnt(8)
	ds_write_b128 v170, v[216:219] offset:0
	ds_write_b128 v170, v[220:223] offset:9216
	ds_write_b128 v170, v[224:227] offset:18432
	ds_write_b128 v170, v[228:231] offset:27648
	ds_write_b128 v171, v[232:235] offset:0
	ds_write_b128 v171, v[236:239] offset:9216
	ds_write_b128 v171, v[152:155] offset:18432
	ds_write_b128 v171, v[156:159] offset:27648
	buffer_load_dwordx4 v[216:219], v160, s[8:11], 0 offen
	buffer_load_dwordx4 v[220:223], v160, s[8:11], s28 offen
	buffer_load_dwordx4 v[224:227], v160, s[8:11], s29 offen
	buffer_load_dwordx4 v[228:231], v160, s[8:11], s30 offen
	buffer_load_dwordx4 v[232:235], v160, s[24:27], 0 offen
	buffer_load_dwordx4 v[236:239], v160, s[24:27], s28 offen
	buffer_load_dwordx4 v[152:155], v160, s[24:27], s29 offen
	buffer_load_dwordx4 v[156:159], v160, s[24:27], s30 offen
	v_add_u32_e32 v160, 0x80, v160
	s_waitcnt lgkmcnt(0)
	s_barrier
	ds_read_b128 v[144:147], v254 offset:0
	ds_read_b128 v[148:151], v254 offset:4608
	ds_read_b128 v[128:131], v175 offset:0
	ds_read_b128 v[132:135], v175 offset:4608
	ds_read_b128 v[136:139], v175 offset:9216
	ds_read_b128 v[140:143], v175 offset:13824
	s_waitcnt vmcnt(8)
	ds_write_b128 v170, v[162:165] offset:36864
	ds_write_b128 v170, v[166:169] offset:46080
	ds_write_b128 v170, v[176:179] offset:55296
	ds_write_b128 v170, v[180:183] offset:64512
	ds_write_b128 v171, v[184:187] offset:36864
	ds_write_b128 v171, v[242:245] offset:46080
	ds_write_b128 v171, v[246:249] offset:55296
	ds_write_b128 v171, v[250:253] offset:64512
	s_waitcnt lgkmcnt(8)
	v_mfma_f32_32x32x16_bf16 v[112:127], v[128:131], v[144:147], 0
	ds_read_b128 v[208:211], v254 offset:32
	v_mfma_f32_32x32x16_bf16 v[96:111], v[128:131], v[148:151], 0
	ds_read_b128 v[212:215], v254 offset:4640
	ds_read_b128 v[192:195], v175 offset:32
	v_mfma_f32_32x32x16_bf16 v[80:95], v[132:135], v[144:147], 0
	ds_read_b128 v[196:199], v175 offset:4640
	ds_read_b128 v[200:203], v175 offset:9248
	v_mfma_f32_32x32x16_bf16 v[64:79], v[132:135], v[148:151], 0
	ds_read_b128 v[204:207], v175 offset:13856
	buffer_load_dwordx4 v[162:165], v160, s[8:11], 0 offen
	v_mfma_f32_32x32x16_bf16 v[48:63], v[136:139], v[144:147], 0
	buffer_load_dwordx4 v[166:169], v160, s[8:11], s28 offen
	buffer_load_dwordx4 v[176:179], v160, s[8:11], s29 offen
	v_mfma_f32_32x32x16_bf16 v[32:47], v[136:139], v[148:151], 0
	buffer_load_dwordx4 v[180:183], v160, s[8:11], s30 offen
	buffer_load_dwordx4 v[184:187], v160, s[24:27], 0 offen
	v_mfma_f32_32x32x16_bf16 v[16:31], v[140:143], v[144:147], 0
	buffer_load_dwordx4 v[242:245], v160, s[24:27], s28 offen
	buffer_load_dwordx4 v[246:249], v160, s[24:27], s29 offen
	v_mfma_f32_32x32x16_bf16 v[0:15], v[140:143], v[148:151], 0
	buffer_load_dwordx4 v[250:253], v160, s[24:27], s30 offen
	v_add_u32_e32 v160, 0x80, v160
	s_waitcnt lgkmcnt(0)
	v_mfma_f32_32x32x16_bf16 v[112:127], v[192:195], v[208:211], v[112:127]
	v_mfma_f32_32x32x16_bf16 v[96:111], v[192:195], v[212:215], v[96:111]
	ds_read_b128 v[144:147], v254 offset:64
	v_mfma_f32_32x32x16_bf16 v[80:95], v[196:199], v[208:211], v[80:95]
	ds_read_b128 v[148:151], v254 offset:4672
	v_mfma_f32_32x32x16_bf16 v[64:79], v[196:199], v[212:215], v[64:79]
	ds_read_b128 v[128:131], v175 offset:64
	v_mfma_f32_32x32x16_bf16 v[48:63], v[200:203], v[208:211], v[48:63]
	v_mfma_f32_32x32x16_bf16 v[32:47], v[200:203], v[212:215], v[32:47]
	ds_read_b128 v[132:135], v175 offset:4672
	v_mfma_f32_32x32x16_bf16 v[16:31], v[204:207], v[208:211], v[16:31]
	ds_read_b128 v[136:139], v175 offset:9280
	v_mfma_f32_32x32x16_bf16 v[0:15], v[204:207], v[212:215], v[0:15]
	ds_read_b128 v[140:143], v175 offset:13888
	s_waitcnt lgkmcnt(0)
	v_mfma_f32_32x32x16_bf16 v[112:127], v[128:131], v[144:147], v[112:127]
	v_mfma_f32_32x32x16_bf16 v[96:111], v[128:131], v[148:151], v[96:111]
	ds_read_b128 v[208:211], v254 offset:96
	v_mfma_f32_32x32x16_bf16 v[80:95], v[132:135], v[144:147], v[80:95]
	ds_read_b128 v[212:215], v254 offset:4704
	v_mfma_f32_32x32x16_bf16 v[64:79], v[132:135], v[148:151], v[64:79]
	ds_read_b128 v[192:195], v175 offset:96
	v_mfma_f32_32x32x16_bf16 v[48:63], v[136:139], v[144:147], v[48:63]
	v_mfma_f32_32x32x16_bf16 v[32:47], v[136:139], v[148:151], v[32:47]
	ds_read_b128 v[196:199], v175 offset:4704
	v_mfma_f32_32x32x16_bf16 v[16:31], v[140:143], v[144:147], v[16:31]
	ds_read_b128 v[200:203], v175 offset:9312
	v_mfma_f32_32x32x16_bf16 v[0:15], v[140:143], v[148:151], v[0:15]
	ds_read_b128 v[204:207], v175 offset:13920
	s_waitcnt lgkmcnt(0)
	s_barrier
	ds_read_b128 v[144:147], v254 offset:36864
	ds_read_b128 v[148:151], v254 offset:41472
	ds_read_b128 v[128:131], v175 offset:36864
	ds_read_b128 v[132:135], v175 offset:41472
	ds_read_b128 v[136:139], v175 offset:46080
	ds_read_b128 v[140:143], v175 offset:50688
	v_mfma_f32_32x32x16_bf16 v[112:127], v[192:195], v[208:211], v[112:127]
	s_waitcnt vmcnt(8)
	v_mfma_f32_32x32x16_bf16 v[96:111], v[192:195], v[212:215], v[96:111]
	ds_write_b128 v170, v[216:219] offset:0
	v_mfma_f32_32x32x16_bf16 v[80:95], v[196:199], v[208:211], v[80:95]
	ds_write_b128 v170, v[220:223] offset:9216
	v_mfma_f32_32x32x16_bf16 v[64:79], v[196:199], v[212:215], v[64:79]
	ds_write_b128 v170, v[224:227] offset:18432
	v_mfma_f32_32x32x16_bf16 v[48:63], v[200:203], v[208:211], v[48:63]
	ds_write_b128 v170, v[228:231] offset:27648
	v_mfma_f32_32x32x16_bf16 v[32:47], v[200:203], v[212:215], v[32:47]
	ds_write_b128 v171, v[232:235] offset:0
	v_mfma_f32_32x32x16_bf16 v[16:31], v[204:207], v[208:211], v[16:31]
	ds_write_b128 v171, v[236:239] offset:9216
	v_mfma_f32_32x32x16_bf16 v[0:15], v[204:207], v[212:215], v[0:15]
	ds_write_b128 v171, v[152:155] offset:18432
	ds_write_b128 v171, v[156:159] offset:27648
	s_waitcnt lgkmcnt(8)
	v_mfma_f32_32x32x16_bf16 v[112:127], v[128:131], v[144:147], v[112:127]
	ds_read_b128 v[208:211], v254 offset:36896
	v_mfma_f32_32x32x16_bf16 v[96:111], v[128:131], v[148:151], v[96:111]
	ds_read_b128 v[212:215], v254 offset:41504
	ds_read_b128 v[192:195], v175 offset:36896
	v_mfma_f32_32x32x16_bf16 v[80:95], v[132:135], v[144:147], v[80:95]
	ds_read_b128 v[196:199], v175 offset:41504
	ds_read_b128 v[200:203], v175 offset:46112
	v_mfma_f32_32x32x16_bf16 v[64:79], v[132:135], v[148:151], v[64:79]
	ds_read_b128 v[204:207], v175 offset:50720
	buffer_load_dwordx4 v[216:219], v160, s[8:11], 0 offen
	v_mfma_f32_32x32x16_bf16 v[48:63], v[136:139], v[144:147], v[48:63]
	buffer_load_dwordx4 v[220:223], v160, s[8:11], s28 offen
	buffer_load_dwordx4 v[224:227], v160, s[8:11], s29 offen
	v_mfma_f32_32x32x16_bf16 v[32:47], v[136:139], v[148:151], v[32:47]
	buffer_load_dwordx4 v[228:231], v160, s[8:11], s30 offen
	buffer_load_dwordx4 v[232:235], v160, s[24:27], 0 offen
	v_mfma_f32_32x32x16_bf16 v[16:31], v[140:143], v[144:147], v[16:31]
	buffer_load_dwordx4 v[236:239], v160, s[24:27], s28 offen
	buffer_load_dwordx4 v[152:155], v160, s[24:27], s29 offen
	v_mfma_f32_32x32x16_bf16 v[0:15], v[140:143], v[148:151], v[0:15]
	buffer_load_dwordx4 v[156:159], v160, s[24:27], s30 offen
	v_add_u32_e32 v160, 0x80, v160
	s_waitcnt lgkmcnt(0)
	v_mfma_f32_32x32x16_bf16 v[112:127], v[192:195], v[208:211], v[112:127]
	v_mfma_f32_32x32x16_bf16 v[96:111], v[192:195], v[212:215], v[96:111]
	ds_read_b128 v[144:147], v254 offset:36928
	v_mfma_f32_32x32x16_bf16 v[80:95], v[196:199], v[208:211], v[80:95]
	ds_read_b128 v[148:151], v254 offset:41536
	v_mfma_f32_32x32x16_bf16 v[64:79], v[196:199], v[212:215], v[64:79]
	ds_read_b128 v[128:131], v175 offset:36928
	v_mfma_f32_32x32x16_bf16 v[48:63], v[200:203], v[208:211], v[48:63]
	v_mfma_f32_32x32x16_bf16 v[32:47], v[200:203], v[212:215], v[32:47]
	ds_read_b128 v[132:135], v175 offset:41536
	v_mfma_f32_32x32x16_bf16 v[16:31], v[204:207], v[208:211], v[16:31]
	ds_read_b128 v[136:139], v175 offset:46144
	v_mfma_f32_32x32x16_bf16 v[0:15], v[204:207], v[212:215], v[0:15]
	ds_read_b128 v[140:143], v175 offset:50752
	s_waitcnt lgkmcnt(0)
	v_mfma_f32_32x32x16_bf16 v[112:127], v[128:131], v[144:147], v[112:127]
	v_mfma_f32_32x32x16_bf16 v[96:111], v[128:131], v[148:151], v[96:111]
	ds_read_b128 v[208:211], v254 offset:36960
	v_mfma_f32_32x32x16_bf16 v[80:95], v[132:135], v[144:147], v[80:95]
	ds_read_b128 v[212:215], v254 offset:41568
	v_mfma_f32_32x32x16_bf16 v[64:79], v[132:135], v[148:151], v[64:79]
	ds_read_b128 v[192:195], v175 offset:36960
	v_mfma_f32_32x32x16_bf16 v[48:63], v[136:139], v[144:147], v[48:63]
	v_mfma_f32_32x32x16_bf16 v[32:47], v[136:139], v[148:151], v[32:47]
	ds_read_b128 v[196:199], v175 offset:41568
	v_mfma_f32_32x32x16_bf16 v[16:31], v[140:143], v[144:147], v[16:31]
	ds_read_b128 v[200:203], v175 offset:46176
	v_mfma_f32_32x32x16_bf16 v[0:15], v[140:143], v[148:151], v[0:15]
	ds_read_b128 v[204:207], v175 offset:50784
	s_waitcnt lgkmcnt(0)
	s_barrier
	s_movk_i32 s31, 13

.LBB0_1561:
	s_or_b64 exec, exec, s[46:47]
	s_waitcnt lgkmcnt(1)
	v_max_u32_dpp v36, v35, v35 quad_perm:[1,0,3,2] row_mask:0xf bank_mask:0xf bound_ctrl:1
	v_bitop3_b32 v32, v32, s52, v32 bitop3:0xc
	v_bitop3_b32 v33, v33, s52, v33 bitop3:0xc
	v_max_u32_dpp v36, v36, v36 quad_perm:[2,3,0,1] row_mask:0xf bank_mask:0xf bound_ctrl:1
	v_ashrrev_i32_e32 v133, 31, v132
	v_mov_b64_e32 v[74:75], v[18:19]
	v_max_u32_dpp v36, v36, v36 row_half_mirror row_mask:0xf bank_mask:0xf bound_ctrl:1
	v_mov_b64_e32 v[82:83], v[22:23]
	v_mov_b64_e32 v[90:91], v[26:27]
	v_max_u32_dpp v36, v36, v36 row_mirror row_mask:0xf bank_mask:0xf bound_ctrl:1
	v_mov_b64_e32 v[94:95], v[30:31]
	v_readlane_b32 s46, v36, 32
	v_readlane_b32 s47, v36, 48
	v_readlane_b32 s45, v36, 16
	s_max_u32 s46, s46, s47
	v_readlane_b32 s4, v36, 0
	v_mov_b32_e32 v36, s45
	s_waitcnt lgkmcnt(0)
	v_mov_b32_e32 v37, s46
	v_max3_u32 v36, s4, v36, v37
	v_cmp_ne_u32_e32 vcc, v35, v36
	v_cndmask_b32_e64 v36, 0, v36, s[8:9]
	s_mov_b32 s74, 0
	v_cndmask_b32_e32 v35, 0, v35, vcc
	s_mov_b32 s75, 5
	v_mov_b64_e32 v[72:73], v[16:17]
	v_max_u32_dpp v37, v35, v35 quad_perm:[1,0,3,2] row_mask:0xf bank_mask:0xf bound_ctrl:1
	v_mov_b64_e32 v[80:81], v[20:21]
	v_mov_b64_e32 v[88:89], v[24:25]
	v_max_u32_dpp v37, v37, v37 quad_perm:[2,3,0,1] row_mask:0xf bank_mask:0xf bound_ctrl:1
	v_mov_b64_e32 v[92:93], v[28:29]
	v_mov_b32_e32 v58, v34
	v_max_u32_dpp v37, v37, v37 row_half_mirror row_mask:0xf bank_mask:0xf bound_ctrl:1
	v_mov_b32_e32 v59, v34
	v_mov_b32_e32 v56, v34
	v_max_u32_dpp v37, v37, v37 row_mirror row_mask:0xf bank_mask:0xf bound_ctrl:1
	v_mov_b32_e32 v57, v34
	v_readlane_b32 s46, v37, 32
	v_readlane_b32 s47, v37, 48
	v_readlane_b32 s45, v37, 16
	s_max_u32 s46, s46, s47
	v_readlane_b32 s4, v37, 0
	v_mov_b32_e32 v37, s45
	v_mov_b32_e32 v38, s46
	v_max3_u32 v37, s4, v37, v38
	v_cmp_ne_u32_e32 vcc, v35, v37
	v_cndmask_b32_e64 v36, v36, v37, s[10:11]
	v_mov_b32_e32 v62, v34
	v_cndmask_b32_e32 v35, 0, v35, vcc
	v_mov_b32_e32 v63, v34
	v_mov_b32_e32 v60, v34
	v_max_u32_dpp v37, v35, v35 quad_perm:[1,0,3,2] row_mask:0xf bank_mask:0xf bound_ctrl:1
	v_mov_b32_e32 v61, v34
	v_mov_b32_e32 v70, v34
	v_max_u32_dpp v37, v37, v37 quad_perm:[2,3,0,1] row_mask:0xf bank_mask:0xf bound_ctrl:1
	v_mov_b32_e32 v71, v34
	v_mov_b32_e32 v68, v34
	v_max_u32_dpp v37, v37, v37 row_half_mirror row_mask:0xf bank_mask:0xf bound_ctrl:1
	v_mov_b32_e32 v69, v34
	s_nop 0
	v_max_u32_dpp v37, v37, v37 row_mirror row_mask:0xf bank_mask:0xf bound_ctrl:1
	s_nop 0
	v_readlane_b32 s46, v37, 32
	v_readlane_b32 s47, v37, 48
	v_readlane_b32 s45, v37, 16
	s_max_u32 s46, s46, s47
	v_readlane_b32 s4, v37, 0
	v_mov_b32_e32 v37, s45
	v_mov_b32_e32 v38, s46
	v_max3_u32 v37, s4, v37, v38
	v_cmp_ne_u32_e32 vcc, v35, v37
	v_cndmask_b32_e64 v36, v36, v37, s[12:13]
	s_nop 0
	v_cndmask_b32_e32 v35, 0, v35, vcc
	s_nop 1
	v_max_u32_dpp v37, v35, v35 quad_perm:[1,0,3,2] row_mask:0xf bank_mask:0xf bound_ctrl:1
	s_nop 1
	v_max_u32_dpp v37, v37, v37 quad_perm:[2,3,0,1] row_mask:0xf bank_mask:0xf bound_ctrl:1
	s_nop 1
	v_max_u32_dpp v37, v37, v37 row_half_mirror row_mask:0xf bank_mask:0xf bound_ctrl:1
	s_nop 1
	v_max_u32_dpp v37, v37, v37 row_mirror row_mask:0xf bank_mask:0xf bound_ctrl:1
	s_nop 0
	v_readlane_b32 s46, v37, 32
	v_readlane_b32 s47, v37, 48
	v_readlane_b32 s45, v37, 16
	s_max_u32 s46, s46, s47
	v_readlane_b32 s4, v37, 0
	v_mov_b32_e32 v37, s45
	v_mov_b32_e32 v38, s46
	v_max3_u32 v37, s4, v37, v38
	v_cmp_ne_u32_e32 vcc, v35, v37
	v_cndmask_b32_e64 v36, v36, v37, s[14:15]
	s_nop 0
	v_cndmask_b32_e32 v35, 0, v35, vcc
	s_nop 1
	v_max_u32_dpp v37, v35, v35 quad_perm:[1,0,3,2] row_mask:0xf bank_mask:0xf bound_ctrl:1
	s_nop 1
	v_max_u32_dpp v37, v37, v37 quad_perm:[2,3,0,1] row_mask:0xf bank_mask:0xf bound_ctrl:1
	s_nop 1
	v_max_u32_dpp v37, v37, v37 row_half_mirror row_mask:0xf bank_mask:0xf bound_ctrl:1
	s_nop 1
	v_max_u32_dpp v37, v37, v37 row_mirror row_mask:0xf bank_mask:0xf bound_ctrl:1
	s_nop 0
	v_readlane_b32 s46, v37, 32
	v_readlane_b32 s47, v37, 48
	v_readlane_b32 s45, v37, 16
	s_max_u32 s46, s46, s47
	v_readlane_b32 s4, v37, 0
	v_mov_b32_e32 v37, s45
	v_mov_b32_e32 v38, s46
	v_max3_u32 v37, s4, v37, v38
	v_cmp_ne_u32_e32 vcc, v35, v37
	v_cndmask_b32_e64 v36, v36, v37, s[16:17]
	s_nop 0
	v_cndmask_b32_e32 v35, 0, v35, vcc
	s_nop 1
	v_max_u32_dpp v37, v35, v35 quad_perm:[1,0,3,2] row_mask:0xf bank_mask:0xf bound_ctrl:1
	s_nop 1
	v_max_u32_dpp v37, v37, v37 quad_perm:[2,3,0,1] row_mask:0xf bank_mask:0xf bound_ctrl:1
	s_nop 1
	v_max_u32_dpp v37, v37, v37 row_half_mirror row_mask:0xf bank_mask:0xf bound_ctrl:1
	s_nop 1
	v_max_u32_dpp v37, v37, v37 row_mirror row_mask:0xf bank_mask:0xf bound_ctrl:1
	s_nop 0
	v_readlane_b32 s46, v37, 32
	v_readlane_b32 s47, v37, 48
	v_readlane_b32 s45, v37, 16
	s_max_u32 s46, s46, s47
	v_readlane_b32 s4, v37, 0
	v_mov_b32_e32 v37, s45
	v_mov_b32_e32 v38, s46
	v_max3_u32 v37, s4, v37, v38
	v_cmp_ne_u32_e32 vcc, v35, v37
	v_cndmask_b32_e64 v36, v36, v37, s[18:19]
	s_nop 0
	v_cndmask_b32_e32 v35, 0, v35, vcc
	s_nop 1
	v_max_u32_dpp v37, v35, v35 quad_perm:[1,0,3,2] row_mask:0xf bank_mask:0xf bound_ctrl:1
	s_nop 1
	v_max_u32_dpp v37, v37, v37 quad_perm:[2,3,0,1] row_mask:0xf bank_mask:0xf bound_ctrl:1
	s_nop 1
	v_max_u32_dpp v37, v37, v37 row_half_mirror row_mask:0xf bank_mask:0xf bound_ctrl:1
	s_nop 1
	v_max_u32_dpp v37, v37, v37 row_mirror row_mask:0xf bank_mask:0xf bound_ctrl:1
	s_nop 0
	v_readlane_b32 s46, v37, 32
	v_readlane_b32 s47, v37, 48
	v_readlane_b32 s45, v37, 16
	s_max_u32 s46, s46, s47
	v_readlane_b32 s4, v37, 0
	v_mov_b32_e32 v37, s45
	v_mov_b32_e32 v38, s46
	v_max3_u32 v37, s4, v37, v38
	v_cmp_ne_u32_e32 vcc, v35, v37
	v_cndmask_b32_e64 v36, v36, v37, s[20:21]
	s_nop 0
	v_cndmask_b32_e32 v35, 0, v35, vcc
	s_nop 1
	v_max_u32_dpp v37, v35, v35 quad_perm:[1,0,3,2] row_mask:0xf bank_mask:0xf bound_ctrl:1
	s_nop 1
	v_max_u32_dpp v37, v37, v37 quad_perm:[2,3,0,1] row_mask:0xf bank_mask:0xf bound_ctrl:1
	s_nop 1
	v_max_u32_dpp v37, v37, v37 row_half_mirror row_mask:0xf bank_mask:0xf bound_ctrl:1
	s_nop 1
	v_max_u32_dpp v37, v37, v37 row_mirror row_mask:0xf bank_mask:0xf bound_ctrl:1
	s_nop 0
	v_readlane_b32 s46, v37, 32
	v_readlane_b32 s47, v37, 48
	v_readlane_b32 s45, v37, 16
	s_max_u32 s46, s46, s47
	v_readlane_b32 s4, v37, 0
	v_mov_b32_e32 v37, s45
	v_mov_b32_e32 v38, s46
	v_max3_u32 v37, s4, v37, v38
	v_cmp_ne_u32_e32 vcc, v35, v37
	v_cndmask_b32_e64 v36, v36, v37, s[22:23]
	s_nop 0
	v_cndmask_b32_e32 v35, 0, v35, vcc
	s_nop 1
	v_max_u32_dpp v37, v35, v35 quad_perm:[1,0,3,2] row_mask:0xf bank_mask:0xf bound_ctrl:1
	s_nop 1
	v_max_u32_dpp v37, v37, v37 quad_perm:[2,3,0,1] row_mask:0xf bank_mask:0xf bound_ctrl:1
	s_nop 1
	v_max_u32_dpp v37, v37, v37 row_half_mirror row_mask:0xf bank_mask:0xf bound_ctrl:1
	s_nop 1
	v_max_u32_dpp v37, v37, v37 row_mirror row_mask:0xf bank_mask:0xf bound_ctrl:1
	s_nop 0
	v_readlane_b32 s46, v37, 32
	v_readlane_b32 s47, v37, 48
	v_readlane_b32 s45, v37, 16
	s_max_u32 s46, s46, s47
	v_readlane_b32 s4, v37, 0
	v_mov_b32_e32 v37, s45
	v_mov_b32_e32 v38, s46
	v_max3_u32 v37, s4, v37, v38
	v_cmp_ne_u32_e32 vcc, v35, v37
	v_cndmask_b32_e64 v36, v36, v37, s[24:25]
	s_nop 0
	v_cndmask_b32_e32 v35, 0, v35, vcc
	s_nop 1
	v_max_u32_dpp v37, v35, v35 quad_perm:[1,0,3,2] row_mask:0xf bank_mask:0xf bound_ctrl:1
	s_nop 1
	v_max_u32_dpp v37, v37, v37 quad_perm:[2,3,0,1] row_mask:0xf bank_mask:0xf bound_ctrl:1
	s_nop 1
	v_max_u32_dpp v37, v37, v37 row_half_mirror row_mask:0xf bank_mask:0xf bound_ctrl:1
	s_nop 1
	v_max_u32_dpp v37, v37, v37 row_mirror row_mask:0xf bank_mask:0xf bound_ctrl:1
	s_nop 0
	v_readlane_b32 s46, v37, 32
	v_readlane_b32 s47, v37, 48
	v_readlane_b32 s45, v37, 16
	s_max_u32 s46, s46, s47
	v_readlane_b32 s4, v37, 0
	v_mov_b32_e32 v37, s45
	v_mov_b32_e32 v38, s46
	v_max3_u32 v37, s4, v37, v38
	v_cmp_ne_u32_e32 vcc, v35, v37
	v_cndmask_b32_e64 v36, v36, v37, s[26:27]
	s_nop 0
	v_cndmask_b32_e32 v35, 0, v35, vcc
	s_nop 1
	v_max_u32_dpp v37, v35, v35 quad_perm:[1,0,3,2] row_mask:0xf bank_mask:0xf bound_ctrl:1
	s_nop 1
	v_max_u32_dpp v37, v37, v37 quad_perm:[2,3,0,1] row_mask:0xf bank_mask:0xf bound_ctrl:1
	s_nop 1
	v_max_u32_dpp v37, v37, v37 row_half_mirror row_mask:0xf bank_mask:0xf bound_ctrl:1
	s_nop 1
	v_max_u32_dpp v37, v37, v37 row_mirror row_mask:0xf bank_mask:0xf bound_ctrl:1
	s_nop 0
	v_readlane_b32 s46, v37, 32
	v_readlane_b32 s47, v37, 48
	v_readlane_b32 s45, v37, 16
	s_max_u32 s46, s46, s47
	v_readlane_b32 s4, v37, 0
	v_mov_b32_e32 v37, s45
	v_mov_b32_e32 v38, s46
	v_max3_u32 v37, s4, v37, v38
	v_cmp_ne_u32_e32 vcc, v35, v37
	v_cndmask_b32_e64 v36, v36, v37, s[28:29]
	s_nop 0
	v_cndmask_b32_e32 v35, 0, v35, vcc
	s_nop 1
	v_max_u32_dpp v37, v35, v35 quad_perm:[1,0,3,2] row_mask:0xf bank_mask:0xf bound_ctrl:1
	s_nop 1
	v_max_u32_dpp v37, v37, v37 quad_perm:[2,3,0,1] row_mask:0xf bank_mask:0xf bound_ctrl:1
	s_nop 1
	v_max_u32_dpp v37, v37, v37 row_half_mirror row_mask:0xf bank_mask:0xf bound_ctrl:1
	s_nop 1
	v_max_u32_dpp v37, v37, v37 row_mirror row_mask:0xf bank_mask:0xf bound_ctrl:1
	s_nop 0
	v_readlane_b32 s46, v37, 32
	v_readlane_b32 s47, v37, 48
	v_readlane_b32 s45, v37, 16
	s_max_u32 s46, s46, s47
	v_readlane_b32 s4, v37, 0
	v_mov_b32_e32 v37, s45
	v_mov_b32_e32 v38, s46
	v_max3_u32 v37, s4, v37, v38
	v_cmp_ne_u32_e32 vcc, v35, v37
	v_cndmask_b32_e64 v36, v36, v37, s[30:31]
	s_nop 0
	v_cndmask_b32_e32 v35, 0, v35, vcc
	s_nop 1
	v_max_u32_dpp v37, v35, v35 quad_perm:[1,0,3,2] row_mask:0xf bank_mask:0xf bound_ctrl:1
	s_nop 1
	v_max_u32_dpp v37, v37, v37 quad_perm:[2,3,0,1] row_mask:0xf bank_mask:0xf bound_ctrl:1
	s_nop 1
	v_max_u32_dpp v37, v37, v37 row_half_mirror row_mask:0xf bank_mask:0xf bound_ctrl:1
	s_nop 1
	v_max_u32_dpp v37, v37, v37 row_mirror row_mask:0xf bank_mask:0xf bound_ctrl:1
	s_nop 0
	v_readlane_b32 s46, v37, 32
	v_readlane_b32 s47, v37, 48
	v_readlane_b32 s45, v37, 16
	s_max_u32 s46, s46, s47
	v_readlane_b32 s4, v37, 0
	v_mov_b32_e32 v37, s45
	v_mov_b32_e32 v38, s46
	v_max3_u32 v37, s4, v37, v38
	v_cmp_ne_u32_e32 vcc, v35, v37
	v_cndmask_b32_e64 v44, v36, v37, s[34:35]
	s_ashr_i32 s45, s44, 31
	v_cndmask_b32_e32 v35, 0, v35, vcc
	s_lshl_b64 s[46:47], s[44:45], 12
	v_lshl_add_u64 v[48:49], v[114:115], 0, s[46:47]
	v_max_u32_dpp v36, v35, v35 quad_perm:[1,0,3,2] row_mask:0xf bank_mask:0xf bound_ctrl:1
	s_nop 1
	v_max_u32_dpp v45, v36, v36 quad_perm:[2,3,0,1] row_mask:0xf bank_mask:0xf bound_ctrl:1
	global_load_dwordx4 v[36:39], v[48:49], off offset:16
	global_load_dwordx4 v[40:43], v[48:49], off
	v_max_u32_dpp v45, v45, v45 row_half_mirror row_mask:0xf bank_mask:0xf bound_ctrl:1
	s_waitcnt vmcnt(1)
	v_lshlrev_b32_e32 v142, 16, v36
	v_max_u32_dpp v45, v45, v45 row_mirror row_mask:0xf bank_mask:0xf bound_ctrl:1
	s_waitcnt vmcnt(0)
	v_lshlrev_b32_e32 v134, 16, v40
	v_readlane_b32 s47, v45, 32
	v_readlane_b32 s48, v45, 48
	v_readlane_b32 s46, v45, 16
	s_max_u32 s47, s47, s48
	v_readlane_b32 s4, v45, 0
	v_mov_b32_e32 v45, s46
	v_mov_b32_e32 v46, s47
	v_max3_u32 v45, s4, v45, v46
	v_cmp_ne_u32_e32 vcc, v35, v45
	v_cndmask_b32_e64 v52, v44, v45, s[36:37]
	global_load_dwordx4 v[44:47], v[48:49], off offset:2064
	s_nop 0
	global_load_dwordx4 v[48:51], v[48:49], off offset:2048
	v_cndmask_b32_e32 v35, 0, v35, vcc
	v_and_b32_e32 v135, 0xffff0000, v40
	v_lshlrev_b32_e32 v136, 16, v41
	v_max_u32_dpp v53, v35, v35 quad_perm:[1,0,3,2] row_mask:0xf bank_mask:0xf bound_ctrl:1
	v_and_b32_e32 v137, 0xffff0000, v41
	v_lshlrev_b32_e32 v138, 16, v42
	v_max_u32_dpp v53, v53, v53 quad_perm:[2,3,0,1] row_mask:0xf bank_mask:0xf bound_ctrl:1
	v_and_b32_e32 v139, 0xffff0000, v42
	v_lshlrev_b32_e32 v140, 16, v43
	v_max_u32_dpp v53, v53, v53 row_half_mirror row_mask:0xf bank_mask:0xf bound_ctrl:1
	v_and_b32_e32 v141, 0xffff0000, v43
	v_and_b32_e32 v143, 0xffff0000, v36
	v_max_u32_dpp v53, v53, v53 row_mirror row_mask:0xf bank_mask:0xf bound_ctrl:1
	v_lshlrev_b32_e32 v144, 16, v37
	v_readlane_b32 s47, v53, 32
	v_readlane_b32 s48, v53, 48
	v_readlane_b32 s46, v53, 16
	s_max_u32 s47, s47, s48
	v_readlane_b32 s4, v53, 0
	v_mov_b32_e32 v53, s46
	v_mov_b32_e32 v54, s47
	v_max3_u32 v53, s4, v53, v54
	v_cmp_ne_u32_e32 vcc, v35, v53
	v_cndmask_b32_e64 v52, v52, v53, s[38:39]
	v_and_b32_e32 v145, 0xffff0000, v37
	v_cndmask_b32_e32 v35, 0, v35, vcc
	v_lshlrev_b32_e32 v146, 16, v38
	v_and_b32_e32 v147, 0xffff0000, v38
	v_max_u32_dpp v35, v35, v35 quad_perm:[1,0,3,2] row_mask:0xf bank_mask:0xf bound_ctrl:1
	v_lshlrev_b32_e32 v148, 16, v39
	v_and_b32_e32 v149, 0xffff0000, v39
	v_max_u32_dpp v35, v35, v35 quad_perm:[2,3,0,1] row_mask:0xf bank_mask:0xf bound_ctrl:1
	v_mov_b32_e32 v38, v34
	v_mov_b32_e32 v39, v34
	v_max_u32_dpp v35, v35, v35 row_half_mirror row_mask:0xf bank_mask:0xf bound_ctrl:1
	v_mov_b32_e32 v36, v34
	v_mov_b32_e32 v37, v34
	v_max_u32_dpp v35, v35, v35 row_mirror row_mask:0xf bank_mask:0xf bound_ctrl:1
	v_mov_b32_e32 v42, v34
	v_readlane_b32 s47, v35, 32
	v_readlane_b32 s48, v35, 48
	v_readlane_b32 s46, v35, 16
	s_max_u32 s47, s47, s48
	v_readlane_b32 s4, v35, 0
	v_mov_b32_e32 v35, s46
	v_mov_b32_e32 v53, s47
	v_max3_u32 v35, s4, v35, v53
	v_cndmask_b32_e64 v35, v52, v35, s[40:41]
	v_and_or_b32 v52, v35, 63, v172
	v_lshlrev_b32_e32 v52, 2, v52
	v_xor_b32_e32 v52, 0xfc, v52
	v_cmp_lt_i32_e32 vcc, -1, v35
	ds_bpermute_b32 v53, v52, v171
	ds_bpermute_b32 v52, v52, v167
	v_cndmask_b32_e64 v54, v169, -1, vcc
	v_bitop3_b32 v35, v54, v35, s3 bitop3:0x78
	ds_bpermute_b32 v54, v176, v35
	s_waitcnt lgkmcnt(2)
	v_and_or_b32 v53, v53, 63, v172
	v_lshlrev_b32_e32 v53, 2, v53
	ds_bpermute_b32 v55, v53, v32
	v_readlane_b32 s46, v240, 14
	s_waitcnt lgkmcnt(1)
	v_sub_f32_e32 v32, v35, v54
	v_mul_f32_e32 v32, 0x3fb8aa3b, v32
	v_exp_f32_e32 v32, v32
	v_and_or_b32 v35, v52, 63, v172
	v_lshlrev_b32_e32 v35, 2, v35
	ds_bpermute_b32 v35, v35, v33
	v_cndmask_b32_e64 v186, 0, v32, s[6:7]
	v_lshlrev_b64 v[32:33], 2, v[132:133]
	v_readlane_b32 s47, v240, 15
	v_add_f32_dpp v54, v186, v186 quad_perm:[1,0,3,2] row_mask:0xf bank_mask:0xf bound_ctrl:1
	v_mov_b32_e32 v43, v34
	v_lshl_add_u64 v[52:53], s[46:47], 0, v[32:33]
	v_lshl_add_u64 v[32:33], s[42:43], 0, v[32:33]
	global_load_dword v187, v[52:53], off
	global_load_dword v188, v[32:33], off
	v_add_f32_dpp v32, v54, v54 quad_perm:[2,3,0,1] row_mask:0xf bank_mask:0xf bound_ctrl:1
	v_mov_b32_e32 v33, v34
	v_mov_b32_e32 v40, v34
	v_add_f32_dpp v32, v32, v32 row_half_mirror row_mask:0xf bank_mask:0xf bound_ctrl:1
	s_waitcnt vmcnt(2)
	v_lshlrev_b32_e32 v150, 16, v48
	v_and_b32_e32 v151, 0xffff0000, v48
	v_add_f32_dpp v32, v32, v32 row_mirror row_mask:0xf bank_mask:0xf bound_ctrl:1
	v_lshlrev_b32_e32 v152, 16, v49
	v_readlane_b32 s67, v32, 0
	v_readlane_b32 s69, v32, 16
	v_readlane_b32 s68, v32, 32
	v_readlane_b32 s71, v32, 48
	s_waitcnt lgkmcnt(0)
	v_lshl_add_u32 v32, v55, 7, v35
	v_and_b32_e32 v32, 0x3fff, v32
	ds_bpermute_b32 v133, v175, v32
	v_and_b32_e32 v153, 0xffff0000, v49
	v_lshlrev_b32_e32 v154, 16, v50
	v_and_b32_e32 v155, 0xffff0000, v50
	v_lshlrev_b32_e32 v156, 16, v51
	v_and_b32_e32 v157, 0xffff0000, v51
	v_lshlrev_b32_e32 v158, 16, v44
	v_and_b32_e32 v159, 0xffff0000, v44
	v_lshlrev_b32_e32 v160, 16, v45
	v_and_b32_e32 v161, 0xffff0000, v45
	v_lshlrev_b32_e32 v162, 16, v46
	v_and_b32_e32 v163, 0xffff0000, v46
	v_lshlrev_b32_e32 v164, 16, v47
	v_and_b32_e32 v165, 0xffff0000, v47
	v_mov_b32_e32 v35, v34
	v_mov_b32_e32 v32, v34
	v_mov_b32_e32 v41, v34
	v_mov_b32_e32 v50, v34
	v_mov_b32_e32 v51, v34
	v_mov_b32_e32 v48, v34
	v_mov_b32_e32 v49, v34
	v_mov_b32_e32 v54, v34
	v_mov_b32_e32 v55, v34
	v_mov_b32_e32 v52, v34
	v_mov_b32_e32 v53, v34
	s_waitcnt vmcnt(0) lgkmcnt(0)
	v_subrev_u32_e32 v254, s96, v116
	s_nop 1
	v_readlane_b32 s100, v132, 6
	s_nop 0
	s_lshl_b32 s100, s100, 11
	s_add_u32 s100, s96, s100
	s_addc_u32 s101, s97, 0
	global_load_dwordx4 v[80:83], v254, s[100:101]
	global_load_dwordx4 v[84:87], v254, s[100:101] offset:1024
	s_waitcnt vmcnt(2)
	v_cvt_pk_f32_fp8_e32 v[44:45], v0
	v_pk_fma_f32 v[72:73], v[44:45], v[134:135], 0 op_sel_hi:[1,1,0]
	v_cvt_pk_f32_fp8_sdwa v[46:47], v0 src0_sel:WORD_1
	v_pk_fma_f32 v[72:73], v[46:47], v[136:137], v[72:73]
	v_cvt_pk_f32_fp8_e32 v[64:65], v1
	v_pk_fma_f32 v[72:73], v[64:65], v[138:139], v[72:73]
	v_cvt_pk_f32_fp8_sdwa v[66:67], v1 src0_sel:WORD_1
	v_pk_fma_f32 v[72:73], v[66:67], v[140:141], v[72:73]
	v_cvt_pk_f32_fp8_e32 v[44:45], v2
	v_pk_fma_f32 v[72:73], v[44:45], v[142:143], v[72:73]
	v_cvt_pk_f32_fp8_sdwa v[46:47], v2 src0_sel:WORD_1
	v_pk_fma_f32 v[72:73], v[46:47], v[144:145], v[72:73]
	v_cvt_pk_f32_fp8_e32 v[64:65], v3
	v_pk_fma_f32 v[72:73], v[64:65], v[146:147], v[72:73]
	v_cvt_pk_f32_fp8_sdwa v[66:67], v3 src0_sel:WORD_1
	v_pk_fma_f32 v[72:73], v[66:67], v[148:149], v[72:73]
	v_cvt_pk_f32_fp8_e32 v[44:45], v4
	v_pk_fma_f32 v[72:73], v[44:45], v[150:151], v[72:73]
	v_cvt_pk_f32_fp8_sdwa v[46:47], v4 src0_sel:WORD_1
	v_pk_fma_f32 v[72:73], v[46:47], v[152:153], v[72:73]
	v_cvt_pk_f32_fp8_e32 v[64:65], v5
	v_pk_fma_f32 v[72:73], v[64:65], v[154:155], v[72:73]
	v_cvt_pk_f32_fp8_sdwa v[66:67], v5 src0_sel:WORD_1
	v_pk_fma_f32 v[72:73], v[66:67], v[156:157], v[72:73]
	v_cvt_pk_f32_fp8_e32 v[44:45], v6
	v_pk_fma_f32 v[72:73], v[44:45], v[158:159], v[72:73]
	v_cvt_pk_f32_fp8_sdwa v[46:47], v6 src0_sel:WORD_1
	v_pk_fma_f32 v[72:73], v[46:47], v[160:161], v[72:73]
	v_cvt_pk_f32_fp8_e32 v[64:65], v7
	v_pk_fma_f32 v[72:73], v[64:65], v[162:163], v[72:73]
	v_cvt_pk_f32_fp8_sdwa v[66:67], v7 src0_sel:WORD_1
	v_pk_fma_f32 v[72:73], v[66:67], v[164:165], v[72:73]
	s_nop 1
	v_readlane_b32 s100, v132, 7
	v_add_f32_e32 v72, v72, v73
	s_lshl_b32 s100, s100, 11
	s_add_u32 s100, s96, s100
	s_addc_u32 s101, s97, 0
	global_load_dwordx4 v[88:91], v254, s[100:101]
	global_load_dwordx4 v[92:95], v254, s[100:101] offset:1024
	s_waitcnt vmcnt(4)
	v_cvt_pk_f32_fp8_e32 v[44:45], v8
	v_pk_fma_f32 v[74:75], v[44:45], v[134:135], 0 op_sel_hi:[1,1,0]
	v_cvt_pk_f32_fp8_sdwa v[46:47], v8 src0_sel:WORD_1
	v_pk_fma_f32 v[74:75], v[46:47], v[136:137], v[74:75]
	v_cvt_pk_f32_fp8_e32 v[64:65], v9
	v_pk_fma_f32 v[74:75], v[64:65], v[138:139], v[74:75]
	v_cvt_pk_f32_fp8_sdwa v[66:67], v9 src0_sel:WORD_1
	v_pk_fma_f32 v[74:75], v[66:67], v[140:141], v[74:75]
	v_cvt_pk_f32_fp8_e32 v[44:45], v10
	v_pk_fma_f32 v[74:75], v[44:45], v[142:143], v[74:75]
	v_cvt_pk_f32_fp8_sdwa v[46:47], v10 src0_sel:WORD_1
	v_pk_fma_f32 v[74:75], v[46:47], v[144:145], v[74:75]
	v_add_f32_dpp v72, v72, v72 quad_perm:[1,0,3,2] row_mask:0xf bank_mask:0xf bound_ctrl:1
	v_cvt_pk_f32_fp8_e32 v[64:65], v11
	v_pk_fma_f32 v[74:75], v[64:65], v[146:147], v[74:75]
	v_cvt_pk_f32_fp8_sdwa v[66:67], v11 src0_sel:WORD_1
	v_add_f32_dpp v72, v72, v72 quad_perm:[2,3,0,1] row_mask:0xf bank_mask:0xf bound_ctrl:1
	v_pk_fma_f32 v[74:75], v[66:67], v[148:149], v[74:75]
	v_cvt_pk_f32_fp8_e32 v[44:45], v12
	v_pk_fma_f32 v[74:75], v[44:45], v[150:151], v[74:75]
	v_add_f32_dpp v72, v72, v72 row_half_mirror row_mask:0xf bank_mask:0xf bound_ctrl:1
	v_cvt_pk_f32_fp8_sdwa v[46:47], v12 src0_sel:WORD_1
	v_pk_fma_f32 v[74:75], v[46:47], v[152:153], v[74:75]
	v_cvt_pk_f32_fp8_e32 v[64:65], v13
	v_add_f32_dpp v72, v72, v72 row_mirror row_mask:0xf bank_mask:0xf bound_ctrl:1
	v_pk_fma_f32 v[74:75], v[64:65], v[154:155], v[74:75]
	v_cvt_pk_f32_fp8_sdwa v[66:67], v13 src0_sel:WORD_1
	v_pk_fma_f32 v[74:75], v[66:67], v[156:157], v[74:75]
	v_add_f32_dpp v72, v72, v72 row_bcast:15 row_mask:0xa bank_mask:0xf
	v_cvt_pk_f32_fp8_e32 v[44:45], v14
	v_pk_fma_f32 v[74:75], v[44:45], v[158:159], v[74:75]
	v_cvt_pk_f32_fp8_sdwa v[46:47], v14 src0_sel:WORD_1
	v_add_f32_dpp v72, v72, v72 row_bcast:31 row_mask:0xc bank_mask:0xf
	v_pk_fma_f32 v[74:75], v[46:47], v[160:161], v[74:75]
	v_cvt_pk_f32_fp8_e32 v[64:65], v15
	v_readlane_b32 s48, v72, 63
	v_pk_fma_f32 v[74:75], v[64:65], v[162:163], v[74:75]
	v_cvt_pk_f32_fp8_sdwa v[66:67], v15 src0_sel:WORD_1
	v_pk_fma_f32 v[74:75], v[66:67], v[164:165], v[74:75]
	v_writelane_b32 v189, s48, 0
	s_nop 1
	v_readlane_b32 s100, v132, 8
	v_add_f32_e32 v74, v74, v75
	s_lshl_b32 s100, s100, 11
	s_add_u32 s100, s96, s100
	s_addc_u32 s101, s97, 0
	global_load_dwordx4 v[0:3], v254, s[100:101]
	global_load_dwordx4 v[4:7], v254, s[100:101] offset:1024
	s_waitcnt vmcnt(6)
	v_cvt_pk_f32_fp8_e32 v[44:45], v16
	v_pk_fma_f32 v[72:73], v[44:45], v[134:135], 0 op_sel_hi:[1,1,0]
	v_cvt_pk_f32_fp8_sdwa v[46:47], v16 src0_sel:WORD_1
	v_pk_fma_f32 v[72:73], v[46:47], v[136:137], v[72:73]
	v_cvt_pk_f32_fp8_e32 v[64:65], v17
	v_pk_fma_f32 v[72:73], v[64:65], v[138:139], v[72:73]
	v_cvt_pk_f32_fp8_sdwa v[66:67], v17 src0_sel:WORD_1
	v_pk_fma_f32 v[72:73], v[66:67], v[140:141], v[72:73]
	v_cvt_pk_f32_fp8_e32 v[44:45], v18
	v_pk_fma_f32 v[72:73], v[44:45], v[142:143], v[72:73]
	v_cvt_pk_f32_fp8_sdwa v[46:47], v18 src0_sel:WORD_1
	v_pk_fma_f32 v[72:73], v[46:47], v[144:145], v[72:73]
	v_add_f32_dpp v74, v74, v74 quad_perm:[1,0,3,2] row_mask:0xf bank_mask:0xf bound_ctrl:1
	v_cvt_pk_f32_fp8_e32 v[64:65], v19
	v_pk_fma_f32 v[72:73], v[64:65], v[146:147], v[72:73]
	v_cvt_pk_f32_fp8_sdwa v[66:67], v19 src0_sel:WORD_1
	v_add_f32_dpp v74, v74, v74 quad_perm:[2,3,0,1] row_mask:0xf bank_mask:0xf bound_ctrl:1
	v_pk_fma_f32 v[72:73], v[66:67], v[148:149], v[72:73]
	v_cvt_pk_f32_fp8_e32 v[44:45], v20
	v_pk_fma_f32 v[72:73], v[44:45], v[150:151], v[72:73]
	v_add_f32_dpp v74, v74, v74 row_half_mirror row_mask:0xf bank_mask:0xf bound_ctrl:1
	v_cvt_pk_f32_fp8_sdwa v[46:47], v20 src0_sel:WORD_1
	v_pk_fma_f32 v[72:73], v[46:47], v[152:153], v[72:73]
	v_cvt_pk_f32_fp8_e32 v[64:65], v21
	v_add_f32_dpp v74, v74, v74 row_mirror row_mask:0xf bank_mask:0xf bound_ctrl:1
	v_pk_fma_f32 v[72:73], v[64:65], v[154:155], v[72:73]
	v_cvt_pk_f32_fp8_sdwa v[66:67], v21 src0_sel:WORD_1
	v_pk_fma_f32 v[72:73], v[66:67], v[156:157], v[72:73]
	v_add_f32_dpp v74, v74, v74 row_bcast:15 row_mask:0xa bank_mask:0xf
	v_cvt_pk_f32_fp8_e32 v[44:45], v22
	v_pk_fma_f32 v[72:73], v[44:45], v[158:159], v[72:73]
	v_cvt_pk_f32_fp8_sdwa v[46:47], v22 src0_sel:WORD_1
	v_add_f32_dpp v74, v74, v74 row_bcast:31 row_mask:0xc bank_mask:0xf
	v_pk_fma_f32 v[72:73], v[46:47], v[160:161], v[72:73]
	v_cvt_pk_f32_fp8_e32 v[64:65], v23
	v_readlane_b32 s48, v74, 63
	v_pk_fma_f32 v[72:73], v[64:65], v[162:163], v[72:73]
	v_cvt_pk_f32_fp8_sdwa v[66:67], v23 src0_sel:WORD_1
	v_pk_fma_f32 v[72:73], v[66:67], v[164:165], v[72:73]
	v_writelane_b32 v189, s48, 1
	s_nop 1
	v_readlane_b32 s100, v132, 9
	v_add_f32_e32 v72, v72, v73
	s_lshl_b32 s100, s100, 11
	s_add_u32 s100, s96, s100
	s_addc_u32 s101, s97, 0
	global_load_dwordx4 v[8:11], v254, s[100:101]
	global_load_dwordx4 v[12:15], v254, s[100:101] offset:1024
	s_waitcnt vmcnt(8)
	v_cvt_pk_f32_fp8_e32 v[44:45], v24
	v_pk_fma_f32 v[74:75], v[44:45], v[134:135], 0 op_sel_hi:[1,1,0]
	v_cvt_pk_f32_fp8_sdwa v[46:47], v24 src0_sel:WORD_1
	v_pk_fma_f32 v[74:75], v[46:47], v[136:137], v[74:75]
	v_cvt_pk_f32_fp8_e32 v[64:65], v25
	v_pk_fma_f32 v[74:75], v[64:65], v[138:139], v[74:75]
	v_cvt_pk_f32_fp8_sdwa v[66:67], v25 src0_sel:WORD_1
	v_pk_fma_f32 v[74:75], v[66:67], v[140:141], v[74:75]
	v_cvt_pk_f32_fp8_e32 v[44:45], v26
	v_pk_fma_f32 v[74:75], v[44:45], v[142:143], v[74:75]
	v_cvt_pk_f32_fp8_sdwa v[46:47], v26 src0_sel:WORD_1
	v_pk_fma_f32 v[74:75], v[46:47], v[144:145], v[74:75]
	v_add_f32_dpp v72, v72, v72 quad_perm:[1,0,3,2] row_mask:0xf bank_mask:0xf bound_ctrl:1
	v_cvt_pk_f32_fp8_e32 v[64:65], v27
	v_pk_fma_f32 v[74:75], v[64:65], v[146:147], v[74:75]
	v_cvt_pk_f32_fp8_sdwa v[66:67], v27 src0_sel:WORD_1
	v_add_f32_dpp v72, v72, v72 quad_perm:[2,3,0,1] row_mask:0xf bank_mask:0xf bound_ctrl:1
	v_pk_fma_f32 v[74:75], v[66:67], v[148:149], v[74:75]
	v_cvt_pk_f32_fp8_e32 v[44:45], v28
	v_pk_fma_f32 v[74:75], v[44:45], v[150:151], v[74:75]
	v_add_f32_dpp v72, v72, v72 row_half_mirror row_mask:0xf bank_mask:0xf bound_ctrl:1
	v_cvt_pk_f32_fp8_sdwa v[46:47], v28 src0_sel:WORD_1
	v_pk_fma_f32 v[74:75], v[46:47], v[152:153], v[74:75]
	v_cvt_pk_f32_fp8_e32 v[64:65], v29
	v_add_f32_dpp v72, v72, v72 row_mirror row_mask:0xf bank_mask:0xf bound_ctrl:1
	v_pk_fma_f32 v[74:75], v[64:65], v[154:155], v[74:75]
	v_cvt_pk_f32_fp8_sdwa v[66:67], v29 src0_sel:WORD_1
	v_pk_fma_f32 v[74:75], v[66:67], v[156:157], v[74:75]
	v_add_f32_dpp v72, v72, v72 row_bcast:15 row_mask:0xa bank_mask:0xf
	v_cvt_pk_f32_fp8_e32 v[44:45], v30
	v_pk_fma_f32 v[74:75], v[44:45], v[158:159], v[74:75]
	v_cvt_pk_f32_fp8_sdwa v[46:47], v30 src0_sel:WORD_1
	v_add_f32_dpp v72, v72, v72 row_bcast:31 row_mask:0xc bank_mask:0xf
	v_pk_fma_f32 v[74:75], v[46:47], v[160:161], v[74:75]
	v_cvt_pk_f32_fp8_e32 v[64:65], v31
	v_readlane_b32 s48, v72, 63
	v_pk_fma_f32 v[74:75], v[64:65], v[162:163], v[74:75]
	v_cvt_pk_f32_fp8_sdwa v[66:67], v31 src0_sel:WORD_1
	v_pk_fma_f32 v[74:75], v[66:67], v[164:165], v[74:75]
	v_writelane_b32 v189, s48, 2
	s_nop 1
	v_readlane_b32 s100, v132, 10
	v_add_f32_e32 v74, v74, v75
	s_lshl_b32 s100, s100, 11
	s_add_u32 s100, s96, s100
	s_addc_u32 s101, s97, 0
	global_load_dwordx4 v[16:19], v254, s[100:101]
	global_load_dwordx4 v[20:23], v254, s[100:101] offset:1024
	s_waitcnt vmcnt(10)
	v_cvt_pk_f32_fp8_e32 v[44:45], v96
	v_pk_fma_f32 v[72:73], v[44:45], v[134:135], 0 op_sel_hi:[1,1,0]
	v_cvt_pk_f32_fp8_sdwa v[46:47], v96 src0_sel:WORD_1
	v_pk_fma_f32 v[72:73], v[46:47], v[136:137], v[72:73]
	v_cvt_pk_f32_fp8_e32 v[64:65], v97
	v_pk_fma_f32 v[72:73], v[64:65], v[138:139], v[72:73]
	v_cvt_pk_f32_fp8_sdwa v[66:67], v97 src0_sel:WORD_1
	v_pk_fma_f32 v[72:73], v[66:67], v[140:141], v[72:73]
	v_cvt_pk_f32_fp8_e32 v[44:45], v98
	v_pk_fma_f32 v[72:73], v[44:45], v[142:143], v[72:73]
	v_cvt_pk_f32_fp8_sdwa v[46:47], v98 src0_sel:WORD_1
	v_pk_fma_f32 v[72:73], v[46:47], v[144:145], v[72:73]
	v_add_f32_dpp v74, v74, v74 quad_perm:[1,0,3,2] row_mask:0xf bank_mask:0xf bound_ctrl:1
	v_cvt_pk_f32_fp8_e32 v[64:65], v99
	v_pk_fma_f32 v[72:73], v[64:65], v[146:147], v[72:73]
	v_cvt_pk_f32_fp8_sdwa v[66:67], v99 src0_sel:WORD_1
	v_add_f32_dpp v74, v74, v74 quad_perm:[2,3,0,1] row_mask:0xf bank_mask:0xf bound_ctrl:1
	v_pk_fma_f32 v[72:73], v[66:67], v[148:149], v[72:73]
	v_cvt_pk_f32_fp8_e32 v[44:45], v100
	v_pk_fma_f32 v[72:73], v[44:45], v[150:151], v[72:73]
	v_add_f32_dpp v74, v74, v74 row_half_mirror row_mask:0xf bank_mask:0xf bound_ctrl:1
	v_cvt_pk_f32_fp8_sdwa v[46:47], v100 src0_sel:WORD_1
	v_pk_fma_f32 v[72:73], v[46:47], v[152:153], v[72:73]
	v_cvt_pk_f32_fp8_e32 v[64:65], v101
	v_add_f32_dpp v74, v74, v74 row_mirror row_mask:0xf bank_mask:0xf bound_ctrl:1
	v_pk_fma_f32 v[72:73], v[64:65], v[154:155], v[72:73]
	v_cvt_pk_f32_fp8_sdwa v[66:67], v101 src0_sel:WORD_1
	v_pk_fma_f32 v[72:73], v[66:67], v[156:157], v[72:73]
	v_add_f32_dpp v74, v74, v74 row_bcast:15 row_mask:0xa bank_mask:0xf
	v_cvt_pk_f32_fp8_e32 v[44:45], v102
	v_pk_fma_f32 v[72:73], v[44:45], v[158:159], v[72:73]
	v_cvt_pk_f32_fp8_sdwa v[46:47], v102 src0_sel:WORD_1
	v_add_f32_dpp v74, v74, v74 row_bcast:31 row_mask:0xc bank_mask:0xf
	v_pk_fma_f32 v[72:73], v[46:47], v[160:161], v[72:73]
	v_cvt_pk_f32_fp8_e32 v[64:65], v103
	v_readlane_b32 s48, v74, 63
	v_pk_fma_f32 v[72:73], v[64:65], v[162:163], v[72:73]
	v_cvt_pk_f32_fp8_sdwa v[66:67], v103 src0_sel:WORD_1
	v_pk_fma_f32 v[72:73], v[66:67], v[164:165], v[72:73]
	v_writelane_b32 v189, s48, 3
	s_nop 1
	v_readlane_b32 s100, v132, 11
	v_add_f32_e32 v72, v72, v73
	s_lshl_b32 s100, s100, 11
	s_add_u32 s100, s96, s100
	s_addc_u32 s101, s97, 0
	global_load_dwordx4 v[24:27], v254, s[100:101]
	global_load_dwordx4 v[28:31], v254, s[100:101] offset:1024
	s_waitcnt vmcnt(12)
	v_cvt_pk_f32_fp8_e32 v[44:45], v104
	v_pk_fma_f32 v[74:75], v[44:45], v[134:135], 0 op_sel_hi:[1,1,0]
	v_cvt_pk_f32_fp8_sdwa v[46:47], v104 src0_sel:WORD_1
	v_pk_fma_f32 v[74:75], v[46:47], v[136:137], v[74:75]
	v_cvt_pk_f32_fp8_e32 v[64:65], v105
	v_pk_fma_f32 v[74:75], v[64:65], v[138:139], v[74:75]
	v_cvt_pk_f32_fp8_sdwa v[66:67], v105 src0_sel:WORD_1
	v_pk_fma_f32 v[74:75], v[66:67], v[140:141], v[74:75]
	v_cvt_pk_f32_fp8_e32 v[44:45], v106
	v_pk_fma_f32 v[74:75], v[44:45], v[142:143], v[74:75]
	v_cvt_pk_f32_fp8_sdwa v[46:47], v106 src0_sel:WORD_1
	v_pk_fma_f32 v[74:75], v[46:47], v[144:145], v[74:75]
	v_add_f32_dpp v72, v72, v72 quad_perm:[1,0,3,2] row_mask:0xf bank_mask:0xf bound_ctrl:1
	v_cvt_pk_f32_fp8_e32 v[64:65], v107
	v_pk_fma_f32 v[74:75], v[64:65], v[146:147], v[74:75]
	v_cvt_pk_f32_fp8_sdwa v[66:67], v107 src0_sel:WORD_1
	v_add_f32_dpp v72, v72, v72 quad_perm:[2,3,0,1] row_mask:0xf bank_mask:0xf bound_ctrl:1
	v_pk_fma_f32 v[74:75], v[66:67], v[148:149], v[74:75]
	v_cvt_pk_f32_fp8_e32 v[44:45], v108
	v_pk_fma_f32 v[74:75], v[44:45], v[150:151], v[74:75]
	v_add_f32_dpp v72, v72, v72 row_half_mirror row_mask:0xf bank_mask:0xf bound_ctrl:1
	v_cvt_pk_f32_fp8_sdwa v[46:47], v108 src0_sel:WORD_1
	v_pk_fma_f32 v[74:75], v[46:47], v[152:153], v[74:75]
	v_cvt_pk_f32_fp8_e32 v[64:65], v109
	v_add_f32_dpp v72, v72, v72 row_mirror row_mask:0xf bank_mask:0xf bound_ctrl:1
	v_pk_fma_f32 v[74:75], v[64:65], v[154:155], v[74:75]
	v_cvt_pk_f32_fp8_sdwa v[66:67], v109 src0_sel:WORD_1
	v_pk_fma_f32 v[74:75], v[66:67], v[156:157], v[74:75]
	v_add_f32_dpp v72, v72, v72 row_bcast:15 row_mask:0xa bank_mask:0xf
	v_cvt_pk_f32_fp8_e32 v[44:45], v110
	v_pk_fma_f32 v[74:75], v[44:45], v[158:159], v[74:75]
	v_cvt_pk_f32_fp8_sdwa v[46:47], v110 src0_sel:WORD_1
	v_add_f32_dpp v72, v72, v72 row_bcast:31 row_mask:0xc bank_mask:0xf
	v_pk_fma_f32 v[74:75], v[46:47], v[160:161], v[74:75]
	v_cvt_pk_f32_fp8_e32 v[64:65], v111
	v_readlane_b32 s48, v72, 63
	v_pk_fma_f32 v[74:75], v[64:65], v[162:163], v[74:75]
	v_cvt_pk_f32_fp8_sdwa v[66:67], v111 src0_sel:WORD_1
	v_pk_fma_f32 v[74:75], v[66:67], v[164:165], v[74:75]
	v_writelane_b32 v189, s48, 4
	s_nop 1
	v_readlane_b32 s100, v132, 12
	v_add_f32_e32 v74, v74, v75
	s_lshl_b32 s100, s100, 11
	s_add_u32 s100, s96, s100
	s_addc_u32 s101, s97, 0
	global_load_dwordx4 v[96:99], v254, s[100:101]
	global_load_dwordx4 v[100:103], v254, s[100:101] offset:1024
	s_waitcnt vmcnt(12)
	v_cvt_pk_f32_fp8_e32 v[44:45], v80
	v_pk_fma_f32 v[72:73], v[44:45], v[134:135], 0 op_sel_hi:[1,1,0]
	v_cvt_pk_f32_fp8_sdwa v[46:47], v80 src0_sel:WORD_1
	v_pk_fma_f32 v[72:73], v[46:47], v[136:137], v[72:73]
	v_cvt_pk_f32_fp8_e32 v[64:65], v81
	v_pk_fma_f32 v[72:73], v[64:65], v[138:139], v[72:73]
	v_cvt_pk_f32_fp8_sdwa v[66:67], v81 src0_sel:WORD_1
	v_pk_fma_f32 v[72:73], v[66:67], v[140:141], v[72:73]
	v_cvt_pk_f32_fp8_e32 v[44:45], v82
	v_pk_fma_f32 v[72:73], v[44:45], v[142:143], v[72:73]
	v_cvt_pk_f32_fp8_sdwa v[46:47], v82 src0_sel:WORD_1
	v_pk_fma_f32 v[72:73], v[46:47], v[144:145], v[72:73]
	v_add_f32_dpp v74, v74, v74 quad_perm:[1,0,3,2] row_mask:0xf bank_mask:0xf bound_ctrl:1
	v_cvt_pk_f32_fp8_e32 v[64:65], v83
	v_pk_fma_f32 v[72:73], v[64:65], v[146:147], v[72:73]
	v_cvt_pk_f32_fp8_sdwa v[66:67], v83 src0_sel:WORD_1
	v_add_f32_dpp v74, v74, v74 quad_perm:[2,3,0,1] row_mask:0xf bank_mask:0xf bound_ctrl:1
	v_pk_fma_f32 v[72:73], v[66:67], v[148:149], v[72:73]
	v_cvt_pk_f32_fp8_e32 v[44:45], v84
	v_pk_fma_f32 v[72:73], v[44:45], v[150:151], v[72:73]
	v_add_f32_dpp v74, v74, v74 row_half_mirror row_mask:0xf bank_mask:0xf bound_ctrl:1
	v_cvt_pk_f32_fp8_sdwa v[46:47], v84 src0_sel:WORD_1
	v_pk_fma_f32 v[72:73], v[46:47], v[152:153], v[72:73]
	v_cvt_pk_f32_fp8_e32 v[64:65], v85
	v_add_f32_dpp v74, v74, v74 row_mirror row_mask:0xf bank_mask:0xf bound_ctrl:1
	v_pk_fma_f32 v[72:73], v[64:65], v[154:155], v[72:73]
	v_cvt_pk_f32_fp8_sdwa v[66:67], v85 src0_sel:WORD_1
	v_pk_fma_f32 v[72:73], v[66:67], v[156:157], v[72:73]
	v_add_f32_dpp v74, v74, v74 row_bcast:15 row_mask:0xa bank_mask:0xf
	v_cvt_pk_f32_fp8_e32 v[44:45], v86
	v_pk_fma_f32 v[72:73], v[44:45], v[158:159], v[72:73]
	v_cvt_pk_f32_fp8_sdwa v[46:47], v86 src0_sel:WORD_1
	v_add_f32_dpp v74, v74, v74 row_bcast:31 row_mask:0xc bank_mask:0xf
	v_pk_fma_f32 v[72:73], v[46:47], v[160:161], v[72:73]
	v_cvt_pk_f32_fp8_e32 v[64:65], v87
	v_readlane_b32 s48, v74, 63
	v_pk_fma_f32 v[72:73], v[64:65], v[162:163], v[72:73]
	v_cvt_pk_f32_fp8_sdwa v[66:67], v87 src0_sel:WORD_1
	v_pk_fma_f32 v[72:73], v[66:67], v[164:165], v[72:73]
	v_writelane_b32 v189, s48, 5
	s_nop 1
	v_readlane_b32 s100, v132, 13
	v_add_f32_e32 v72, v72, v73
	s_lshl_b32 s100, s100, 11
	s_add_u32 s100, s96, s100
	s_addc_u32 s101, s97, 0
	global_load_dwordx4 v[104:107], v254, s[100:101]
	global_load_dwordx4 v[108:111], v254, s[100:101] offset:1024
	s_waitcnt vmcnt(12)
	v_cvt_pk_f32_fp8_e32 v[44:45], v88
	v_pk_fma_f32 v[74:75], v[44:45], v[134:135], 0 op_sel_hi:[1,1,0]
	v_cvt_pk_f32_fp8_sdwa v[46:47], v88 src0_sel:WORD_1
	v_pk_fma_f32 v[74:75], v[46:47], v[136:137], v[74:75]
	v_cvt_pk_f32_fp8_e32 v[64:65], v89
	v_pk_fma_f32 v[74:75], v[64:65], v[138:139], v[74:75]
	v_cvt_pk_f32_fp8_sdwa v[66:67], v89 src0_sel:WORD_1
	v_pk_fma_f32 v[74:75], v[66:67], v[140:141], v[74:75]
	v_cvt_pk_f32_fp8_e32 v[44:45], v90
	v_pk_fma_f32 v[74:75], v[44:45], v[142:143], v[74:75]
	v_cvt_pk_f32_fp8_sdwa v[46:47], v90 src0_sel:WORD_1
	v_pk_fma_f32 v[74:75], v[46:47], v[144:145], v[74:75]
	v_add_f32_dpp v72, v72, v72 quad_perm:[1,0,3,2] row_mask:0xf bank_mask:0xf bound_ctrl:1
	v_cvt_pk_f32_fp8_e32 v[64:65], v91
	v_pk_fma_f32 v[74:75], v[64:65], v[146:147], v[74:75]
	v_cvt_pk_f32_fp8_sdwa v[66:67], v91 src0_sel:WORD_1
	v_add_f32_dpp v72, v72, v72 quad_perm:[2,3,0,1] row_mask:0xf bank_mask:0xf bound_ctrl:1
	v_pk_fma_f32 v[74:75], v[66:67], v[148:149], v[74:75]
	v_cvt_pk_f32_fp8_e32 v[44:45], v92
	v_pk_fma_f32 v[74:75], v[44:45], v[150:151], v[74:75]
	v_add_f32_dpp v72, v72, v72 row_half_mirror row_mask:0xf bank_mask:0xf bound_ctrl:1
	v_cvt_pk_f32_fp8_sdwa v[46:47], v92 src0_sel:WORD_1
	v_pk_fma_f32 v[74:75], v[46:47], v[152:153], v[74:75]
	v_cvt_pk_f32_fp8_e32 v[64:65], v93
	v_add_f32_dpp v72, v72, v72 row_mirror row_mask:0xf bank_mask:0xf bound_ctrl:1
	v_pk_fma_f32 v[74:75], v[64:65], v[154:155], v[74:75]
	v_cvt_pk_f32_fp8_sdwa v[66:67], v93 src0_sel:WORD_1
	v_pk_fma_f32 v[74:75], v[66:67], v[156:157], v[74:75]
	v_add_f32_dpp v72, v72, v72 row_bcast:15 row_mask:0xa bank_mask:0xf
	v_cvt_pk_f32_fp8_e32 v[44:45], v94
	v_pk_fma_f32 v[74:75], v[44:45], v[158:159], v[74:75]
	v_cvt_pk_f32_fp8_sdwa v[46:47], v94 src0_sel:WORD_1
	v_add_f32_dpp v72, v72, v72 row_bcast:31 row_mask:0xc bank_mask:0xf
	v_pk_fma_f32 v[74:75], v[46:47], v[160:161], v[74:75]
	v_cvt_pk_f32_fp8_e32 v[64:65], v95
	v_readlane_b32 s48, v72, 63
	v_pk_fma_f32 v[74:75], v[64:65], v[162:163], v[74:75]
	v_cvt_pk_f32_fp8_sdwa v[66:67], v95 src0_sel:WORD_1
	v_pk_fma_f32 v[74:75], v[66:67], v[164:165], v[74:75]
	v_writelane_b32 v189, s48, 6
	s_nop 1
	v_readlane_b32 s100, v132, 14
	v_add_f32_e32 v74, v74, v75
	s_lshl_b32 s100, s100, 11
	s_add_u32 s100, s96, s100
	s_addc_u32 s101, s97, 0
	global_load_dwordx4 v[80:83], v254, s[100:101]
	global_load_dwordx4 v[84:87], v254, s[100:101] offset:1024
	s_waitcnt vmcnt(12)
	v_cvt_pk_f32_fp8_e32 v[44:45], v0
	v_pk_fma_f32 v[72:73], v[44:45], v[134:135], 0 op_sel_hi:[1,1,0]
	v_cvt_pk_f32_fp8_sdwa v[46:47], v0 src0_sel:WORD_1
	v_pk_fma_f32 v[72:73], v[46:47], v[136:137], v[72:73]
	v_cvt_pk_f32_fp8_e32 v[64:65], v1
	v_pk_fma_f32 v[72:73], v[64:65], v[138:139], v[72:73]
	v_cvt_pk_f32_fp8_sdwa v[66:67], v1 src0_sel:WORD_1
	v_pk_fma_f32 v[72:73], v[66:67], v[140:141], v[72:73]
	v_cvt_pk_f32_fp8_e32 v[44:45], v2
	v_pk_fma_f32 v[72:73], v[44:45], v[142:143], v[72:73]
	v_cvt_pk_f32_fp8_sdwa v[46:47], v2 src0_sel:WORD_1
	v_pk_fma_f32 v[72:73], v[46:47], v[144:145], v[72:73]
	v_add_f32_dpp v74, v74, v74 quad_perm:[1,0,3,2] row_mask:0xf bank_mask:0xf bound_ctrl:1
	v_cvt_pk_f32_fp8_e32 v[64:65], v3
	v_pk_fma_f32 v[72:73], v[64:65], v[146:147], v[72:73]
	v_cvt_pk_f32_fp8_sdwa v[66:67], v3 src0_sel:WORD_1
	v_add_f32_dpp v74, v74, v74 quad_perm:[2,3,0,1] row_mask:0xf bank_mask:0xf bound_ctrl:1
	v_pk_fma_f32 v[72:73], v[66:67], v[148:149], v[72:73]
	v_cvt_pk_f32_fp8_e32 v[44:45], v4
	v_pk_fma_f32 v[72:73], v[44:45], v[150:151], v[72:73]
	v_add_f32_dpp v74, v74, v74 row_half_mirror row_mask:0xf bank_mask:0xf bound_ctrl:1
	v_cvt_pk_f32_fp8_sdwa v[46:47], v4 src0_sel:WORD_1
	v_pk_fma_f32 v[72:73], v[46:47], v[152:153], v[72:73]
	v_cvt_pk_f32_fp8_e32 v[64:65], v5
	v_add_f32_dpp v74, v74, v74 row_mirror row_mask:0xf bank_mask:0xf bound_ctrl:1
	v_pk_fma_f32 v[72:73], v[64:65], v[154:155], v[72:73]
	v_cvt_pk_f32_fp8_sdwa v[66:67], v5 src0_sel:WORD_1
	v_pk_fma_f32 v[72:73], v[66:67], v[156:157], v[72:73]
	v_add_f32_dpp v74, v74, v74 row_bcast:15 row_mask:0xa bank_mask:0xf
	v_cvt_pk_f32_fp8_e32 v[44:45], v6
	v_pk_fma_f32 v[72:73], v[44:45], v[158:159], v[72:73]
	v_cvt_pk_f32_fp8_sdwa v[46:47], v6 src0_sel:WORD_1
	v_add_f32_dpp v74, v74, v74 row_bcast:31 row_mask:0xc bank_mask:0xf
	v_pk_fma_f32 v[72:73], v[46:47], v[160:161], v[72:73]
	v_cvt_pk_f32_fp8_e32 v[64:65], v7
	v_readlane_b32 s48, v74, 63
	v_pk_fma_f32 v[72:73], v[64:65], v[162:163], v[72:73]
	v_cvt_pk_f32_fp8_sdwa v[66:67], v7 src0_sel:WORD_1
	v_pk_fma_f32 v[72:73], v[66:67], v[164:165], v[72:73]
	v_writelane_b32 v189, s48, 7
	s_nop 1
	v_readlane_b32 s100, v132, 15
	v_add_f32_e32 v72, v72, v73
	s_lshl_b32 s100, s100, 11
	s_add_u32 s100, s96, s100
	s_addc_u32 s101, s97, 0
	global_load_dwordx4 v[88:91], v254, s[100:101]
	global_load_dwordx4 v[92:95], v254, s[100:101] offset:1024
	s_waitcnt vmcnt(12)
	v_cvt_pk_f32_fp8_e32 v[44:45], v8
	v_pk_fma_f32 v[74:75], v[44:45], v[134:135], 0 op_sel_hi:[1,1,0]
	v_cvt_pk_f32_fp8_sdwa v[46:47], v8 src0_sel:WORD_1
	v_pk_fma_f32 v[74:75], v[46:47], v[136:137], v[74:75]
	v_cvt_pk_f32_fp8_e32 v[64:65], v9
	v_pk_fma_f32 v[74:75], v[64:65], v[138:139], v[74:75]
	v_cvt_pk_f32_fp8_sdwa v[66:67], v9 src0_sel:WORD_1
	v_pk_fma_f32 v[74:75], v[66:67], v[140:141], v[74:75]
	v_cvt_pk_f32_fp8_e32 v[44:45], v10
	v_pk_fma_f32 v[74:75], v[44:45], v[142:143], v[74:75]
	v_cvt_pk_f32_fp8_sdwa v[46:47], v10 src0_sel:WORD_1
	v_pk_fma_f32 v[74:75], v[46:47], v[144:145], v[74:75]
	v_add_f32_dpp v72, v72, v72 quad_perm:[1,0,3,2] row_mask:0xf bank_mask:0xf bound_ctrl:1
	v_cvt_pk_f32_fp8_e32 v[64:65], v11
	v_pk_fma_f32 v[74:75], v[64:65], v[146:147], v[74:75]
	v_cvt_pk_f32_fp8_sdwa v[66:67], v11 src0_sel:WORD_1
	v_add_f32_dpp v72, v72, v72 quad_perm:[2,3,0,1] row_mask:0xf bank_mask:0xf bound_ctrl:1
	v_pk_fma_f32 v[74:75], v[66:67], v[148:149], v[74:75]
	v_cvt_pk_f32_fp8_e32 v[44:45], v12
	v_pk_fma_f32 v[74:75], v[44:45], v[150:151], v[74:75]
	v_add_f32_dpp v72, v72, v72 row_half_mirror row_mask:0xf bank_mask:0xf bound_ctrl:1
	v_cvt_pk_f32_fp8_sdwa v[46:47], v12 src0_sel:WORD_1
	v_pk_fma_f32 v[74:75], v[46:47], v[152:153], v[74:75]
	v_cvt_pk_f32_fp8_e32 v[64:65], v13
	v_add_f32_dpp v72, v72, v72 row_mirror row_mask:0xf bank_mask:0xf bound_ctrl:1
	v_pk_fma_f32 v[74:75], v[64:65], v[154:155], v[74:75]
	v_cvt_pk_f32_fp8_sdwa v[66:67], v13 src0_sel:WORD_1
	v_pk_fma_f32 v[74:75], v[66:67], v[156:157], v[74:75]
	v_add_f32_dpp v72, v72, v72 row_bcast:15 row_mask:0xa bank_mask:0xf
	v_cvt_pk_f32_fp8_e32 v[44:45], v14
	v_pk_fma_f32 v[74:75], v[44:45], v[158:159], v[74:75]
	v_cvt_pk_f32_fp8_sdwa v[46:47], v14 src0_sel:WORD_1
	v_add_f32_dpp v72, v72, v72 row_bcast:31 row_mask:0xc bank_mask:0xf
	v_pk_fma_f32 v[74:75], v[46:47], v[160:161], v[74:75]
	v_cvt_pk_f32_fp8_e32 v[64:65], v15
	v_readlane_b32 s48, v72, 63
	v_pk_fma_f32 v[74:75], v[64:65], v[162:163], v[74:75]
	v_cvt_pk_f32_fp8_sdwa v[66:67], v15 src0_sel:WORD_1
	v_pk_fma_f32 v[74:75], v[66:67], v[164:165], v[74:75]
	v_writelane_b32 v189, s48, 8
	s_nop 1
	v_readlane_b32 s100, v132, 0
	v_add_f32_e32 v74, v74, v75
	s_lshl_b32 s100, s100, 11
	s_add_u32 s100, s98, s100
	s_addc_u32 s101, s99, 0
	global_load_dwordx4 v[192:195], v254, s[100:101]
	global_load_dwordx4 v[196:199], v254, s[100:101] offset:1024
	s_waitcnt vmcnt(12)
	v_cvt_pk_f32_fp8_e32 v[44:45], v16
	v_pk_fma_f32 v[72:73], v[44:45], v[134:135], 0 op_sel_hi:[1,1,0]
	v_cvt_pk_f32_fp8_sdwa v[46:47], v16 src0_sel:WORD_1
	v_pk_fma_f32 v[72:73], v[46:47], v[136:137], v[72:73]
	v_cvt_pk_f32_fp8_e32 v[64:65], v17
	v_pk_fma_f32 v[72:73], v[64:65], v[138:139], v[72:73]
	v_cvt_pk_f32_fp8_sdwa v[66:67], v17 src0_sel:WORD_1
	v_pk_fma_f32 v[72:73], v[66:67], v[140:141], v[72:73]
	v_cvt_pk_f32_fp8_e32 v[44:45], v18
	v_pk_fma_f32 v[72:73], v[44:45], v[142:143], v[72:73]
	v_cvt_pk_f32_fp8_sdwa v[46:47], v18 src0_sel:WORD_1
	v_pk_fma_f32 v[72:73], v[46:47], v[144:145], v[72:73]
	v_add_f32_dpp v74, v74, v74 quad_perm:[1,0,3,2] row_mask:0xf bank_mask:0xf bound_ctrl:1
	v_cvt_pk_f32_fp8_e32 v[64:65], v19
	v_pk_fma_f32 v[72:73], v[64:65], v[146:147], v[72:73]
	v_cvt_pk_f32_fp8_sdwa v[66:67], v19 src0_sel:WORD_1
	v_add_f32_dpp v74, v74, v74 quad_perm:[2,3,0,1] row_mask:0xf bank_mask:0xf bound_ctrl:1
	v_pk_fma_f32 v[72:73], v[66:67], v[148:149], v[72:73]
	v_cvt_pk_f32_fp8_e32 v[44:45], v20
	v_pk_fma_f32 v[72:73], v[44:45], v[150:151], v[72:73]
	v_add_f32_dpp v74, v74, v74 row_half_mirror row_mask:0xf bank_mask:0xf bound_ctrl:1
	v_cvt_pk_f32_fp8_sdwa v[46:47], v20 src0_sel:WORD_1
	v_pk_fma_f32 v[72:73], v[46:47], v[152:153], v[72:73]
	v_cvt_pk_f32_fp8_e32 v[64:65], v21
	v_add_f32_dpp v74, v74, v74 row_mirror row_mask:0xf bank_mask:0xf bound_ctrl:1
	v_pk_fma_f32 v[72:73], v[64:65], v[154:155], v[72:73]
	v_cvt_pk_f32_fp8_sdwa v[66:67], v21 src0_sel:WORD_1
	v_pk_fma_f32 v[72:73], v[66:67], v[156:157], v[72:73]
	v_add_f32_dpp v74, v74, v74 row_bcast:15 row_mask:0xa bank_mask:0xf
	v_cvt_pk_f32_fp8_e32 v[44:45], v22
	v_pk_fma_f32 v[72:73], v[44:45], v[158:159], v[72:73]
	v_cvt_pk_f32_fp8_sdwa v[46:47], v22 src0_sel:WORD_1
	v_add_f32_dpp v74, v74, v74 row_bcast:31 row_mask:0xc bank_mask:0xf
	v_pk_fma_f32 v[72:73], v[46:47], v[160:161], v[72:73]
	v_cvt_pk_f32_fp8_e32 v[64:65], v23
	v_readlane_b32 s48, v74, 63
	v_pk_fma_f32 v[72:73], v[64:65], v[162:163], v[72:73]
	v_cvt_pk_f32_fp8_sdwa v[66:67], v23 src0_sel:WORD_1
	v_pk_fma_f32 v[72:73], v[66:67], v[164:165], v[72:73]
	v_writelane_b32 v189, s48, 9
	s_nop 1
	v_readlane_b32 s100, v132, 1
	v_add_f32_e32 v72, v72, v73
	s_lshl_b32 s100, s100, 11
	s_add_u32 s100, s98, s100
	s_addc_u32 s101, s99, 0
	global_load_dwordx4 v[200:203], v254, s[100:101]
	global_load_dwordx4 v[204:207], v254, s[100:101] offset:1024
	s_waitcnt vmcnt(12)
	v_cvt_pk_f32_fp8_e32 v[44:45], v24
	v_pk_fma_f32 v[74:75], v[44:45], v[134:135], 0 op_sel_hi:[1,1,0]
	v_cvt_pk_f32_fp8_sdwa v[46:47], v24 src0_sel:WORD_1
	v_pk_fma_f32 v[74:75], v[46:47], v[136:137], v[74:75]
	v_cvt_pk_f32_fp8_e32 v[64:65], v25
	v_pk_fma_f32 v[74:75], v[64:65], v[138:139], v[74:75]
	v_cvt_pk_f32_fp8_sdwa v[66:67], v25 src0_sel:WORD_1
	v_pk_fma_f32 v[74:75], v[66:67], v[140:141], v[74:75]
	v_cvt_pk_f32_fp8_e32 v[44:45], v26
	v_pk_fma_f32 v[74:75], v[44:45], v[142:143], v[74:75]
	v_cvt_pk_f32_fp8_sdwa v[46:47], v26 src0_sel:WORD_1
	v_pk_fma_f32 v[74:75], v[46:47], v[144:145], v[74:75]
	v_add_f32_dpp v72, v72, v72 quad_perm:[1,0,3,2] row_mask:0xf bank_mask:0xf bound_ctrl:1
	v_cvt_pk_f32_fp8_e32 v[64:65], v27
	v_pk_fma_f32 v[74:75], v[64:65], v[146:147], v[74:75]
	v_cvt_pk_f32_fp8_sdwa v[66:67], v27 src0_sel:WORD_1
	v_add_f32_dpp v72, v72, v72 quad_perm:[2,3,0,1] row_mask:0xf bank_mask:0xf bound_ctrl:1
	v_pk_fma_f32 v[74:75], v[66:67], v[148:149], v[74:75]
	v_cvt_pk_f32_fp8_e32 v[44:45], v28
	v_pk_fma_f32 v[74:75], v[44:45], v[150:151], v[74:75]
	v_add_f32_dpp v72, v72, v72 row_half_mirror row_mask:0xf bank_mask:0xf bound_ctrl:1
	v_cvt_pk_f32_fp8_sdwa v[46:47], v28 src0_sel:WORD_1
	v_pk_fma_f32 v[74:75], v[46:47], v[152:153], v[74:75]
	v_cvt_pk_f32_fp8_e32 v[64:65], v29
	v_add_f32_dpp v72, v72, v72 row_mirror row_mask:0xf bank_mask:0xf bound_ctrl:1
	v_pk_fma_f32 v[74:75], v[64:65], v[154:155], v[74:75]
	v_cvt_pk_f32_fp8_sdwa v[66:67], v29 src0_sel:WORD_1
	v_pk_fma_f32 v[74:75], v[66:67], v[156:157], v[74:75]
	v_add_f32_dpp v72, v72, v72 row_bcast:15 row_mask:0xa bank_mask:0xf
	v_cvt_pk_f32_fp8_e32 v[44:45], v30
	v_pk_fma_f32 v[74:75], v[44:45], v[158:159], v[74:75]
	v_cvt_pk_f32_fp8_sdwa v[46:47], v30 src0_sel:WORD_1
	v_add_f32_dpp v72, v72, v72 row_bcast:31 row_mask:0xc bank_mask:0xf
	v_pk_fma_f32 v[74:75], v[46:47], v[160:161], v[74:75]
	v_cvt_pk_f32_fp8_e32 v[64:65], v31
	v_readlane_b32 s48, v72, 63
	v_pk_fma_f32 v[74:75], v[64:65], v[162:163], v[74:75]
	v_cvt_pk_f32_fp8_sdwa v[66:67], v31 src0_sel:WORD_1
	v_pk_fma_f32 v[74:75], v[66:67], v[164:165], v[74:75]
	v_writelane_b32 v189, s48, 10
	s_nop 1
	v_readlane_b32 s100, v132, 2
	v_add_f32_e32 v74, v74, v75
	s_lshl_b32 s100, s100, 11
	s_add_u32 s100, s98, s100
	s_addc_u32 s101, s99, 0
	global_load_dwordx4 v[208:211], v254, s[100:101]
	global_load_dwordx4 v[212:215], v254, s[100:101] offset:1024
	s_waitcnt vmcnt(12)
	v_cvt_pk_f32_fp8_e32 v[44:45], v96
	v_pk_fma_f32 v[72:73], v[44:45], v[134:135], 0 op_sel_hi:[1,1,0]
	v_cvt_pk_f32_fp8_sdwa v[46:47], v96 src0_sel:WORD_1
	v_pk_fma_f32 v[72:73], v[46:47], v[136:137], v[72:73]
	v_cvt_pk_f32_fp8_e32 v[64:65], v97
	v_pk_fma_f32 v[72:73], v[64:65], v[138:139], v[72:73]
	v_cvt_pk_f32_fp8_sdwa v[66:67], v97 src0_sel:WORD_1
	v_pk_fma_f32 v[72:73], v[66:67], v[140:141], v[72:73]
	v_cvt_pk_f32_fp8_e32 v[44:45], v98
	v_pk_fma_f32 v[72:73], v[44:45], v[142:143], v[72:73]
	v_cvt_pk_f32_fp8_sdwa v[46:47], v98 src0_sel:WORD_1
	v_pk_fma_f32 v[72:73], v[46:47], v[144:145], v[72:73]
	v_add_f32_dpp v74, v74, v74 quad_perm:[1,0,3,2] row_mask:0xf bank_mask:0xf bound_ctrl:1
	v_cvt_pk_f32_fp8_e32 v[64:65], v99
	v_pk_fma_f32 v[72:73], v[64:65], v[146:147], v[72:73]
	v_cvt_pk_f32_fp8_sdwa v[66:67], v99 src0_sel:WORD_1
	v_add_f32_dpp v74, v74, v74 quad_perm:[2,3,0,1] row_mask:0xf bank_mask:0xf bound_ctrl:1
	v_pk_fma_f32 v[72:73], v[66:67], v[148:149], v[72:73]
	v_cvt_pk_f32_fp8_e32 v[44:45], v100
	v_pk_fma_f32 v[72:73], v[44:45], v[150:151], v[72:73]
	v_add_f32_dpp v74, v74, v74 row_half_mirror row_mask:0xf bank_mask:0xf bound_ctrl:1
	v_cvt_pk_f32_fp8_sdwa v[46:47], v100 src0_sel:WORD_1
	v_pk_fma_f32 v[72:73], v[46:47], v[152:153], v[72:73]
	v_cvt_pk_f32_fp8_e32 v[64:65], v101
	v_add_f32_dpp v74, v74, v74 row_mirror row_mask:0xf bank_mask:0xf bound_ctrl:1
	v_pk_fma_f32 v[72:73], v[64:65], v[154:155], v[72:73]
	v_cvt_pk_f32_fp8_sdwa v[66:67], v101 src0_sel:WORD_1
	v_pk_fma_f32 v[72:73], v[66:67], v[156:157], v[72:73]
	v_add_f32_dpp v74, v74, v74 row_bcast:15 row_mask:0xa bank_mask:0xf
	v_cvt_pk_f32_fp8_e32 v[44:45], v102
	v_pk_fma_f32 v[72:73], v[44:45], v[158:159], v[72:73]
	v_cvt_pk_f32_fp8_sdwa v[46:47], v102 src0_sel:WORD_1
	v_add_f32_dpp v74, v74, v74 row_bcast:31 row_mask:0xc bank_mask:0xf
	v_pk_fma_f32 v[72:73], v[46:47], v[160:161], v[72:73]
	v_cvt_pk_f32_fp8_e32 v[64:65], v103
	v_readlane_b32 s48, v74, 63
	v_pk_fma_f32 v[72:73], v[64:65], v[162:163], v[72:73]
	v_cvt_pk_f32_fp8_sdwa v[66:67], v103 src0_sel:WORD_1
	v_pk_fma_f32 v[72:73], v[66:67], v[164:165], v[72:73]
	v_writelane_b32 v189, s48, 11
	s_nop 1
	v_readlane_b32 s100, v132, 3
	v_add_f32_e32 v72, v72, v73
	s_lshl_b32 s100, s100, 11
	s_add_u32 s100, s98, s100
	s_addc_u32 s101, s99, 0
	global_load_dwordx4 v[216:219], v254, s[100:101]
	global_load_dwordx4 v[220:223], v254, s[100:101] offset:1024
	s_waitcnt vmcnt(12)
	v_cvt_pk_f32_fp8_e32 v[44:45], v104
	v_pk_fma_f32 v[74:75], v[44:45], v[134:135], 0 op_sel_hi:[1,1,0]
	v_cvt_pk_f32_fp8_sdwa v[46:47], v104 src0_sel:WORD_1
	v_pk_fma_f32 v[74:75], v[46:47], v[136:137], v[74:75]
	v_cvt_pk_f32_fp8_e32 v[64:65], v105
	v_pk_fma_f32 v[74:75], v[64:65], v[138:139], v[74:75]
	v_cvt_pk_f32_fp8_sdwa v[66:67], v105 src0_sel:WORD_1
	v_pk_fma_f32 v[74:75], v[66:67], v[140:141], v[74:75]
	v_cvt_pk_f32_fp8_e32 v[44:45], v106
	v_pk_fma_f32 v[74:75], v[44:45], v[142:143], v[74:75]
	v_cvt_pk_f32_fp8_sdwa v[46:47], v106 src0_sel:WORD_1
	v_pk_fma_f32 v[74:75], v[46:47], v[144:145], v[74:75]
	v_add_f32_dpp v72, v72, v72 quad_perm:[1,0,3,2] row_mask:0xf bank_mask:0xf bound_ctrl:1
	v_cvt_pk_f32_fp8_e32 v[64:65], v107
	v_pk_fma_f32 v[74:75], v[64:65], v[146:147], v[74:75]
	v_cvt_pk_f32_fp8_sdwa v[66:67], v107 src0_sel:WORD_1
	v_add_f32_dpp v72, v72, v72 quad_perm:[2,3,0,1] row_mask:0xf bank_mask:0xf bound_ctrl:1
	v_pk_fma_f32 v[74:75], v[66:67], v[148:149], v[74:75]
	v_cvt_pk_f32_fp8_e32 v[44:45], v108
	v_pk_fma_f32 v[74:75], v[44:45], v[150:151], v[74:75]
	v_add_f32_dpp v72, v72, v72 row_half_mirror row_mask:0xf bank_mask:0xf bound_ctrl:1
	v_cvt_pk_f32_fp8_sdwa v[46:47], v108 src0_sel:WORD_1
	v_pk_fma_f32 v[74:75], v[46:47], v[152:153], v[74:75]
	v_cvt_pk_f32_fp8_e32 v[64:65], v109
	v_add_f32_dpp v72, v72, v72 row_mirror row_mask:0xf bank_mask:0xf bound_ctrl:1
	v_pk_fma_f32 v[74:75], v[64:65], v[154:155], v[74:75]
	v_cvt_pk_f32_fp8_sdwa v[66:67], v109 src0_sel:WORD_1
	v_pk_fma_f32 v[74:75], v[66:67], v[156:157], v[74:75]
	v_add_f32_dpp v72, v72, v72 row_bcast:15 row_mask:0xa bank_mask:0xf
	v_cvt_pk_f32_fp8_e32 v[44:45], v110
	v_pk_fma_f32 v[74:75], v[44:45], v[158:159], v[74:75]
	v_cvt_pk_f32_fp8_sdwa v[46:47], v110 src0_sel:WORD_1
	v_add_f32_dpp v72, v72, v72 row_bcast:31 row_mask:0xc bank_mask:0xf
	v_pk_fma_f32 v[74:75], v[46:47], v[160:161], v[74:75]
	v_cvt_pk_f32_fp8_e32 v[64:65], v111
	v_readlane_b32 s48, v72, 63
	v_pk_fma_f32 v[74:75], v[64:65], v[162:163], v[74:75]
	v_cvt_pk_f32_fp8_sdwa v[66:67], v111 src0_sel:WORD_1
	v_pk_fma_f32 v[74:75], v[66:67], v[164:165], v[74:75]
	v_writelane_b32 v189, s48, 12
	s_nop 1
	v_readlane_b32 s100, v132, 4
	v_add_f32_e32 v74, v74, v75
	s_lshl_b32 s100, s100, 11
	s_add_u32 s100, s98, s100
	s_addc_u32 s101, s99, 0
	global_load_dwordx4 v[224:227], v254, s[100:101]
	global_load_dwordx4 v[228:231], v254, s[100:101] offset:1024
	s_waitcnt vmcnt(12)
	v_cvt_pk_f32_fp8_e32 v[44:45], v80
	v_pk_fma_f32 v[72:73], v[44:45], v[134:135], 0 op_sel_hi:[1,1,0]
	v_cvt_pk_f32_fp8_sdwa v[46:47], v80 src0_sel:WORD_1
	v_pk_fma_f32 v[72:73], v[46:47], v[136:137], v[72:73]
	v_cvt_pk_f32_fp8_e32 v[64:65], v81
	v_pk_fma_f32 v[72:73], v[64:65], v[138:139], v[72:73]
	v_cvt_pk_f32_fp8_sdwa v[66:67], v81 src0_sel:WORD_1
	v_pk_fma_f32 v[72:73], v[66:67], v[140:141], v[72:73]
	v_cvt_pk_f32_fp8_e32 v[44:45], v82
	v_pk_fma_f32 v[72:73], v[44:45], v[142:143], v[72:73]
	v_cvt_pk_f32_fp8_sdwa v[46:47], v82 src0_sel:WORD_1
	v_pk_fma_f32 v[72:73], v[46:47], v[144:145], v[72:73]
	v_add_f32_dpp v74, v74, v74 quad_perm:[1,0,3,2] row_mask:0xf bank_mask:0xf bound_ctrl:1
	v_cvt_pk_f32_fp8_e32 v[64:65], v83
	v_pk_fma_f32 v[72:73], v[64:65], v[146:147], v[72:73]
	v_cvt_pk_f32_fp8_sdwa v[66:67], v83 src0_sel:WORD_1
	v_add_f32_dpp v74, v74, v74 quad_perm:[2,3,0,1] row_mask:0xf bank_mask:0xf bound_ctrl:1
	v_pk_fma_f32 v[72:73], v[66:67], v[148:149], v[72:73]
	v_cvt_pk_f32_fp8_e32 v[44:45], v84
	v_pk_fma_f32 v[72:73], v[44:45], v[150:151], v[72:73]
	v_add_f32_dpp v74, v74, v74 row_half_mirror row_mask:0xf bank_mask:0xf bound_ctrl:1
	v_cvt_pk_f32_fp8_sdwa v[46:47], v84 src0_sel:WORD_1
	v_pk_fma_f32 v[72:73], v[46:47], v[152:153], v[72:73]
	v_cvt_pk_f32_fp8_e32 v[64:65], v85
	v_add_f32_dpp v74, v74, v74 row_mirror row_mask:0xf bank_mask:0xf bound_ctrl:1
	v_pk_fma_f32 v[72:73], v[64:65], v[154:155], v[72:73]
	v_cvt_pk_f32_fp8_sdwa v[66:67], v85 src0_sel:WORD_1
	v_pk_fma_f32 v[72:73], v[66:67], v[156:157], v[72:73]
	v_add_f32_dpp v74, v74, v74 row_bcast:15 row_mask:0xa bank_mask:0xf
	v_cvt_pk_f32_fp8_e32 v[44:45], v86
	v_pk_fma_f32 v[72:73], v[44:45], v[158:159], v[72:73]
	v_cvt_pk_f32_fp8_sdwa v[46:47], v86 src0_sel:WORD_1
	v_add_f32_dpp v74, v74, v74 row_bcast:31 row_mask:0xc bank_mask:0xf
	v_pk_fma_f32 v[72:73], v[46:47], v[160:161], v[72:73]
	v_cvt_pk_f32_fp8_e32 v[64:65], v87
	v_readlane_b32 s48, v74, 63
	v_pk_fma_f32 v[72:73], v[64:65], v[162:163], v[72:73]
	v_cvt_pk_f32_fp8_sdwa v[66:67], v87 src0_sel:WORD_1
	v_pk_fma_f32 v[72:73], v[66:67], v[164:165], v[72:73]
	v_writelane_b32 v189, s48, 13
	s_nop 1
	v_readlane_b32 s100, v132, 5
	v_add_f32_e32 v72, v72, v73
	s_lshl_b32 s100, s100, 11
	s_add_u32 s100, s98, s100
	s_addc_u32 s101, s99, 0
	global_load_dwordx4 v[232:235], v254, s[100:101]
	global_load_dwordx4 v[236:239], v254, s[100:101] offset:1024
	s_waitcnt vmcnt(12)
	v_cvt_pk_f32_fp8_e32 v[44:45], v88
	v_pk_fma_f32 v[74:75], v[44:45], v[134:135], 0 op_sel_hi:[1,1,0]
	v_cvt_pk_f32_fp8_sdwa v[46:47], v88 src0_sel:WORD_1
	v_pk_fma_f32 v[74:75], v[46:47], v[136:137], v[74:75]
	v_cvt_pk_f32_fp8_e32 v[64:65], v89
	v_pk_fma_f32 v[74:75], v[64:65], v[138:139], v[74:75]
	v_cvt_pk_f32_fp8_sdwa v[66:67], v89 src0_sel:WORD_1
	v_pk_fma_f32 v[74:75], v[66:67], v[140:141], v[74:75]
	v_cvt_pk_f32_fp8_e32 v[44:45], v90
	v_pk_fma_f32 v[74:75], v[44:45], v[142:143], v[74:75]
	v_cvt_pk_f32_fp8_sdwa v[46:47], v90 src0_sel:WORD_1
	v_pk_fma_f32 v[74:75], v[46:47], v[144:145], v[74:75]
	v_add_f32_dpp v72, v72, v72 quad_perm:[1,0,3,2] row_mask:0xf bank_mask:0xf bound_ctrl:1
	v_cvt_pk_f32_fp8_e32 v[64:65], v91
	v_pk_fma_f32 v[74:75], v[64:65], v[146:147], v[74:75]
	v_cvt_pk_f32_fp8_sdwa v[66:67], v91 src0_sel:WORD_1
	v_add_f32_dpp v72, v72, v72 quad_perm:[2,3,0,1] row_mask:0xf bank_mask:0xf bound_ctrl:1
	v_pk_fma_f32 v[74:75], v[66:67], v[148:149], v[74:75]
	v_cvt_pk_f32_fp8_e32 v[44:45], v92
	v_pk_fma_f32 v[74:75], v[44:45], v[150:151], v[74:75]
	v_add_f32_dpp v72, v72, v72 row_half_mirror row_mask:0xf bank_mask:0xf bound_ctrl:1
	v_cvt_pk_f32_fp8_sdwa v[46:47], v92 src0_sel:WORD_1
	v_pk_fma_f32 v[74:75], v[46:47], v[152:153], v[74:75]
	v_cvt_pk_f32_fp8_e32 v[64:65], v93
	v_add_f32_dpp v72, v72, v72 row_mirror row_mask:0xf bank_mask:0xf bound_ctrl:1
	v_pk_fma_f32 v[74:75], v[64:65], v[154:155], v[74:75]
	v_cvt_pk_f32_fp8_sdwa v[66:67], v93 src0_sel:WORD_1
	v_pk_fma_f32 v[74:75], v[66:67], v[156:157], v[74:75]
	v_add_f32_dpp v72, v72, v72 row_bcast:15 row_mask:0xa bank_mask:0xf
	v_cvt_pk_f32_fp8_e32 v[44:45], v94
	v_pk_fma_f32 v[74:75], v[44:45], v[158:159], v[74:75]
	v_cvt_pk_f32_fp8_sdwa v[46:47], v94 src0_sel:WORD_1
	v_add_f32_dpp v72, v72, v72 row_bcast:31 row_mask:0xc bank_mask:0xf
	v_pk_fma_f32 v[74:75], v[46:47], v[160:161], v[74:75]
	v_cvt_pk_f32_fp8_e32 v[64:65], v95
	v_readlane_b32 s48, v72, 63
	v_pk_fma_f32 v[74:75], v[64:65], v[162:163], v[74:75]
	v_cvt_pk_f32_fp8_sdwa v[66:67], v95 src0_sel:WORD_1
	v_pk_fma_f32 v[74:75], v[66:67], v[164:165], v[74:75]
	v_writelane_b32 v189, s48, 14
	s_nop 1
	v_add_f32_e32 v74, v74, v75
	s_nop 0
	s_nop 0
	v_add_f32_dpp v74, v74, v74 quad_perm:[1,0,3,2] row_mask:0xf bank_mask:0xf bound_ctrl:1
	s_nop 0
	s_nop 0
	v_add_f32_dpp v74, v74, v74 quad_perm:[2,3,0,1] row_mask:0xf bank_mask:0xf bound_ctrl:1
	s_nop 0
	s_nop 0
	v_add_f32_dpp v74, v74, v74 row_half_mirror row_mask:0xf bank_mask:0xf bound_ctrl:1
	s_nop 0
	s_nop 0
	v_add_f32_dpp v74, v74, v74 row_mirror row_mask:0xf bank_mask:0xf bound_ctrl:1
	s_nop 0
	s_nop 0
	v_add_f32_dpp v74, v74, v74 row_bcast:15 row_mask:0xa bank_mask:0xf
	s_nop 0
	s_nop 0
	v_add_f32_dpp v74, v74, v74 row_bcast:31 row_mask:0xc bank_mask:0xf
	s_nop 0
	v_readlane_b32 s48, v74, 63
	v_mul_f32_e32 v74, v179, v188
	v_mul_f32_e32 v74, 0.5, v74
	v_writelane_b32 v189, s48, 15
	v_mul_f32_e32 v44, v187, v189
	v_mul_f32_e32 v45, 0x3f3504f3, v44
	v_fma_f32 v46, |v45|, s55, v183
	v_fma_f32 v46, |v45|, v46, s56
	v_fma_f32 v46, |v45|, v46, s57
	v_fma_f32 v46, |v45|, v46, s58
	v_fma_f32 v46, |v45|, v46, s59
	v_fma_f32 v46, |v45|, v46, s60
	v_fma_f32 v46, |v45|, v46, |v45|
	v_mul_f32_e32 v47, 0xbfb8aa3b, v46
	v_fma_f32 v64, v46, s61, -v47
	v_rndne_f32_e32 v65, v47
	v_fmac_f32_e32 v64, 0xb2a5705f, v46
	v_sub_f32_e32 v47, v47, v65
	v_add_f32_e32 v47, v47, v64
	v_exp_f32_e32 v47, v47
	v_cmp_nlt_f32_e32 vcc, s62, v46
	v_cvt_i32_f32_e32 v64, v65
	v_ldexp_f32 v47, v47, v64
	v_cndmask_b32_e32 v47, 0, v47, vcc
	v_cmp_ngt_f32_e32 vcc, s63, v46
	v_mul_f32_e32 v64, v45, v45
	v_fmamk_f32 v65, v64, 0xba1345e1, v112
	v_fmaak_f32 v65, v64, v65, 0xbcdac9b8
	v_cndmask_b32_e32 v46, v184, v47, vcc
	v_fmaak_f32 v65, v64, v65, 0x3de703be
	v_fmaak_f32 v65, v64, v65, 0xbec09330
	v_cmp_nlt_f32_e64 vcc, |v45|, 1.0
	v_fmaak_f32 v64, v64, v65, 0x3e0375d0
	v_sub_f32_e32 v66, 1.0, v46
	v_fma_f32 v67, |v45|, v64, |v45|
	v_cndmask_b32_e32 v66, v67, v66, vcc
	v_bfi_b32 v67, s64, v66, v45
	v_mul_f32_e32 v74, v44, v74
	v_add_f32_e32 v67, 1.0, v67
	v_mul_f32_e32 v74, v74, v67
	s_nop 1
	v_readlane_b32 s100, v132, 6
	v_readlane_b32 s48, v74, 0
	s_lshl_b32 s100, s100, 11
	s_add_u32 s100, s98, s100
	s_addc_u32 s101, s99, 0
	global_load_dwordx4 v[242:245], v254, s[100:101]
	global_load_dwordx4 v[246:249], v254, s[100:101] offset:1024
	s_waitcnt vmcnt(12)
	v_mov_b32_e32 v72, s48
	v_cvt_pk_f32_fp8_e32 v[44:45], v192
	v_cvt_pk_f32_fp8_sdwa v[46:47], v192 src0_sel:WORD_1
	v_cvt_pk_f32_fp8_e32 v[64:65], v193
	v_cvt_pk_f32_fp8_sdwa v[66:67], v193 src0_sel:WORD_1
	v_pk_fma_f32 v[68:69], v[72:73], v[44:45], 0 op_sel_hi:[0,1,0]
	v_pk_fma_f32 v[70:71], v[72:73], v[46:47], 0 op_sel_hi:[0,1,0]
	v_pk_fma_f32 v[60:61], v[72:73], v[64:65], 0 op_sel_hi:[0,1,0]
	v_pk_fma_f32 v[62:63], v[72:73], v[66:67], 0 op_sel_hi:[0,1,0]
	v_cvt_pk_f32_fp8_e32 v[44:45], v194
	v_cvt_pk_f32_fp8_sdwa v[46:47], v194 src0_sel:WORD_1
	v_cvt_pk_f32_fp8_e32 v[64:65], v195
	v_cvt_pk_f32_fp8_sdwa v[66:67], v195 src0_sel:WORD_1
	v_pk_fma_f32 v[56:57], v[72:73], v[44:45], 0 op_sel_hi:[0,1,0]
	v_pk_fma_f32 v[58:59], v[72:73], v[46:47], 0 op_sel_hi:[0,1,0]
	v_pk_fma_f32 v[52:53], v[72:73], v[64:65], 0 op_sel_hi:[0,1,0]
	v_pk_fma_f32 v[54:55], v[72:73], v[66:67], 0 op_sel_hi:[0,1,0]
	v_cvt_pk_f32_fp8_e32 v[44:45], v196
	v_cvt_pk_f32_fp8_sdwa v[46:47], v196 src0_sel:WORD_1
	v_cvt_pk_f32_fp8_e32 v[64:65], v197
	v_cvt_pk_f32_fp8_sdwa v[66:67], v197 src0_sel:WORD_1
	v_pk_fma_f32 v[48:49], v[72:73], v[44:45], 0 op_sel_hi:[0,1,0]
	v_pk_fma_f32 v[50:51], v[72:73], v[46:47], 0 op_sel_hi:[0,1,0]
	v_pk_fma_f32 v[40:41], v[72:73], v[64:65], 0 op_sel_hi:[0,1,0]
	v_pk_fma_f32 v[42:43], v[72:73], v[66:67], 0 op_sel_hi:[0,1,0]
	v_cvt_pk_f32_fp8_e32 v[44:45], v198
	v_cvt_pk_f32_fp8_sdwa v[46:47], v198 src0_sel:WORD_1
	v_cvt_pk_f32_fp8_e32 v[64:65], v199
	v_cvt_pk_f32_fp8_sdwa v[66:67], v199 src0_sel:WORD_1
	v_pk_fma_f32 v[36:37], v[72:73], v[44:45], 0 op_sel_hi:[0,1,0]
	v_pk_fma_f32 v[38:39], v[72:73], v[46:47], 0 op_sel_hi:[0,1,0]
	v_pk_fma_f32 v[32:33], v[72:73], v[64:65], 0 op_sel_hi:[0,1,0]
	v_pk_fma_f32 v[34:35], v[72:73], v[66:67], 0 op_sel_hi:[0,1,0]
	s_nop 1
	v_readlane_b32 s100, v132, 7
	v_readlane_b32 s48, v74, 1
	s_lshl_b32 s100, s100, 11
	s_add_u32 s100, s98, s100
	s_addc_u32 s101, s99, 0
	global_load_dwordx4 v[250:253], v254, s[100:101]
	global_load_dwordx4 v[76:79], v254, s[100:101] offset:1024
	s_waitcnt vmcnt(12)
	v_mov_b32_e32 v72, s48
	v_cvt_pk_f32_fp8_e32 v[44:45], v200
	v_cvt_pk_f32_fp8_sdwa v[46:47], v200 src0_sel:WORD_1
	v_cvt_pk_f32_fp8_e32 v[64:65], v201
	v_cvt_pk_f32_fp8_sdwa v[66:67], v201 src0_sel:WORD_1
	v_pk_fma_f32 v[68:69], v[72:73], v[44:45], v[68:69] op_sel_hi:[0,1,1]
	v_pk_fma_f32 v[70:71], v[72:73], v[46:47], v[70:71] op_sel_hi:[0,1,1]
	v_pk_fma_f32 v[60:61], v[72:73], v[64:65], v[60:61] op_sel_hi:[0,1,1]
	v_pk_fma_f32 v[62:63], v[72:73], v[66:67], v[62:63] op_sel_hi:[0,1,1]
	v_cvt_pk_f32_fp8_e32 v[44:45], v202
	v_cvt_pk_f32_fp8_sdwa v[46:47], v202 src0_sel:WORD_1
	v_cvt_pk_f32_fp8_e32 v[64:65], v203
	v_cvt_pk_f32_fp8_sdwa v[66:67], v203 src0_sel:WORD_1
	v_pk_fma_f32 v[56:57], v[72:73], v[44:45], v[56:57] op_sel_hi:[0,1,1]
	v_pk_fma_f32 v[58:59], v[72:73], v[46:47], v[58:59] op_sel_hi:[0,1,1]
	v_pk_fma_f32 v[52:53], v[72:73], v[64:65], v[52:53] op_sel_hi:[0,1,1]
	v_pk_fma_f32 v[54:55], v[72:73], v[66:67], v[54:55] op_sel_hi:[0,1,1]
	v_cvt_pk_f32_fp8_e32 v[44:45], v204
	v_cvt_pk_f32_fp8_sdwa v[46:47], v204 src0_sel:WORD_1
	v_cvt_pk_f32_fp8_e32 v[64:65], v205
	v_cvt_pk_f32_fp8_sdwa v[66:67], v205 src0_sel:WORD_1
	v_pk_fma_f32 v[48:49], v[72:73], v[44:45], v[48:49] op_sel_hi:[0,1,1]
	v_pk_fma_f32 v[50:51], v[72:73], v[46:47], v[50:51] op_sel_hi:[0,1,1]
	v_pk_fma_f32 v[40:41], v[72:73], v[64:65], v[40:41] op_sel_hi:[0,1,1]
	v_pk_fma_f32 v[42:43], v[72:73], v[66:67], v[42:43] op_sel_hi:[0,1,1]
	v_cvt_pk_f32_fp8_e32 v[44:45], v206
	v_cvt_pk_f32_fp8_sdwa v[46:47], v206 src0_sel:WORD_1
	v_cvt_pk_f32_fp8_e32 v[64:65], v207
	v_cvt_pk_f32_fp8_sdwa v[66:67], v207 src0_sel:WORD_1
	v_pk_fma_f32 v[36:37], v[72:73], v[44:45], v[36:37] op_sel_hi:[0,1,1]
	v_pk_fma_f32 v[38:39], v[72:73], v[46:47], v[38:39] op_sel_hi:[0,1,1]
	v_pk_fma_f32 v[32:33], v[72:73], v[64:65], v[32:33] op_sel_hi:[0,1,1]
	v_pk_fma_f32 v[34:35], v[72:73], v[66:67], v[34:35] op_sel_hi:[0,1,1]
	s_nop 1
	v_readlane_b32 s100, v132, 8
	v_readlane_b32 s48, v74, 2
	s_lshl_b32 s100, s100, 11
	s_add_u32 s100, s98, s100
	s_addc_u32 s101, s99, 0
	global_load_dwordx4 v[192:195], v254, s[100:101]
	global_load_dwordx4 v[196:199], v254, s[100:101] offset:1024
	s_waitcnt vmcnt(12)
	v_mov_b32_e32 v72, s48
	v_cvt_pk_f32_fp8_e32 v[44:45], v208
	v_cvt_pk_f32_fp8_sdwa v[46:47], v208 src0_sel:WORD_1
	v_cvt_pk_f32_fp8_e32 v[64:65], v209
	v_cvt_pk_f32_fp8_sdwa v[66:67], v209 src0_sel:WORD_1
	v_pk_fma_f32 v[68:69], v[72:73], v[44:45], v[68:69] op_sel_hi:[0,1,1]
	v_pk_fma_f32 v[70:71], v[72:73], v[46:47], v[70:71] op_sel_hi:[0,1,1]
	v_pk_fma_f32 v[60:61], v[72:73], v[64:65], v[60:61] op_sel_hi:[0,1,1]
	v_pk_fma_f32 v[62:63], v[72:73], v[66:67], v[62:63] op_sel_hi:[0,1,1]
	v_cvt_pk_f32_fp8_e32 v[44:45], v210
	v_cvt_pk_f32_fp8_sdwa v[46:47], v210 src0_sel:WORD_1
	v_cvt_pk_f32_fp8_e32 v[64:65], v211
	v_cvt_pk_f32_fp8_sdwa v[66:67], v211 src0_sel:WORD_1
	v_pk_fma_f32 v[56:57], v[72:73], v[44:45], v[56:57] op_sel_hi:[0,1,1]
	v_pk_fma_f32 v[58:59], v[72:73], v[46:47], v[58:59] op_sel_hi:[0,1,1]
	v_pk_fma_f32 v[52:53], v[72:73], v[64:65], v[52:53] op_sel_hi:[0,1,1]
	v_pk_fma_f32 v[54:55], v[72:73], v[66:67], v[54:55] op_sel_hi:[0,1,1]
	v_cvt_pk_f32_fp8_e32 v[44:45], v212
	v_cvt_pk_f32_fp8_sdwa v[46:47], v212 src0_sel:WORD_1
	v_cvt_pk_f32_fp8_e32 v[64:65], v213
	v_cvt_pk_f32_fp8_sdwa v[66:67], v213 src0_sel:WORD_1
	v_pk_fma_f32 v[48:49], v[72:73], v[44:45], v[48:49] op_sel_hi:[0,1,1]
	v_pk_fma_f32 v[50:51], v[72:73], v[46:47], v[50:51] op_sel_hi:[0,1,1]
	v_pk_fma_f32 v[40:41], v[72:73], v[64:65], v[40:41] op_sel_hi:[0,1,1]
	v_pk_fma_f32 v[42:43], v[72:73], v[66:67], v[42:43] op_sel_hi:[0,1,1]
	v_cvt_pk_f32_fp8_e32 v[44:45], v214
	v_cvt_pk_f32_fp8_sdwa v[46:47], v214 src0_sel:WORD_1
	v_cvt_pk_f32_fp8_e32 v[64:65], v215
	v_cvt_pk_f32_fp8_sdwa v[66:67], v215 src0_sel:WORD_1
	v_pk_fma_f32 v[36:37], v[72:73], v[44:45], v[36:37] op_sel_hi:[0,1,1]
	v_pk_fma_f32 v[38:39], v[72:73], v[46:47], v[38:39] op_sel_hi:[0,1,1]
	v_pk_fma_f32 v[32:33], v[72:73], v[64:65], v[32:33] op_sel_hi:[0,1,1]
	v_pk_fma_f32 v[34:35], v[72:73], v[66:67], v[34:35] op_sel_hi:[0,1,1]
	s_nop 1
	v_readlane_b32 s100, v132, 9
	v_readlane_b32 s48, v74, 3
	s_lshl_b32 s100, s100, 11
	s_add_u32 s100, s98, s100
	s_addc_u32 s101, s99, 0
	global_load_dwordx4 v[200:203], v254, s[100:101]
	global_load_dwordx4 v[204:207], v254, s[100:101] offset:1024
	s_waitcnt vmcnt(12)
	v_mov_b32_e32 v72, s48
	v_cvt_pk_f32_fp8_e32 v[44:45], v216
	v_cvt_pk_f32_fp8_sdwa v[46:47], v216 src0_sel:WORD_1
	v_cvt_pk_f32_fp8_e32 v[64:65], v217
	v_cvt_pk_f32_fp8_sdwa v[66:67], v217 src0_sel:WORD_1
	v_pk_fma_f32 v[68:69], v[72:73], v[44:45], v[68:69] op_sel_hi:[0,1,1]
	v_pk_fma_f32 v[70:71], v[72:73], v[46:47], v[70:71] op_sel_hi:[0,1,1]
	v_pk_fma_f32 v[60:61], v[72:73], v[64:65], v[60:61] op_sel_hi:[0,1,1]
	v_pk_fma_f32 v[62:63], v[72:73], v[66:67], v[62:63] op_sel_hi:[0,1,1]
	v_cvt_pk_f32_fp8_e32 v[44:45], v218
	v_cvt_pk_f32_fp8_sdwa v[46:47], v218 src0_sel:WORD_1
	v_cvt_pk_f32_fp8_e32 v[64:65], v219
	v_cvt_pk_f32_fp8_sdwa v[66:67], v219 src0_sel:WORD_1
	v_pk_fma_f32 v[56:57], v[72:73], v[44:45], v[56:57] op_sel_hi:[0,1,1]
	v_pk_fma_f32 v[58:59], v[72:73], v[46:47], v[58:59] op_sel_hi:[0,1,1]
	v_pk_fma_f32 v[52:53], v[72:73], v[64:65], v[52:53] op_sel_hi:[0,1,1]
	v_pk_fma_f32 v[54:55], v[72:73], v[66:67], v[54:55] op_sel_hi:[0,1,1]
	v_cvt_pk_f32_fp8_e32 v[44:45], v220
	v_cvt_pk_f32_fp8_sdwa v[46:47], v220 src0_sel:WORD_1
	v_cvt_pk_f32_fp8_e32 v[64:65], v221
	v_cvt_pk_f32_fp8_sdwa v[66:67], v221 src0_sel:WORD_1
	v_pk_fma_f32 v[48:49], v[72:73], v[44:45], v[48:49] op_sel_hi:[0,1,1]
	v_pk_fma_f32 v[50:51], v[72:73], v[46:47], v[50:51] op_sel_hi:[0,1,1]
	v_pk_fma_f32 v[40:41], v[72:73], v[64:65], v[40:41] op_sel_hi:[0,1,1]
	v_pk_fma_f32 v[42:43], v[72:73], v[66:67], v[42:43] op_sel_hi:[0,1,1]
	v_cvt_pk_f32_fp8_e32 v[44:45], v222
	v_cvt_pk_f32_fp8_sdwa v[46:47], v222 src0_sel:WORD_1
	v_cvt_pk_f32_fp8_e32 v[64:65], v223
	v_cvt_pk_f32_fp8_sdwa v[66:67], v223 src0_sel:WORD_1
	v_pk_fma_f32 v[36:37], v[72:73], v[44:45], v[36:37] op_sel_hi:[0,1,1]
	v_pk_fma_f32 v[38:39], v[72:73], v[46:47], v[38:39] op_sel_hi:[0,1,1]
	v_pk_fma_f32 v[32:33], v[72:73], v[64:65], v[32:33] op_sel_hi:[0,1,1]
	v_pk_fma_f32 v[34:35], v[72:73], v[66:67], v[34:35] op_sel_hi:[0,1,1]
	s_nop 1
	v_readlane_b32 s100, v132, 10
	v_readlane_b32 s48, v74, 4
	s_lshl_b32 s100, s100, 11
	s_add_u32 s100, s98, s100
	s_addc_u32 s101, s99, 0
	global_load_dwordx4 v[208:211], v254, s[100:101]
	global_load_dwordx4 v[212:215], v254, s[100:101] offset:1024
	s_waitcnt vmcnt(12)
	v_mov_b32_e32 v72, s48
	v_cvt_pk_f32_fp8_e32 v[44:45], v224
	v_cvt_pk_f32_fp8_sdwa v[46:47], v224 src0_sel:WORD_1
	v_cvt_pk_f32_fp8_e32 v[64:65], v225
	v_cvt_pk_f32_fp8_sdwa v[66:67], v225 src0_sel:WORD_1
	v_pk_fma_f32 v[68:69], v[72:73], v[44:45], v[68:69] op_sel_hi:[0,1,1]
	v_pk_fma_f32 v[70:71], v[72:73], v[46:47], v[70:71] op_sel_hi:[0,1,1]
	v_pk_fma_f32 v[60:61], v[72:73], v[64:65], v[60:61] op_sel_hi:[0,1,1]
	v_pk_fma_f32 v[62:63], v[72:73], v[66:67], v[62:63] op_sel_hi:[0,1,1]
	v_cvt_pk_f32_fp8_e32 v[44:45], v226
	v_cvt_pk_f32_fp8_sdwa v[46:47], v226 src0_sel:WORD_1
	v_cvt_pk_f32_fp8_e32 v[64:65], v227
	v_cvt_pk_f32_fp8_sdwa v[66:67], v227 src0_sel:WORD_1
	v_pk_fma_f32 v[56:57], v[72:73], v[44:45], v[56:57] op_sel_hi:[0,1,1]
	v_pk_fma_f32 v[58:59], v[72:73], v[46:47], v[58:59] op_sel_hi:[0,1,1]
	v_pk_fma_f32 v[52:53], v[72:73], v[64:65], v[52:53] op_sel_hi:[0,1,1]
	v_pk_fma_f32 v[54:55], v[72:73], v[66:67], v[54:55] op_sel_hi:[0,1,1]
	v_cvt_pk_f32_fp8_e32 v[44:45], v228
	v_cvt_pk_f32_fp8_sdwa v[46:47], v228 src0_sel:WORD_1
	v_cvt_pk_f32_fp8_e32 v[64:65], v229
	v_cvt_pk_f32_fp8_sdwa v[66:67], v229 src0_sel:WORD_1
	v_pk_fma_f32 v[48:49], v[72:73], v[44:45], v[48:49] op_sel_hi:[0,1,1]
	v_pk_fma_f32 v[50:51], v[72:73], v[46:47], v[50:51] op_sel_hi:[0,1,1]
	v_pk_fma_f32 v[40:41], v[72:73], v[64:65], v[40:41] op_sel_hi:[0,1,1]
	v_pk_fma_f32 v[42:43], v[72:73], v[66:67], v[42:43] op_sel_hi:[0,1,1]
	v_cvt_pk_f32_fp8_e32 v[44:45], v230
	v_cvt_pk_f32_fp8_sdwa v[46:47], v230 src0_sel:WORD_1
	v_cvt_pk_f32_fp8_e32 v[64:65], v231
	v_cvt_pk_f32_fp8_sdwa v[66:67], v231 src0_sel:WORD_1
	v_pk_fma_f32 v[36:37], v[72:73], v[44:45], v[36:37] op_sel_hi:[0,1,1]
	v_pk_fma_f32 v[38:39], v[72:73], v[46:47], v[38:39] op_sel_hi:[0,1,1]
	v_pk_fma_f32 v[32:33], v[72:73], v[64:65], v[32:33] op_sel_hi:[0,1,1]
	v_pk_fma_f32 v[34:35], v[72:73], v[66:67], v[34:35] op_sel_hi:[0,1,1]
	s_nop 1
	v_readlane_b32 s100, v132, 11
	v_readlane_b32 s48, v74, 5
	s_lshl_b32 s100, s100, 11
	s_add_u32 s100, s98, s100
	s_addc_u32 s101, s99, 0
	global_load_dwordx4 v[216:219], v254, s[100:101]
	global_load_dwordx4 v[220:223], v254, s[100:101] offset:1024
	s_waitcnt vmcnt(12)
	v_mov_b32_e32 v72, s48
	v_cvt_pk_f32_fp8_e32 v[44:45], v232
	v_cvt_pk_f32_fp8_sdwa v[46:47], v232 src0_sel:WORD_1
	v_cvt_pk_f32_fp8_e32 v[64:65], v233
	v_cvt_pk_f32_fp8_sdwa v[66:67], v233 src0_sel:WORD_1
	v_pk_fma_f32 v[68:69], v[72:73], v[44:45], v[68:69] op_sel_hi:[0,1,1]
	v_pk_fma_f32 v[70:71], v[72:73], v[46:47], v[70:71] op_sel_hi:[0,1,1]
	v_pk_fma_f32 v[60:61], v[72:73], v[64:65], v[60:61] op_sel_hi:[0,1,1]
	v_pk_fma_f32 v[62:63], v[72:73], v[66:67], v[62:63] op_sel_hi:[0,1,1]
	v_cvt_pk_f32_fp8_e32 v[44:45], v234
	v_cvt_pk_f32_fp8_sdwa v[46:47], v234 src0_sel:WORD_1
	v_cvt_pk_f32_fp8_e32 v[64:65], v235
	v_cvt_pk_f32_fp8_sdwa v[66:67], v235 src0_sel:WORD_1
	v_pk_fma_f32 v[56:57], v[72:73], v[44:45], v[56:57] op_sel_hi:[0,1,1]
	v_pk_fma_f32 v[58:59], v[72:73], v[46:47], v[58:59] op_sel_hi:[0,1,1]
	v_pk_fma_f32 v[52:53], v[72:73], v[64:65], v[52:53] op_sel_hi:[0,1,1]
	v_pk_fma_f32 v[54:55], v[72:73], v[66:67], v[54:55] op_sel_hi:[0,1,1]
	v_cvt_pk_f32_fp8_e32 v[44:45], v236
	v_cvt_pk_f32_fp8_sdwa v[46:47], v236 src0_sel:WORD_1
	v_cvt_pk_f32_fp8_e32 v[64:65], v237
	v_cvt_pk_f32_fp8_sdwa v[66:67], v237 src0_sel:WORD_1
	v_pk_fma_f32 v[48:49], v[72:73], v[44:45], v[48:49] op_sel_hi:[0,1,1]
	v_pk_fma_f32 v[50:51], v[72:73], v[46:47], v[50:51] op_sel_hi:[0,1,1]
	v_pk_fma_f32 v[40:41], v[72:73], v[64:65], v[40:41] op_sel_hi:[0,1,1]
	v_pk_fma_f32 v[42:43], v[72:73], v[66:67], v[42:43] op_sel_hi:[0,1,1]
	v_cvt_pk_f32_fp8_e32 v[44:45], v238
	v_cvt_pk_f32_fp8_sdwa v[46:47], v238 src0_sel:WORD_1
	v_cvt_pk_f32_fp8_e32 v[64:65], v239
	v_cvt_pk_f32_fp8_sdwa v[66:67], v239 src0_sel:WORD_1
	v_pk_fma_f32 v[36:37], v[72:73], v[44:45], v[36:37] op_sel_hi:[0,1,1]
	v_pk_fma_f32 v[38:39], v[72:73], v[46:47], v[38:39] op_sel_hi:[0,1,1]
	v_pk_fma_f32 v[32:33], v[72:73], v[64:65], v[32:33] op_sel_hi:[0,1,1]
	v_pk_fma_f32 v[34:35], v[72:73], v[66:67], v[34:35] op_sel_hi:[0,1,1]
	s_nop 1
	v_readlane_b32 s100, v132, 12
	v_readlane_b32 s48, v74, 6
	s_lshl_b32 s100, s100, 11
	s_add_u32 s100, s98, s100
	s_addc_u32 s101, s99, 0
	global_load_dwordx4 v[224:227], v254, s[100:101]
	global_load_dwordx4 v[228:231], v254, s[100:101] offset:1024
	s_waitcnt vmcnt(12)
	v_mov_b32_e32 v72, s48
	v_cvt_pk_f32_fp8_e32 v[44:45], v242
	v_cvt_pk_f32_fp8_sdwa v[46:47], v242 src0_sel:WORD_1
	v_cvt_pk_f32_fp8_e32 v[64:65], v243
	v_cvt_pk_f32_fp8_sdwa v[66:67], v243 src0_sel:WORD_1
	v_pk_fma_f32 v[68:69], v[72:73], v[44:45], v[68:69] op_sel_hi:[0,1,1]
	v_pk_fma_f32 v[70:71], v[72:73], v[46:47], v[70:71] op_sel_hi:[0,1,1]
	v_pk_fma_f32 v[60:61], v[72:73], v[64:65], v[60:61] op_sel_hi:[0,1,1]
	v_pk_fma_f32 v[62:63], v[72:73], v[66:67], v[62:63] op_sel_hi:[0,1,1]
	v_cvt_pk_f32_fp8_e32 v[44:45], v244
	v_cvt_pk_f32_fp8_sdwa v[46:47], v244 src0_sel:WORD_1
	v_cvt_pk_f32_fp8_e32 v[64:65], v245
	v_cvt_pk_f32_fp8_sdwa v[66:67], v245 src0_sel:WORD_1
	v_pk_fma_f32 v[56:57], v[72:73], v[44:45], v[56:57] op_sel_hi:[0,1,1]
	v_pk_fma_f32 v[58:59], v[72:73], v[46:47], v[58:59] op_sel_hi:[0,1,1]
	v_pk_fma_f32 v[52:53], v[72:73], v[64:65], v[52:53] op_sel_hi:[0,1,1]
	v_pk_fma_f32 v[54:55], v[72:73], v[66:67], v[54:55] op_sel_hi:[0,1,1]
	v_cvt_pk_f32_fp8_e32 v[44:45], v246
	v_cvt_pk_f32_fp8_sdwa v[46:47], v246 src0_sel:WORD_1
	v_cvt_pk_f32_fp8_e32 v[64:65], v247
	v_cvt_pk_f32_fp8_sdwa v[66:67], v247 src0_sel:WORD_1
	v_pk_fma_f32 v[48:49], v[72:73], v[44:45], v[48:49] op_sel_hi:[0,1,1]
	v_pk_fma_f32 v[50:51], v[72:73], v[46:47], v[50:51] op_sel_hi:[0,1,1]
	v_pk_fma_f32 v[40:41], v[72:73], v[64:65], v[40:41] op_sel_hi:[0,1,1]
	v_pk_fma_f32 v[42:43], v[72:73], v[66:67], v[42:43] op_sel_hi:[0,1,1]
	v_cvt_pk_f32_fp8_e32 v[44:45], v248
	v_cvt_pk_f32_fp8_sdwa v[46:47], v248 src0_sel:WORD_1
	v_cvt_pk_f32_fp8_e32 v[64:65], v249
	v_cvt_pk_f32_fp8_sdwa v[66:67], v249 src0_sel:WORD_1
	v_pk_fma_f32 v[36:37], v[72:73], v[44:45], v[36:37] op_sel_hi:[0,1,1]
	v_pk_fma_f32 v[38:39], v[72:73], v[46:47], v[38:39] op_sel_hi:[0,1,1]
	v_pk_fma_f32 v[32:33], v[72:73], v[64:65], v[32:33] op_sel_hi:[0,1,1]
	v_pk_fma_f32 v[34:35], v[72:73], v[66:67], v[34:35] op_sel_hi:[0,1,1]
	s_nop 1
	v_readlane_b32 s100, v132, 13
	v_readlane_b32 s48, v74, 7
	s_lshl_b32 s100, s100, 11
	s_add_u32 s100, s98, s100
	s_addc_u32 s101, s99, 0
	global_load_dwordx4 v[232:235], v254, s[100:101]
	global_load_dwordx4 v[236:239], v254, s[100:101] offset:1024
	s_waitcnt vmcnt(12)
	v_mov_b32_e32 v72, s48
	v_cvt_pk_f32_fp8_e32 v[44:45], v250
	v_cvt_pk_f32_fp8_sdwa v[46:47], v250 src0_sel:WORD_1
	v_cvt_pk_f32_fp8_e32 v[64:65], v251
	v_cvt_pk_f32_fp8_sdwa v[66:67], v251 src0_sel:WORD_1
	v_pk_fma_f32 v[68:69], v[72:73], v[44:45], v[68:69] op_sel_hi:[0,1,1]
	v_pk_fma_f32 v[70:71], v[72:73], v[46:47], v[70:71] op_sel_hi:[0,1,1]
	v_pk_fma_f32 v[60:61], v[72:73], v[64:65], v[60:61] op_sel_hi:[0,1,1]
	v_pk_fma_f32 v[62:63], v[72:73], v[66:67], v[62:63] op_sel_hi:[0,1,1]
	v_cvt_pk_f32_fp8_e32 v[44:45], v252
	v_cvt_pk_f32_fp8_sdwa v[46:47], v252 src0_sel:WORD_1
	v_cvt_pk_f32_fp8_e32 v[64:65], v253
	v_cvt_pk_f32_fp8_sdwa v[66:67], v253 src0_sel:WORD_1
	v_pk_fma_f32 v[56:57], v[72:73], v[44:45], v[56:57] op_sel_hi:[0,1,1]
	v_pk_fma_f32 v[58:59], v[72:73], v[46:47], v[58:59] op_sel_hi:[0,1,1]
	v_pk_fma_f32 v[52:53], v[72:73], v[64:65], v[52:53] op_sel_hi:[0,1,1]
	v_pk_fma_f32 v[54:55], v[72:73], v[66:67], v[54:55] op_sel_hi:[0,1,1]
	v_cvt_pk_f32_fp8_e32 v[44:45], v76
	v_cvt_pk_f32_fp8_sdwa v[46:47], v76 src0_sel:WORD_1
	v_cvt_pk_f32_fp8_e32 v[64:65], v77
	v_cvt_pk_f32_fp8_sdwa v[66:67], v77 src0_sel:WORD_1
	v_pk_fma_f32 v[48:49], v[72:73], v[44:45], v[48:49] op_sel_hi:[0,1,1]
	v_pk_fma_f32 v[50:51], v[72:73], v[46:47], v[50:51] op_sel_hi:[0,1,1]
	v_pk_fma_f32 v[40:41], v[72:73], v[64:65], v[40:41] op_sel_hi:[0,1,1]
	v_pk_fma_f32 v[42:43], v[72:73], v[66:67], v[42:43] op_sel_hi:[0,1,1]
	v_cvt_pk_f32_fp8_e32 v[44:45], v78
	v_cvt_pk_f32_fp8_sdwa v[46:47], v78 src0_sel:WORD_1
	v_cvt_pk_f32_fp8_e32 v[64:65], v79
	v_cvt_pk_f32_fp8_sdwa v[66:67], v79 src0_sel:WORD_1
	v_pk_fma_f32 v[36:37], v[72:73], v[44:45], v[36:37] op_sel_hi:[0,1,1]
	v_pk_fma_f32 v[38:39], v[72:73], v[46:47], v[38:39] op_sel_hi:[0,1,1]
	v_pk_fma_f32 v[32:33], v[72:73], v[64:65], v[32:33] op_sel_hi:[0,1,1]
	v_pk_fma_f32 v[34:35], v[72:73], v[66:67], v[34:35] op_sel_hi:[0,1,1]
	s_nop 1
	v_readlane_b32 s100, v132, 14
	v_readlane_b32 s48, v74, 8
	s_lshl_b32 s100, s100, 11
	s_add_u32 s100, s98, s100
	s_addc_u32 s101, s99, 0
	global_load_dwordx4 v[242:245], v254, s[100:101]
	global_load_dwordx4 v[246:249], v254, s[100:101] offset:1024
	s_waitcnt vmcnt(12)
	v_mov_b32_e32 v72, s48
	v_cvt_pk_f32_fp8_e32 v[44:45], v192
	v_cvt_pk_f32_fp8_sdwa v[46:47], v192 src0_sel:WORD_1
	v_cvt_pk_f32_fp8_e32 v[64:65], v193
	v_cvt_pk_f32_fp8_sdwa v[66:67], v193 src0_sel:WORD_1
	v_pk_fma_f32 v[68:69], v[72:73], v[44:45], v[68:69] op_sel_hi:[0,1,1]
	v_pk_fma_f32 v[70:71], v[72:73], v[46:47], v[70:71] op_sel_hi:[0,1,1]
	v_pk_fma_f32 v[60:61], v[72:73], v[64:65], v[60:61] op_sel_hi:[0,1,1]
	v_pk_fma_f32 v[62:63], v[72:73], v[66:67], v[62:63] op_sel_hi:[0,1,1]
	v_cvt_pk_f32_fp8_e32 v[44:45], v194
	v_cvt_pk_f32_fp8_sdwa v[46:47], v194 src0_sel:WORD_1
	v_cvt_pk_f32_fp8_e32 v[64:65], v195
	v_cvt_pk_f32_fp8_sdwa v[66:67], v195 src0_sel:WORD_1
	v_pk_fma_f32 v[56:57], v[72:73], v[44:45], v[56:57] op_sel_hi:[0,1,1]
	v_pk_fma_f32 v[58:59], v[72:73], v[46:47], v[58:59] op_sel_hi:[0,1,1]
	v_pk_fma_f32 v[52:53], v[72:73], v[64:65], v[52:53] op_sel_hi:[0,1,1]
	v_pk_fma_f32 v[54:55], v[72:73], v[66:67], v[54:55] op_sel_hi:[0,1,1]
	v_cvt_pk_f32_fp8_e32 v[44:45], v196
	v_cvt_pk_f32_fp8_sdwa v[46:47], v196 src0_sel:WORD_1
	v_cvt_pk_f32_fp8_e32 v[64:65], v197
	v_cvt_pk_f32_fp8_sdwa v[66:67], v197 src0_sel:WORD_1
	v_pk_fma_f32 v[48:49], v[72:73], v[44:45], v[48:49] op_sel_hi:[0,1,1]
	v_pk_fma_f32 v[50:51], v[72:73], v[46:47], v[50:51] op_sel_hi:[0,1,1]
	v_pk_fma_f32 v[40:41], v[72:73], v[64:65], v[40:41] op_sel_hi:[0,1,1]
	v_pk_fma_f32 v[42:43], v[72:73], v[66:67], v[42:43] op_sel_hi:[0,1,1]
	v_cvt_pk_f32_fp8_e32 v[44:45], v198
	v_cvt_pk_f32_fp8_sdwa v[46:47], v198 src0_sel:WORD_1
	v_cvt_pk_f32_fp8_e32 v[64:65], v199
	v_cvt_pk_f32_fp8_sdwa v[66:67], v199 src0_sel:WORD_1
	v_pk_fma_f32 v[36:37], v[72:73], v[44:45], v[36:37] op_sel_hi:[0,1,1]
	v_pk_fma_f32 v[38:39], v[72:73], v[46:47], v[38:39] op_sel_hi:[0,1,1]
	v_pk_fma_f32 v[32:33], v[72:73], v[64:65], v[32:33] op_sel_hi:[0,1,1]
	v_pk_fma_f32 v[34:35], v[72:73], v[66:67], v[34:35] op_sel_hi:[0,1,1]
	s_nop 1
	v_readlane_b32 s100, v132, 15
	v_readlane_b32 s48, v74, 9
	s_lshl_b32 s100, s100, 11
	s_add_u32 s100, s98, s100
	s_addc_u32 s101, s99, 0
	global_load_dwordx4 v[250:253], v254, s[100:101]
	global_load_dwordx4 v[76:79], v254, s[100:101] offset:1024
	s_waitcnt vmcnt(12)
	v_mov_b32_e32 v72, s48
	v_cvt_pk_f32_fp8_e32 v[44:45], v200
	v_cvt_pk_f32_fp8_sdwa v[46:47], v200 src0_sel:WORD_1
	v_cvt_pk_f32_fp8_e32 v[64:65], v201
	v_cvt_pk_f32_fp8_sdwa v[66:67], v201 src0_sel:WORD_1
	v_pk_fma_f32 v[68:69], v[72:73], v[44:45], v[68:69] op_sel_hi:[0,1,1]
	v_pk_fma_f32 v[70:71], v[72:73], v[46:47], v[70:71] op_sel_hi:[0,1,1]
	v_pk_fma_f32 v[60:61], v[72:73], v[64:65], v[60:61] op_sel_hi:[0,1,1]
	v_pk_fma_f32 v[62:63], v[72:73], v[66:67], v[62:63] op_sel_hi:[0,1,1]
	v_cvt_pk_f32_fp8_e32 v[44:45], v202
	v_cvt_pk_f32_fp8_sdwa v[46:47], v202 src0_sel:WORD_1
	v_cvt_pk_f32_fp8_e32 v[64:65], v203
	v_cvt_pk_f32_fp8_sdwa v[66:67], v203 src0_sel:WORD_1
	v_pk_fma_f32 v[56:57], v[72:73], v[44:45], v[56:57] op_sel_hi:[0,1,1]
	v_pk_fma_f32 v[58:59], v[72:73], v[46:47], v[58:59] op_sel_hi:[0,1,1]
	v_pk_fma_f32 v[52:53], v[72:73], v[64:65], v[52:53] op_sel_hi:[0,1,1]
	v_pk_fma_f32 v[54:55], v[72:73], v[66:67], v[54:55] op_sel_hi:[0,1,1]
	v_cvt_pk_f32_fp8_e32 v[44:45], v204
	v_cvt_pk_f32_fp8_sdwa v[46:47], v204 src0_sel:WORD_1
	v_cvt_pk_f32_fp8_e32 v[64:65], v205
	v_cvt_pk_f32_fp8_sdwa v[66:67], v205 src0_sel:WORD_1
	v_pk_fma_f32 v[48:49], v[72:73], v[44:45], v[48:49] op_sel_hi:[0,1,1]
	v_pk_fma_f32 v[50:51], v[72:73], v[46:47], v[50:51] op_sel_hi:[0,1,1]
	v_pk_fma_f32 v[40:41], v[72:73], v[64:65], v[40:41] op_sel_hi:[0,1,1]
	v_pk_fma_f32 v[42:43], v[72:73], v[66:67], v[42:43] op_sel_hi:[0,1,1]
	v_cvt_pk_f32_fp8_e32 v[44:45], v206
	v_cvt_pk_f32_fp8_sdwa v[46:47], v206 src0_sel:WORD_1
	v_cvt_pk_f32_fp8_e32 v[64:65], v207
	v_cvt_pk_f32_fp8_sdwa v[66:67], v207 src0_sel:WORD_1
	v_pk_fma_f32 v[36:37], v[72:73], v[44:45], v[36:37] op_sel_hi:[0,1,1]
	v_pk_fma_f32 v[38:39], v[72:73], v[46:47], v[38:39] op_sel_hi:[0,1,1]
	v_pk_fma_f32 v[32:33], v[72:73], v[64:65], v[32:33] op_sel_hi:[0,1,1]
	v_pk_fma_f32 v[34:35], v[72:73], v[66:67], v[34:35] op_sel_hi:[0,1,1]
	s_nop 1
	v_readlane_b32 s100, v133, 0
	v_readlane_b32 s48, v74, 10
	s_lshl_b32 s100, s100, 11
	s_add_u32 s100, s96, s100
	s_addc_u32 s101, s97, 0
	global_load_dwordx4 v[0:3], v254, s[100:101]
	global_load_dwordx4 v[4:7], v254, s[100:101] offset:1024
	s_waitcnt vmcnt(12)
	v_mov_b32_e32 v72, s48
	v_cvt_pk_f32_fp8_e32 v[44:45], v208
	v_cvt_pk_f32_fp8_sdwa v[46:47], v208 src0_sel:WORD_1
	v_cvt_pk_f32_fp8_e32 v[64:65], v209
	v_cvt_pk_f32_fp8_sdwa v[66:67], v209 src0_sel:WORD_1
	v_pk_fma_f32 v[68:69], v[72:73], v[44:45], v[68:69] op_sel_hi:[0,1,1]
	v_pk_fma_f32 v[70:71], v[72:73], v[46:47], v[70:71] op_sel_hi:[0,1,1]
	v_pk_fma_f32 v[60:61], v[72:73], v[64:65], v[60:61] op_sel_hi:[0,1,1]
	v_pk_fma_f32 v[62:63], v[72:73], v[66:67], v[62:63] op_sel_hi:[0,1,1]
	v_cvt_pk_f32_fp8_e32 v[44:45], v210
	v_cvt_pk_f32_fp8_sdwa v[46:47], v210 src0_sel:WORD_1
	v_cvt_pk_f32_fp8_e32 v[64:65], v211
	v_cvt_pk_f32_fp8_sdwa v[66:67], v211 src0_sel:WORD_1
	v_pk_fma_f32 v[56:57], v[72:73], v[44:45], v[56:57] op_sel_hi:[0,1,1]
	v_pk_fma_f32 v[58:59], v[72:73], v[46:47], v[58:59] op_sel_hi:[0,1,1]
	v_pk_fma_f32 v[52:53], v[72:73], v[64:65], v[52:53] op_sel_hi:[0,1,1]
	v_pk_fma_f32 v[54:55], v[72:73], v[66:67], v[54:55] op_sel_hi:[0,1,1]
	v_cvt_pk_f32_fp8_e32 v[44:45], v212
	v_cvt_pk_f32_fp8_sdwa v[46:47], v212 src0_sel:WORD_1
	v_cvt_pk_f32_fp8_e32 v[64:65], v213
	v_cvt_pk_f32_fp8_sdwa v[66:67], v213 src0_sel:WORD_1
	v_pk_fma_f32 v[48:49], v[72:73], v[44:45], v[48:49] op_sel_hi:[0,1,1]
	v_pk_fma_f32 v[50:51], v[72:73], v[46:47], v[50:51] op_sel_hi:[0,1,1]
	v_pk_fma_f32 v[40:41], v[72:73], v[64:65], v[40:41] op_sel_hi:[0,1,1]
	v_pk_fma_f32 v[42:43], v[72:73], v[66:67], v[42:43] op_sel_hi:[0,1,1]
	v_cvt_pk_f32_fp8_e32 v[44:45], v214
	v_cvt_pk_f32_fp8_sdwa v[46:47], v214 src0_sel:WORD_1
	v_cvt_pk_f32_fp8_e32 v[64:65], v215
	v_cvt_pk_f32_fp8_sdwa v[66:67], v215 src0_sel:WORD_1
	v_pk_fma_f32 v[36:37], v[72:73], v[44:45], v[36:37] op_sel_hi:[0,1,1]
	v_pk_fma_f32 v[38:39], v[72:73], v[46:47], v[38:39] op_sel_hi:[0,1,1]
	v_pk_fma_f32 v[32:33], v[72:73], v[64:65], v[32:33] op_sel_hi:[0,1,1]
	v_pk_fma_f32 v[34:35], v[72:73], v[66:67], v[34:35] op_sel_hi:[0,1,1]
	s_nop 1
	v_readlane_b32 s100, v133, 1
	v_readlane_b32 s48, v74, 11
	s_lshl_b32 s100, s100, 11
	s_add_u32 s100, s96, s100
	s_addc_u32 s101, s97, 0
	global_load_dwordx4 v[8:11], v254, s[100:101]
	global_load_dwordx4 v[12:15], v254, s[100:101] offset:1024
	s_waitcnt vmcnt(12)
	v_mov_b32_e32 v72, s48
	v_cvt_pk_f32_fp8_e32 v[44:45], v216
	v_cvt_pk_f32_fp8_sdwa v[46:47], v216 src0_sel:WORD_1
	v_cvt_pk_f32_fp8_e32 v[64:65], v217
	v_cvt_pk_f32_fp8_sdwa v[66:67], v217 src0_sel:WORD_1
	v_pk_fma_f32 v[68:69], v[72:73], v[44:45], v[68:69] op_sel_hi:[0,1,1]
	v_pk_fma_f32 v[70:71], v[72:73], v[46:47], v[70:71] op_sel_hi:[0,1,1]
	v_pk_fma_f32 v[60:61], v[72:73], v[64:65], v[60:61] op_sel_hi:[0,1,1]
	v_pk_fma_f32 v[62:63], v[72:73], v[66:67], v[62:63] op_sel_hi:[0,1,1]
	v_cvt_pk_f32_fp8_e32 v[44:45], v218
	v_cvt_pk_f32_fp8_sdwa v[46:47], v218 src0_sel:WORD_1
	v_cvt_pk_f32_fp8_e32 v[64:65], v219
	v_cvt_pk_f32_fp8_sdwa v[66:67], v219 src0_sel:WORD_1
	v_pk_fma_f32 v[56:57], v[72:73], v[44:45], v[56:57] op_sel_hi:[0,1,1]
	v_pk_fma_f32 v[58:59], v[72:73], v[46:47], v[58:59] op_sel_hi:[0,1,1]
	v_pk_fma_f32 v[52:53], v[72:73], v[64:65], v[52:53] op_sel_hi:[0,1,1]
	v_pk_fma_f32 v[54:55], v[72:73], v[66:67], v[54:55] op_sel_hi:[0,1,1]
	v_cvt_pk_f32_fp8_e32 v[44:45], v220
	v_cvt_pk_f32_fp8_sdwa v[46:47], v220 src0_sel:WORD_1
	v_cvt_pk_f32_fp8_e32 v[64:65], v221
	v_cvt_pk_f32_fp8_sdwa v[66:67], v221 src0_sel:WORD_1
	v_pk_fma_f32 v[48:49], v[72:73], v[44:45], v[48:49] op_sel_hi:[0,1,1]
	v_pk_fma_f32 v[50:51], v[72:73], v[46:47], v[50:51] op_sel_hi:[0,1,1]
	v_pk_fma_f32 v[40:41], v[72:73], v[64:65], v[40:41] op_sel_hi:[0,1,1]
	v_pk_fma_f32 v[42:43], v[72:73], v[66:67], v[42:43] op_sel_hi:[0,1,1]
	v_cvt_pk_f32_fp8_e32 v[44:45], v222
	v_cvt_pk_f32_fp8_sdwa v[46:47], v222 src0_sel:WORD_1
	v_cvt_pk_f32_fp8_e32 v[64:65], v223
	v_cvt_pk_f32_fp8_sdwa v[66:67], v223 src0_sel:WORD_1
	v_pk_fma_f32 v[36:37], v[72:73], v[44:45], v[36:37] op_sel_hi:[0,1,1]
	v_pk_fma_f32 v[38:39], v[72:73], v[46:47], v[38:39] op_sel_hi:[0,1,1]
	v_pk_fma_f32 v[32:33], v[72:73], v[64:65], v[32:33] op_sel_hi:[0,1,1]
	v_pk_fma_f32 v[34:35], v[72:73], v[66:67], v[34:35] op_sel_hi:[0,1,1]
	s_nop 1
	v_readlane_b32 s100, v133, 2
	v_readlane_b32 s48, v74, 12
	s_lshl_b32 s100, s100, 11
	s_add_u32 s100, s96, s100
	s_addc_u32 s101, s97, 0
	global_load_dwordx4 v[16:19], v254, s[100:101]
	global_load_dwordx4 v[20:23], v254, s[100:101] offset:1024
	s_waitcnt vmcnt(12)
	v_mov_b32_e32 v72, s48
	v_cvt_pk_f32_fp8_e32 v[44:45], v224
	v_cvt_pk_f32_fp8_sdwa v[46:47], v224 src0_sel:WORD_1
	v_cvt_pk_f32_fp8_e32 v[64:65], v225
	v_cvt_pk_f32_fp8_sdwa v[66:67], v225 src0_sel:WORD_1
	v_pk_fma_f32 v[68:69], v[72:73], v[44:45], v[68:69] op_sel_hi:[0,1,1]
	v_pk_fma_f32 v[70:71], v[72:73], v[46:47], v[70:71] op_sel_hi:[0,1,1]
	v_pk_fma_f32 v[60:61], v[72:73], v[64:65], v[60:61] op_sel_hi:[0,1,1]
	v_pk_fma_f32 v[62:63], v[72:73], v[66:67], v[62:63] op_sel_hi:[0,1,1]
	v_cvt_pk_f32_fp8_e32 v[44:45], v226
	v_cvt_pk_f32_fp8_sdwa v[46:47], v226 src0_sel:WORD_1
	v_cvt_pk_f32_fp8_e32 v[64:65], v227
	v_cvt_pk_f32_fp8_sdwa v[66:67], v227 src0_sel:WORD_1
	v_pk_fma_f32 v[56:57], v[72:73], v[44:45], v[56:57] op_sel_hi:[0,1,1]
	v_pk_fma_f32 v[58:59], v[72:73], v[46:47], v[58:59] op_sel_hi:[0,1,1]
	v_pk_fma_f32 v[52:53], v[72:73], v[64:65], v[52:53] op_sel_hi:[0,1,1]
	v_pk_fma_f32 v[54:55], v[72:73], v[66:67], v[54:55] op_sel_hi:[0,1,1]
	v_cvt_pk_f32_fp8_e32 v[44:45], v228
	v_cvt_pk_f32_fp8_sdwa v[46:47], v228 src0_sel:WORD_1
	v_cvt_pk_f32_fp8_e32 v[64:65], v229
	v_cvt_pk_f32_fp8_sdwa v[66:67], v229 src0_sel:WORD_1
	v_pk_fma_f32 v[48:49], v[72:73], v[44:45], v[48:49] op_sel_hi:[0,1,1]
	v_pk_fma_f32 v[50:51], v[72:73], v[46:47], v[50:51] op_sel_hi:[0,1,1]
	v_pk_fma_f32 v[40:41], v[72:73], v[64:65], v[40:41] op_sel_hi:[0,1,1]
	v_pk_fma_f32 v[42:43], v[72:73], v[66:67], v[42:43] op_sel_hi:[0,1,1]
	v_cvt_pk_f32_fp8_e32 v[44:45], v230
	v_cvt_pk_f32_fp8_sdwa v[46:47], v230 src0_sel:WORD_1
	v_cvt_pk_f32_fp8_e32 v[64:65], v231
	v_cvt_pk_f32_fp8_sdwa v[66:67], v231 src0_sel:WORD_1
	v_pk_fma_f32 v[36:37], v[72:73], v[44:45], v[36:37] op_sel_hi:[0,1,1]
	v_pk_fma_f32 v[38:39], v[72:73], v[46:47], v[38:39] op_sel_hi:[0,1,1]
	v_pk_fma_f32 v[32:33], v[72:73], v[64:65], v[32:33] op_sel_hi:[0,1,1]
	v_pk_fma_f32 v[34:35], v[72:73], v[66:67], v[34:35] op_sel_hi:[0,1,1]
	s_nop 1
	v_readlane_b32 s100, v133, 3
	v_readlane_b32 s48, v74, 13
	s_lshl_b32 s100, s100, 11
	s_add_u32 s100, s96, s100
	s_addc_u32 s101, s97, 0
	global_load_dwordx4 v[24:27], v254, s[100:101]
	global_load_dwordx4 v[28:31], v254, s[100:101] offset:1024
	s_waitcnt vmcnt(12)
	v_mov_b32_e32 v72, s48
	v_cvt_pk_f32_fp8_e32 v[44:45], v232
	v_cvt_pk_f32_fp8_sdwa v[46:47], v232 src0_sel:WORD_1
	v_cvt_pk_f32_fp8_e32 v[64:65], v233
	v_cvt_pk_f32_fp8_sdwa v[66:67], v233 src0_sel:WORD_1
	v_pk_fma_f32 v[68:69], v[72:73], v[44:45], v[68:69] op_sel_hi:[0,1,1]
	v_pk_fma_f32 v[70:71], v[72:73], v[46:47], v[70:71] op_sel_hi:[0,1,1]
	v_pk_fma_f32 v[60:61], v[72:73], v[64:65], v[60:61] op_sel_hi:[0,1,1]
	v_pk_fma_f32 v[62:63], v[72:73], v[66:67], v[62:63] op_sel_hi:[0,1,1]
	v_cvt_pk_f32_fp8_e32 v[44:45], v234
	v_cvt_pk_f32_fp8_sdwa v[46:47], v234 src0_sel:WORD_1
	v_cvt_pk_f32_fp8_e32 v[64:65], v235
	v_cvt_pk_f32_fp8_sdwa v[66:67], v235 src0_sel:WORD_1
	v_pk_fma_f32 v[56:57], v[72:73], v[44:45], v[56:57] op_sel_hi:[0,1,1]
	v_pk_fma_f32 v[58:59], v[72:73], v[46:47], v[58:59] op_sel_hi:[0,1,1]
	v_pk_fma_f32 v[52:53], v[72:73], v[64:65], v[52:53] op_sel_hi:[0,1,1]
	v_pk_fma_f32 v[54:55], v[72:73], v[66:67], v[54:55] op_sel_hi:[0,1,1]
	v_cvt_pk_f32_fp8_e32 v[44:45], v236
	v_cvt_pk_f32_fp8_sdwa v[46:47], v236 src0_sel:WORD_1
	v_cvt_pk_f32_fp8_e32 v[64:65], v237
	v_cvt_pk_f32_fp8_sdwa v[66:67], v237 src0_sel:WORD_1
	v_pk_fma_f32 v[48:49], v[72:73], v[44:45], v[48:49] op_sel_hi:[0,1,1]
	v_pk_fma_f32 v[50:51], v[72:73], v[46:47], v[50:51] op_sel_hi:[0,1,1]
	v_pk_fma_f32 v[40:41], v[72:73], v[64:65], v[40:41] op_sel_hi:[0,1,1]
	v_pk_fma_f32 v[42:43], v[72:73], v[66:67], v[42:43] op_sel_hi:[0,1,1]
	v_cvt_pk_f32_fp8_e32 v[44:45], v238
	v_cvt_pk_f32_fp8_sdwa v[46:47], v238 src0_sel:WORD_1
	v_cvt_pk_f32_fp8_e32 v[64:65], v239
	v_cvt_pk_f32_fp8_sdwa v[66:67], v239 src0_sel:WORD_1
	v_pk_fma_f32 v[36:37], v[72:73], v[44:45], v[36:37] op_sel_hi:[0,1,1]
	v_pk_fma_f32 v[38:39], v[72:73], v[46:47], v[38:39] op_sel_hi:[0,1,1]
	v_pk_fma_f32 v[32:33], v[72:73], v[64:65], v[32:33] op_sel_hi:[0,1,1]
	v_pk_fma_f32 v[34:35], v[72:73], v[66:67], v[34:35] op_sel_hi:[0,1,1]
	s_nop 1
	v_readlane_b32 s100, v133, 4
	v_readlane_b32 s48, v74, 14
	s_lshl_b32 s100, s100, 11
	s_add_u32 s100, s96, s100
	s_addc_u32 s101, s97, 0
	global_load_dwordx4 v[96:99], v254, s[100:101]
	global_load_dwordx4 v[100:103], v254, s[100:101] offset:1024
	s_waitcnt vmcnt(12)
	v_mov_b32_e32 v72, s48
	v_cvt_pk_f32_fp8_e32 v[44:45], v242
	v_cvt_pk_f32_fp8_sdwa v[46:47], v242 src0_sel:WORD_1
	v_cvt_pk_f32_fp8_e32 v[64:65], v243
	v_cvt_pk_f32_fp8_sdwa v[66:67], v243 src0_sel:WORD_1
	v_pk_fma_f32 v[68:69], v[72:73], v[44:45], v[68:69] op_sel_hi:[0,1,1]
	v_pk_fma_f32 v[70:71], v[72:73], v[46:47], v[70:71] op_sel_hi:[0,1,1]
	v_pk_fma_f32 v[60:61], v[72:73], v[64:65], v[60:61] op_sel_hi:[0,1,1]
	v_pk_fma_f32 v[62:63], v[72:73], v[66:67], v[62:63] op_sel_hi:[0,1,1]
	v_cvt_pk_f32_fp8_e32 v[44:45], v244
	v_cvt_pk_f32_fp8_sdwa v[46:47], v244 src0_sel:WORD_1
	v_cvt_pk_f32_fp8_e32 v[64:65], v245
	v_cvt_pk_f32_fp8_sdwa v[66:67], v245 src0_sel:WORD_1
	v_pk_fma_f32 v[56:57], v[72:73], v[44:45], v[56:57] op_sel_hi:[0,1,1]
	v_pk_fma_f32 v[58:59], v[72:73], v[46:47], v[58:59] op_sel_hi:[0,1,1]
	v_pk_fma_f32 v[52:53], v[72:73], v[64:65], v[52:53] op_sel_hi:[0,1,1]
	v_pk_fma_f32 v[54:55], v[72:73], v[66:67], v[54:55] op_sel_hi:[0,1,1]
	v_cvt_pk_f32_fp8_e32 v[44:45], v246
	v_cvt_pk_f32_fp8_sdwa v[46:47], v246 src0_sel:WORD_1
	v_cvt_pk_f32_fp8_e32 v[64:65], v247
	v_cvt_pk_f32_fp8_sdwa v[66:67], v247 src0_sel:WORD_1
	v_pk_fma_f32 v[48:49], v[72:73], v[44:45], v[48:49] op_sel_hi:[0,1,1]
	v_pk_fma_f32 v[50:51], v[72:73], v[46:47], v[50:51] op_sel_hi:[0,1,1]
	v_pk_fma_f32 v[40:41], v[72:73], v[64:65], v[40:41] op_sel_hi:[0,1,1]
	v_pk_fma_f32 v[42:43], v[72:73], v[66:67], v[42:43] op_sel_hi:[0,1,1]
	v_cvt_pk_f32_fp8_e32 v[44:45], v248
	v_cvt_pk_f32_fp8_sdwa v[46:47], v248 src0_sel:WORD_1
	v_cvt_pk_f32_fp8_e32 v[64:65], v249
	v_cvt_pk_f32_fp8_sdwa v[66:67], v249 src0_sel:WORD_1
	v_pk_fma_f32 v[36:37], v[72:73], v[44:45], v[36:37] op_sel_hi:[0,1,1]
	v_pk_fma_f32 v[38:39], v[72:73], v[46:47], v[38:39] op_sel_hi:[0,1,1]
	v_pk_fma_f32 v[32:33], v[72:73], v[64:65], v[32:33] op_sel_hi:[0,1,1]
	v_pk_fma_f32 v[34:35], v[72:73], v[66:67], v[34:35] op_sel_hi:[0,1,1]
	s_nop 1
	v_readlane_b32 s100, v133, 5
	v_readlane_b32 s48, v74, 15
	s_lshl_b32 s100, s100, 11
	s_add_u32 s100, s96, s100
	s_addc_u32 s101, s97, 0
	global_load_dwordx4 v[104:107], v254, s[100:101]
	global_load_dwordx4 v[108:111], v254, s[100:101] offset:1024
	s_waitcnt vmcnt(12)
	v_mov_b32_e32 v72, s48
	v_cvt_pk_f32_fp8_e32 v[44:45], v250
	v_cvt_pk_f32_fp8_sdwa v[46:47], v250 src0_sel:WORD_1
	v_cvt_pk_f32_fp8_e32 v[64:65], v251
	v_cvt_pk_f32_fp8_sdwa v[66:67], v251 src0_sel:WORD_1
	v_pk_fma_f32 v[68:69], v[72:73], v[44:45], v[68:69] op_sel_hi:[0,1,1]
	v_pk_fma_f32 v[70:71], v[72:73], v[46:47], v[70:71] op_sel_hi:[0,1,1]
	v_pk_fma_f32 v[60:61], v[72:73], v[64:65], v[60:61] op_sel_hi:[0,1,1]
	v_pk_fma_f32 v[62:63], v[72:73], v[66:67], v[62:63] op_sel_hi:[0,1,1]
	v_cvt_pk_f32_fp8_e32 v[44:45], v252
	v_cvt_pk_f32_fp8_sdwa v[46:47], v252 src0_sel:WORD_1
	v_cvt_pk_f32_fp8_e32 v[64:65], v253
	v_cvt_pk_f32_fp8_sdwa v[66:67], v253 src0_sel:WORD_1
	v_pk_fma_f32 v[56:57], v[72:73], v[44:45], v[56:57] op_sel_hi:[0,1,1]
	v_pk_fma_f32 v[58:59], v[72:73], v[46:47], v[58:59] op_sel_hi:[0,1,1]
	v_pk_fma_f32 v[52:53], v[72:73], v[64:65], v[52:53] op_sel_hi:[0,1,1]
	v_pk_fma_f32 v[54:55], v[72:73], v[66:67], v[54:55] op_sel_hi:[0,1,1]
	v_cvt_pk_f32_fp8_e32 v[44:45], v76
	v_cvt_pk_f32_fp8_sdwa v[46:47], v76 src0_sel:WORD_1
	v_cvt_pk_f32_fp8_e32 v[64:65], v77
	v_cvt_pk_f32_fp8_sdwa v[66:67], v77 src0_sel:WORD_1
	v_pk_fma_f32 v[48:49], v[72:73], v[44:45], v[48:49] op_sel_hi:[0,1,1]
	v_pk_fma_f32 v[50:51], v[72:73], v[46:47], v[50:51] op_sel_hi:[0,1,1]
	v_pk_fma_f32 v[40:41], v[72:73], v[64:65], v[40:41] op_sel_hi:[0,1,1]
	v_pk_fma_f32 v[42:43], v[72:73], v[66:67], v[42:43] op_sel_hi:[0,1,1]
	v_cvt_pk_f32_fp8_e32 v[44:45], v78
	v_cvt_pk_f32_fp8_sdwa v[46:47], v78 src0_sel:WORD_1
	v_cvt_pk_f32_fp8_e32 v[64:65], v79
	v_cvt_pk_f32_fp8_sdwa v[66:67], v79 src0_sel:WORD_1
	v_pk_fma_f32 v[36:37], v[72:73], v[44:45], v[36:37] op_sel_hi:[0,1,1]
	v_pk_fma_f32 v[38:39], v[72:73], v[46:47], v[38:39] op_sel_hi:[0,1,1]
	v_pk_fma_f32 v[32:33], v[72:73], v[64:65], v[32:33] op_sel_hi:[0,1,1]
	v_pk_fma_f32 v[34:35], v[72:73], v[66:67], v[34:35] op_sel_hi:[0,1,1]

.LBB0_2004:
.Lgout1_tile:
	s_bfe_u32 s20, s79, 0x30005
	s_and_b32 s21, s79, 31
	s_lshr_b32 s7, s79, 8
	s_lshl_b32 s6, s7, 5
	s_lshr_b32 s7, s20, 3
	s_lshl_b32 s7, s7, 5
	s_add_u32 s6, s6, s7
	s_lshr_b32 s7, s21, 0
	s_add_u32 s6, s6, s7
	s_and_b32 s7, s20, 7
	s_lshl_b32 s7, s7, 0
	s_and_b32 s21, s21, 0
	s_add_u32 s7, s7, s21
	s_lshl_b32 s6, s6, 8
	s_lshl_b32 s7, s7, 8
	s_lshl_b32 s20, s6, 12
	s_add_u32 s20, s20, 0x6224000
	s_add_u32 s8, s92, s20
	s_addc_u32 s9, s93, 0
	s_and_b32 s9, s9, 0xffff
	s_mov_b32 s10, 0x100000
	s_mov_b32 s11, 0x20000
	s_lshl_b32 s20, s7, 12
	s_add_u32 s20, s20, 0x3380000
	s_add_u32 s24, s92, s20
	s_addc_u32 s25, s93, 0
	s_and_b32 s25, s25, 0xffff
	s_sub_u32 s20, 0x800, s7
	s_min_u32 s20, s20, 0x100
	s_lshl_b32 s26, s20, 12
	s_mov_b32 s27, 0x20000
	s_mov_b32 s28, 0x40000
	s_mov_b32 s29, 0x80000
	s_mov_b32 s30, 0xc0000
	v_lshrrev_b32_e32 v128, 3, v190
	v_and_b32_e32 v129, 7, v190
	v_lshlrev_b32_e32 v129, 4, v129
	v_lshl_add_u32 v160, v128, 12, v129
	v_mul_u32_u24_e32 v130, 0x90, v128
	v_add_u32_e32 v170, v130, v129
	v_add_u32_e32 v171, 0x12000, v170
	v_and_b32_e32 v131, 31, v190
	v_bfe_u32 v132, v190, 5, 1
	v_bfe_u32 v133, v190, 6, 2
	v_bfe_u32 v134, v190, 8, 1
	v_lshl_add_u32 v135, v134, 7, v131
	v_mul_u32_u24_e32 v135, 0x90, v135
	v_lshl_add_u32 v175, v132, 4, v135
	v_lshl_add_u32 v136, v133, 6, v131
	v_mul_u32_u24_e32 v136, 0x90, v136
	v_lshl_add_u32 v136, v132, 4, v136
	v_add_u32_e32 v254, 0x12000, v136
	buffer_load_dwordx4 v[216:219], v160, s[8:11], 0 offen
	buffer_load_dwordx4 v[220:223], v160, s[8:11], s28 offen
	buffer_load_dwordx4 v[224:227], v160, s[8:11], s29 offen
	buffer_load_dwordx4 v[228:231], v160, s[8:11], s30 offen
	buffer_load_dwordx4 v[232:235], v160, s[24:27], 0 offen
	buffer_load_dwordx4 v[236:239], v160, s[24:27], s28 offen
	buffer_load_dwordx4 v[152:155], v160, s[24:27], s29 offen
	buffer_load_dwordx4 v[156:159], v160, s[24:27], s30 offen
	v_add_u32_e32 v160, 0x80, v160
	buffer_load_dwordx4 v[162:165], v160, s[8:11], 0 offen
	buffer_load_dwordx4 v[166:169], v160, s[8:11], s28 offen
	buffer_load_dwordx4 v[176:179], v160, s[8:11], s29 offen
	buffer_load_dwordx4 v[180:183], v160, s[8:11], s30 offen
	buffer_load_dwordx4 v[184:187], v160, s[24:27], 0 offen
	buffer_load_dwordx4 v[242:245], v160, s[24:27], s28 offen
	buffer_load_dwordx4 v[246:249], v160, s[24:27], s29 offen
	buffer_load_dwordx4 v[250:253], v160, s[24:27], s30 offen
	v_add_u32_e32 v160, 0x80, v160
	s_waitcnt vmcnt(8)
	ds_write_b128 v170, v[216:219] offset:0
	ds_write_b128 v170, v[220:223] offset:9216
	ds_write_b128 v170, v[224:227] offset:18432
	ds_write_b128 v170, v[228:231] offset:27648
	ds_write_b128 v171, v[232:235] offset:0
	ds_write_b128 v171, v[236:239] offset:9216
	ds_write_b128 v171, v[152:155] offset:18432
	ds_write_b128 v171, v[156:159] offset:27648
	buffer_load_dwordx4 v[216:219], v160, s[8:11], 0 offen
	buffer_load_dwordx4 v[220:223], v160, s[8:11], s28 offen
	buffer_load_dwordx4 v[224:227], v160, s[8:11], s29 offen
	buffer_load_dwordx4 v[228:231], v160, s[8:11], s30 offen
	buffer_load_dwordx4 v[232:235], v160, s[24:27], 0 offen
	buffer_load_dwordx4 v[236:239], v160, s[24:27], s28 offen
	buffer_load_dwordx4 v[152:155], v160, s[24:27], s29 offen
	buffer_load_dwordx4 v[156:159], v160, s[24:27], s30 offen
	v_add_u32_e32 v160, 0x80, v160
	s_waitcnt lgkmcnt(0)
	s_barrier
	ds_read_b128 v[144:147], v254 offset:0
	ds_read_b128 v[148:151], v254 offset:4608
	ds_read_b128 v[128:131], v175 offset:0
	ds_read_b128 v[132:135], v175 offset:4608
	ds_read_b128 v[136:139], v175 offset:9216
	ds_read_b128 v[140:143], v175 offset:13824
	s_waitcnt vmcnt(8)
	ds_write_b128 v170, v[162:165] offset:36864
	ds_write_b128 v170, v[166:169] offset:46080
	ds_write_b128 v170, v[176:179] offset:55296
	ds_write_b128 v170, v[180:183] offset:64512
	ds_write_b128 v171, v[184:187] offset:36864
	ds_write_b128 v171, v[242:245] offset:46080
	ds_write_b128 v171, v[246:249] offset:55296
	ds_write_b128 v171, v[250:253] offset:64512
	s_waitcnt lgkmcnt(8)
	v_mfma_f32_32x32x16_bf16 v[112:127], v[128:131], v[144:147], 0
	ds_read_b128 v[208:211], v254 offset:32
	v_mfma_f32_32x32x16_bf16 v[96:111], v[128:131], v[148:151], 0
	ds_read_b128 v[212:215], v254 offset:4640
	ds_read_b128 v[192:195], v175 offset:32
	v_mfma_f32_32x32x16_bf16 v[80:95], v[132:135], v[144:147], 0
	ds_read_b128 v[196:199], v175 offset:4640
	ds_read_b128 v[200:203], v175 offset:9248
	v_mfma_f32_32x32x16_bf16 v[64:79], v[132:135], v[148:151], 0
	ds_read_b128 v[204:207], v175 offset:13856
	buffer_load_dwordx4 v[162:165], v160, s[8:11], 0 offen
	v_mfma_f32_32x32x16_bf16 v[48:63], v[136:139], v[144:147], 0
	buffer_load_dwordx4 v[166:169], v160, s[8:11], s28 offen
	buffer_load_dwordx4 v[176:179], v160, s[8:11], s29 offen
	v_mfma_f32_32x32x16_bf16 v[32:47], v[136:139], v[148:151], 0
	buffer_load_dwordx4 v[180:183], v160, s[8:11], s30 offen
	buffer_load_dwordx4 v[184:187], v160, s[24:27], 0 offen
	v_mfma_f32_32x32x16_bf16 v[16:31], v[140:143], v[144:147], 0
	buffer_load_dwordx4 v[242:245], v160, s[24:27], s28 offen
	buffer_load_dwordx4 v[246:249], v160, s[24:27], s29 offen
	v_mfma_f32_32x32x16_bf16 v[0:15], v[140:143], v[148:151], 0
	buffer_load_dwordx4 v[250:253], v160, s[24:27], s30 offen
	v_add_u32_e32 v160, 0x80, v160
	s_waitcnt lgkmcnt(0)
	v_mfma_f32_32x32x16_bf16 v[112:127], v[192:195], v[208:211], v[112:127]
	v_mfma_f32_32x32x16_bf16 v[96:111], v[192:195], v[212:215], v[96:111]
	ds_read_b128 v[144:147], v254 offset:64
	v_mfma_f32_32x32x16_bf16 v[80:95], v[196:199], v[208:211], v[80:95]
	ds_read_b128 v[148:151], v254 offset:4672
	v_mfma_f32_32x32x16_bf16 v[64:79], v[196:199], v[212:215], v[64:79]
	ds_read_b128 v[128:131], v175 offset:64
	v_mfma_f32_32x32x16_bf16 v[48:63], v[200:203], v[208:211], v[48:63]
	v_mfma_f32_32x32x16_bf16 v[32:47], v[200:203], v[212:215], v[32:47]
	ds_read_b128 v[132:135], v175 offset:4672
	v_mfma_f32_32x32x16_bf16 v[16:31], v[204:207], v[208:211], v[16:31]
	ds_read_b128 v[136:139], v175 offset:9280
	v_mfma_f32_32x32x16_bf16 v[0:15], v[204:207], v[212:215], v[0:15]
	ds_read_b128 v[140:143], v175 offset:13888
	s_waitcnt lgkmcnt(0)
	v_mfma_f32_32x32x16_bf16 v[112:127], v[128:131], v[144:147], v[112:127]
	v_mfma_f32_32x32x16_bf16 v[96:111], v[128:131], v[148:151], v[96:111]
	ds_read_b128 v[208:211], v254 offset:96
	v_mfma_f32_32x32x16_bf16 v[80:95], v[132:135], v[144:147], v[80:95]
	ds_read_b128 v[212:215], v254 offset:4704
	v_mfma_f32_32x32x16_bf16 v[64:79], v[132:135], v[148:151], v[64:79]
	ds_read_b128 v[192:195], v175 offset:96
	v_mfma_f32_32x32x16_bf16 v[48:63], v[136:139], v[144:147], v[48:63]
	v_mfma_f32_32x32x16_bf16 v[32:47], v[136:139], v[148:151], v[32:47]
	ds_read_b128 v[196:199], v175 offset:4704
	v_mfma_f32_32x32x16_bf16 v[16:31], v[140:143], v[144:147], v[16:31]
	ds_read_b128 v[200:203], v175 offset:9312
	v_mfma_f32_32x32x16_bf16 v[0:15], v[140:143], v[148:151], v[0:15]
	ds_read_b128 v[204:207], v175 offset:13920
	s_waitcnt lgkmcnt(0)
	s_barrier
	ds_read_b128 v[144:147], v254 offset:36864
	ds_read_b128 v[148:151], v254 offset:41472
	ds_read_b128 v[128:131], v175 offset:36864
	ds_read_b128 v[132:135], v175 offset:41472
	ds_read_b128 v[136:139], v175 offset:46080
	ds_read_b128 v[140:143], v175 offset:50688
	v_mfma_f32_32x32x16_bf16 v[112:127], v[192:195], v[208:211], v[112:127]
	s_waitcnt vmcnt(8)
	v_mfma_f32_32x32x16_bf16 v[96:111], v[192:195], v[212:215], v[96:111]
	ds_write_b128 v170, v[216:219] offset:0
	v_mfma_f32_32x32x16_bf16 v[80:95], v[196:199], v[208:211], v[80:95]
	ds_write_b128 v170, v[220:223] offset:9216
	v_mfma_f32_32x32x16_bf16 v[64:79], v[196:199], v[212:215], v[64:79]
	ds_write_b128 v170, v[224:227] offset:18432
	v_mfma_f32_32x32x16_bf16 v[48:63], v[200:203], v[208:211], v[48:63]
	ds_write_b128 v170, v[228:231] offset:27648
	v_mfma_f32_32x32x16_bf16 v[32:47], v[200:203], v[212:215], v[32:47]
	ds_write_b128 v171, v[232:235] offset:0
	v_mfma_f32_32x32x16_bf16 v[16:31], v[204:207], v[208:211], v[16:31]
	ds_write_b128 v171, v[236:239] offset:9216
	v_mfma_f32_32x32x16_bf16 v[0:15], v[204:207], v[212:215], v[0:15]
	ds_write_b128 v171, v[152:155] offset:18432
	ds_write_b128 v171, v[156:159] offset:27648
	s_waitcnt lgkmcnt(8)
	v_mfma_f32_32x32x16_bf16 v[112:127], v[128:131], v[144:147], v[112:127]
	ds_read_b128 v[208:211], v254 offset:36896
	v_mfma_f32_32x32x16_bf16 v[96:111], v[128:131], v[148:151], v[96:111]
	ds_read_b128 v[212:215], v254 offset:41504
	ds_read_b128 v[192:195], v175 offset:36896
	v_mfma_f32_32x32x16_bf16 v[80:95], v[132:135], v[144:147], v[80:95]
	ds_read_b128 v[196:199], v175 offset:41504
	ds_read_b128 v[200:203], v175 offset:46112
	v_mfma_f32_32x32x16_bf16 v[64:79], v[132:135], v[148:151], v[64:79]
	ds_read_b128 v[204:207], v175 offset:50720
	buffer_load_dwordx4 v[216:219], v160, s[8:11], 0 offen
	v_mfma_f32_32x32x16_bf16 v[48:63], v[136:139], v[144:147], v[48:63]
	buffer_load_dwordx4 v[220:223], v160, s[8:11], s28 offen
	buffer_load_dwordx4 v[224:227], v160, s[8:11], s29 offen
	v_mfma_f32_32x32x16_bf16 v[32:47], v[136:139], v[148:151], v[32:47]
	buffer_load_dwordx4 v[228:231], v160, s[8:11], s30 offen
	buffer_load_dwordx4 v[232:235], v160, s[24:27], 0 offen
	v_mfma_f32_32x32x16_bf16 v[16:31], v[140:143], v[144:147], v[16:31]
	buffer_load_dwordx4 v[236:239], v160, s[24:27], s28 offen
	buffer_load_dwordx4 v[152:155], v160, s[24:27], s29 offen
	v_mfma_f32_32x32x16_bf16 v[0:15], v[140:143], v[148:151], v[0:15]
	buffer_load_dwordx4 v[156:159], v160, s[24:27], s30 offen
	v_add_u32_e32 v160, 0x80, v160
	s_waitcnt lgkmcnt(0)
	v_mfma_f32_32x32x16_bf16 v[112:127], v[192:195], v[208:211], v[112:127]
	v_mfma_f32_32x32x16_bf16 v[96:111], v[192:195], v[212:215], v[96:111]
	ds_read_b128 v[144:147], v254 offset:36928
	v_mfma_f32_32x32x16_bf16 v[80:95], v[196:199], v[208:211], v[80:95]
	ds_read_b128 v[148:151], v254 offset:41536
	v_mfma_f32_32x32x16_bf16 v[64:79], v[196:199], v[212:215], v[64:79]
	ds_read_b128 v[128:131], v175 offset:36928
	v_mfma_f32_32x32x16_bf16 v[48:63], v[200:203], v[208:211], v[48:63]
	v_mfma_f32_32x32x16_bf16 v[32:47], v[200:203], v[212:215], v[32:47]
	ds_read_b128 v[132:135], v175 offset:41536
	v_mfma_f32_32x32x16_bf16 v[16:31], v[204:207], v[208:211], v[16:31]
	ds_read_b128 v[136:139], v175 offset:46144
	v_mfma_f32_32x32x16_bf16 v[0:15], v[204:207], v[212:215], v[0:15]
	ds_read_b128 v[140:143], v175 offset:50752
	s_waitcnt lgkmcnt(0)
	v_mfma_f32_32x32x16_bf16 v[112:127], v[128:131], v[144:147], v[112:127]
	v_mfma_f32_32x32x16_bf16 v[96:111], v[128:131], v[148:151], v[96:111]
	ds_read_b128 v[208:211], v254 offset:36960
	v_mfma_f32_32x32x16_bf16 v[80:95], v[132:135], v[144:147], v[80:95]
	ds_read_b128 v[212:215], v254 offset:41568
	v_mfma_f32_32x32x16_bf16 v[64:79], v[132:135], v[148:151], v[64:79]
	ds_read_b128 v[192:195], v175 offset:36960
	v_mfma_f32_32x32x16_bf16 v[48:63], v[136:139], v[144:147], v[48:63]
	v_mfma_f32_32x32x16_bf16 v[32:47], v[136:139], v[148:151], v[32:47]
	ds_read_b128 v[196:199], v175 offset:41568
	v_mfma_f32_32x32x16_bf16 v[16:31], v[140:143], v[144:147], v[16:31]
	ds_read_b128 v[200:203], v175 offset:46176
	v_mfma_f32_32x32x16_bf16 v[0:15], v[140:143], v[148:151], v[0:15]
	ds_read_b128 v[204:207], v175 offset:50784
	s_waitcnt lgkmcnt(0)
	s_barrier
	s_movk_i32 s31, 13

.LBB0_2779:
	s_or_b64 exec, exec, s[48:49]
	s_waitcnt lgkmcnt(1)
	v_max_u32_dpp v36, v35, v35 quad_perm:[1,0,3,2] row_mask:0xf bank_mask:0xf bound_ctrl:1
	v_bitop3_b32 v32, v32, s54, v32 bitop3:0xc
	v_ashrrev_i32_e32 v123, 31, v122
	v_max_u32_dpp v36, v36, v36 quad_perm:[2,3,0,1] row_mask:0xf bank_mask:0xf bound_ctrl:1
	s_mov_b32 s70, 0
	s_mov_b32 s71, 5
	v_max_u32_dpp v36, v36, v36 row_half_mirror row_mask:0xf bank_mask:0xf bound_ctrl:1
	v_mov_b32_e32 v58, v34
	v_mov_b32_e32 v59, v34
	v_max_u32_dpp v36, v36, v36 row_mirror row_mask:0xf bank_mask:0xf bound_ctrl:1
	v_mov_b32_e32 v57, v34
	v_readlane_b32 s48, v36, 32
	v_readlane_b32 s49, v36, 48
	v_readlane_b32 s40, v36, 16
	s_max_u32 s48, s48, s49
	v_readlane_b32 s3, v36, 0
	v_mov_b32_e32 v36, s40
	s_waitcnt lgkmcnt(0)
	v_mov_b32_e32 v37, s48
	v_max3_u32 v36, s3, v36, v37
	v_cmp_ne_u32_e32 vcc, v35, v36
	v_cndmask_b32_e64 v36, 0, v36, s[6:7]
	v_mov_b32_e32 v62, v34
	v_cndmask_b32_e32 v35, 0, v35, vcc
	v_mov_b32_e32 v63, v34
	v_mov_b32_e32 v60, v34
	v_max_u32_dpp v37, v35, v35 quad_perm:[1,0,3,2] row_mask:0xf bank_mask:0xf bound_ctrl:1
	v_mov_b32_e32 v61, v34
	s_nop 0
	v_max_u32_dpp v37, v37, v37 quad_perm:[2,3,0,1] row_mask:0xf bank_mask:0xf bound_ctrl:1
	s_nop 1
	v_max_u32_dpp v37, v37, v37 row_half_mirror row_mask:0xf bank_mask:0xf bound_ctrl:1
	s_nop 1
	v_max_u32_dpp v37, v37, v37 row_mirror row_mask:0xf bank_mask:0xf bound_ctrl:1
	s_nop 0
	v_readlane_b32 s48, v37, 32
	v_readlane_b32 s49, v37, 48
	v_readlane_b32 s40, v37, 16
	s_max_u32 s48, s48, s49
	v_readlane_b32 s3, v37, 0
	v_mov_b32_e32 v37, s40
	v_mov_b32_e32 v38, s48
	v_max3_u32 v37, s3, v37, v38
	v_cmp_ne_u32_e32 vcc, v35, v37
	v_cndmask_b32_e64 v36, v36, v37, s[8:9]
	s_nop 0
	v_cndmask_b32_e32 v35, 0, v35, vcc
	s_nop 1
	v_max_u32_dpp v37, v35, v35 quad_perm:[1,0,3,2] row_mask:0xf bank_mask:0xf bound_ctrl:1
	s_nop 1
	v_max_u32_dpp v37, v37, v37 quad_perm:[2,3,0,1] row_mask:0xf bank_mask:0xf bound_ctrl:1
	s_nop 1
	v_max_u32_dpp v37, v37, v37 row_half_mirror row_mask:0xf bank_mask:0xf bound_ctrl:1
	s_nop 1
	v_max_u32_dpp v37, v37, v37 row_mirror row_mask:0xf bank_mask:0xf bound_ctrl:1
	s_nop 0
	v_readlane_b32 s48, v37, 32
	v_readlane_b32 s49, v37, 48
	v_readlane_b32 s40, v37, 16
	s_max_u32 s48, s48, s49
	v_readlane_b32 s3, v37, 0
	v_mov_b32_e32 v37, s40
	v_mov_b32_e32 v38, s48
	v_max3_u32 v37, s3, v37, v38
	v_cmp_ne_u32_e32 vcc, v35, v37
	v_cndmask_b32_e64 v36, v36, v37, s[10:11]
	s_nop 0
	v_cndmask_b32_e32 v35, 0, v35, vcc
	s_nop 1
	v_max_u32_dpp v37, v35, v35 quad_perm:[1,0,3,2] row_mask:0xf bank_mask:0xf bound_ctrl:1
	s_nop 1
	v_max_u32_dpp v37, v37, v37 quad_perm:[2,3,0,1] row_mask:0xf bank_mask:0xf bound_ctrl:1
	s_nop 1
	v_max_u32_dpp v37, v37, v37 row_half_mirror row_mask:0xf bank_mask:0xf bound_ctrl:1
	s_nop 1
	v_max_u32_dpp v37, v37, v37 row_mirror row_mask:0xf bank_mask:0xf bound_ctrl:1
	s_nop 0
	v_readlane_b32 s48, v37, 32
	v_readlane_b32 s49, v37, 48
	v_readlane_b32 s40, v37, 16
	s_max_u32 s48, s48, s49
	v_readlane_b32 s3, v37, 0
	v_mov_b32_e32 v37, s40
	v_mov_b32_e32 v38, s48
	v_max3_u32 v37, s3, v37, v38
	v_cmp_ne_u32_e32 vcc, v35, v37
	v_cndmask_b32_e64 v36, v36, v37, s[12:13]
	s_nop 0
	v_cndmask_b32_e32 v35, 0, v35, vcc
	s_nop 1
	v_max_u32_dpp v37, v35, v35 quad_perm:[1,0,3,2] row_mask:0xf bank_mask:0xf bound_ctrl:1
	s_nop 1
	v_max_u32_dpp v37, v37, v37 quad_perm:[2,3,0,1] row_mask:0xf bank_mask:0xf bound_ctrl:1
	s_nop 1
	v_max_u32_dpp v37, v37, v37 row_half_mirror row_mask:0xf bank_mask:0xf bound_ctrl:1
	s_nop 1
	v_max_u32_dpp v37, v37, v37 row_mirror row_mask:0xf bank_mask:0xf bound_ctrl:1
	s_nop 0
	v_readlane_b32 s48, v37, 32
	v_readlane_b32 s49, v37, 48
	v_readlane_b32 s40, v37, 16
	s_max_u32 s48, s48, s49
	v_readlane_b32 s3, v37, 0
	v_mov_b32_e32 v37, s40
	v_mov_b32_e32 v38, s48
	v_max3_u32 v37, s3, v37, v38
	v_cmp_ne_u32_e32 vcc, v35, v37
	v_cndmask_b32_e64 v36, v36, v37, s[14:15]
	s_nop 0
	v_cndmask_b32_e32 v35, 0, v35, vcc
	s_nop 1
	v_max_u32_dpp v37, v35, v35 quad_perm:[1,0,3,2] row_mask:0xf bank_mask:0xf bound_ctrl:1
	s_nop 1
	v_max_u32_dpp v37, v37, v37 quad_perm:[2,3,0,1] row_mask:0xf bank_mask:0xf bound_ctrl:1
	s_nop 1
	v_max_u32_dpp v37, v37, v37 row_half_mirror row_mask:0xf bank_mask:0xf bound_ctrl:1
	s_nop 1
	v_max_u32_dpp v37, v37, v37 row_mirror row_mask:0xf bank_mask:0xf bound_ctrl:1
	s_nop 0
	v_readlane_b32 s48, v37, 32
	v_readlane_b32 s49, v37, 48
	v_readlane_b32 s40, v37, 16
	s_max_u32 s48, s48, s49
	v_readlane_b32 s3, v37, 0
	v_mov_b32_e32 v37, s40
	v_mov_b32_e32 v38, s48
	v_max3_u32 v37, s3, v37, v38
	v_cmp_ne_u32_e32 vcc, v35, v37
	v_cndmask_b32_e64 v36, v36, v37, s[16:17]
	s_nop 0
	v_cndmask_b32_e32 v35, 0, v35, vcc
	s_nop 1
	v_max_u32_dpp v37, v35, v35 quad_perm:[1,0,3,2] row_mask:0xf bank_mask:0xf bound_ctrl:1
	s_nop 1
	v_max_u32_dpp v37, v37, v37 quad_perm:[2,3,0,1] row_mask:0xf bank_mask:0xf bound_ctrl:1
	s_nop 1
	v_max_u32_dpp v37, v37, v37 row_half_mirror row_mask:0xf bank_mask:0xf bound_ctrl:1
	s_nop 1
	v_max_u32_dpp v37, v37, v37 row_mirror row_mask:0xf bank_mask:0xf bound_ctrl:1
	s_nop 0
	v_readlane_b32 s48, v37, 32
	v_readlane_b32 s49, v37, 48
	v_readlane_b32 s40, v37, 16
	s_max_u32 s48, s48, s49
	v_readlane_b32 s3, v37, 0
	v_mov_b32_e32 v37, s40
	v_mov_b32_e32 v38, s48
	v_max3_u32 v37, s3, v37, v38
	v_cmp_ne_u32_e32 vcc, v35, v37
	v_cndmask_b32_e64 v36, v36, v37, s[18:19]
	s_nop 0
	v_cndmask_b32_e32 v35, 0, v35, vcc
	s_nop 1
	v_max_u32_dpp v37, v35, v35 quad_perm:[1,0,3,2] row_mask:0xf bank_mask:0xf bound_ctrl:1
	s_nop 1
	v_max_u32_dpp v37, v37, v37 quad_perm:[2,3,0,1] row_mask:0xf bank_mask:0xf bound_ctrl:1
	s_nop 1
	v_max_u32_dpp v37, v37, v37 row_half_mirror row_mask:0xf bank_mask:0xf bound_ctrl:1
	s_nop 1
	v_max_u32_dpp v37, v37, v37 row_mirror row_mask:0xf bank_mask:0xf bound_ctrl:1
	s_nop 0
	v_readlane_b32 s48, v37, 32
	v_readlane_b32 s49, v37, 48
	v_readlane_b32 s40, v37, 16
	s_max_u32 s48, s48, s49
	v_readlane_b32 s3, v37, 0
	v_mov_b32_e32 v37, s40
	v_mov_b32_e32 v38, s48
	v_max3_u32 v37, s3, v37, v38
	v_cmp_ne_u32_e32 vcc, v35, v37
	v_cndmask_b32_e64 v36, v36, v37, s[20:21]
	s_nop 0
	v_cndmask_b32_e32 v35, 0, v35, vcc
	s_nop 1
	v_max_u32_dpp v37, v35, v35 quad_perm:[1,0,3,2] row_mask:0xf bank_mask:0xf bound_ctrl:1
	s_nop 1
	v_max_u32_dpp v37, v37, v37 quad_perm:[2,3,0,1] row_mask:0xf bank_mask:0xf bound_ctrl:1
	s_nop 1
	v_max_u32_dpp v37, v37, v37 row_half_mirror row_mask:0xf bank_mask:0xf bound_ctrl:1
	s_nop 1
	v_max_u32_dpp v37, v37, v37 row_mirror row_mask:0xf bank_mask:0xf bound_ctrl:1
	s_nop 0
	v_readlane_b32 s48, v37, 32
	v_readlane_b32 s49, v37, 48
	v_readlane_b32 s40, v37, 16
	s_max_u32 s48, s48, s49
	v_readlane_b32 s3, v37, 0
	v_mov_b32_e32 v37, s40
	v_mov_b32_e32 v38, s48
	v_max3_u32 v37, s3, v37, v38
	v_cmp_ne_u32_e32 vcc, v35, v37
	v_cndmask_b32_e64 v36, v36, v37, s[22:23]
	s_nop 0
	v_cndmask_b32_e32 v35, 0, v35, vcc
	s_nop 1
	v_max_u32_dpp v37, v35, v35 quad_perm:[1,0,3,2] row_mask:0xf bank_mask:0xf bound_ctrl:1
	s_nop 1
	v_max_u32_dpp v37, v37, v37 quad_perm:[2,3,0,1] row_mask:0xf bank_mask:0xf bound_ctrl:1
	s_nop 1
	v_max_u32_dpp v37, v37, v37 row_half_mirror row_mask:0xf bank_mask:0xf bound_ctrl:1
	s_nop 1
	v_max_u32_dpp v37, v37, v37 row_mirror row_mask:0xf bank_mask:0xf bound_ctrl:1
	s_nop 0
	v_readlane_b32 s48, v37, 32
	v_readlane_b32 s49, v37, 48
	v_readlane_b32 s40, v37, 16
	s_max_u32 s48, s48, s49
	v_readlane_b32 s3, v37, 0
	v_mov_b32_e32 v37, s40
	v_mov_b32_e32 v38, s48
	v_max3_u32 v37, s3, v37, v38
	v_cmp_ne_u32_e32 vcc, v35, v37
	v_cndmask_b32_e64 v36, v36, v37, s[24:25]
	s_nop 0
	v_cndmask_b32_e32 v35, 0, v35, vcc
	s_nop 1
	v_max_u32_dpp v37, v35, v35 quad_perm:[1,0,3,2] row_mask:0xf bank_mask:0xf bound_ctrl:1
	s_nop 1
	v_max_u32_dpp v37, v37, v37 quad_perm:[2,3,0,1] row_mask:0xf bank_mask:0xf bound_ctrl:1
	s_nop 1
	v_max_u32_dpp v37, v37, v37 row_half_mirror row_mask:0xf bank_mask:0xf bound_ctrl:1
	s_nop 1
	v_max_u32_dpp v37, v37, v37 row_mirror row_mask:0xf bank_mask:0xf bound_ctrl:1
	s_nop 0
	v_readlane_b32 s48, v37, 32
	v_readlane_b32 s49, v37, 48
	v_readlane_b32 s40, v37, 16
	s_max_u32 s48, s48, s49
	v_readlane_b32 s3, v37, 0
	v_mov_b32_e32 v37, s40
	v_mov_b32_e32 v38, s48
	v_max3_u32 v37, s3, v37, v38
	v_cmp_ne_u32_e32 vcc, v35, v37
	v_cndmask_b32_e64 v36, v36, v37, s[26:27]
	s_nop 0
	v_cndmask_b32_e32 v35, 0, v35, vcc
	s_nop 1
	v_max_u32_dpp v37, v35, v35 quad_perm:[1,0,3,2] row_mask:0xf bank_mask:0xf bound_ctrl:1
	s_nop 1
	v_max_u32_dpp v37, v37, v37 quad_perm:[2,3,0,1] row_mask:0xf bank_mask:0xf bound_ctrl:1
	s_nop 1
	v_max_u32_dpp v37, v37, v37 row_half_mirror row_mask:0xf bank_mask:0xf bound_ctrl:1
	s_nop 1
	v_max_u32_dpp v37, v37, v37 row_mirror row_mask:0xf bank_mask:0xf bound_ctrl:1
	s_nop 0
	v_readlane_b32 s48, v37, 32
	v_readlane_b32 s49, v37, 48
	v_readlane_b32 s40, v37, 16
	s_max_u32 s48, s48, s49
	v_readlane_b32 s3, v37, 0
	v_mov_b32_e32 v37, s40
	v_mov_b32_e32 v38, s48
	v_max3_u32 v37, s3, v37, v38
	v_cmp_ne_u32_e32 vcc, v35, v37
	v_cndmask_b32_e64 v36, v36, v37, s[28:29]
	s_nop 0
	v_cndmask_b32_e32 v35, 0, v35, vcc
	s_nop 1
	v_max_u32_dpp v37, v35, v35 quad_perm:[1,0,3,2] row_mask:0xf bank_mask:0xf bound_ctrl:1
	s_nop 1
	v_max_u32_dpp v37, v37, v37 quad_perm:[2,3,0,1] row_mask:0xf bank_mask:0xf bound_ctrl:1
	s_nop 1
	v_max_u32_dpp v37, v37, v37 row_half_mirror row_mask:0xf bank_mask:0xf bound_ctrl:1
	s_nop 1
	v_max_u32_dpp v37, v37, v37 row_mirror row_mask:0xf bank_mask:0xf bound_ctrl:1
	s_nop 0
	v_readlane_b32 s48, v37, 32
	v_readlane_b32 s49, v37, 48
	v_readlane_b32 s40, v37, 16
	s_max_u32 s48, s48, s49
	v_readlane_b32 s3, v37, 0
	v_mov_b32_e32 v37, s40
	v_mov_b32_e32 v38, s48
	v_max3_u32 v37, s3, v37, v38
	v_cmp_ne_u32_e32 vcc, v35, v37
	v_cndmask_b32_e64 v44, v36, v37, s[30:31]
	s_ashr_i32 s3, s2, 31
	v_cndmask_b32_e32 v35, 0, v35, vcc
	s_lshl_b64 s[48:49], s[2:3], 12
	v_lshl_add_u64 v[48:49], v[112:113], 0, s[48:49]
	v_max_u32_dpp v36, v35, v35 quad_perm:[1,0,3,2] row_mask:0xf bank_mask:0xf bound_ctrl:1
	s_nop 1
	v_max_u32_dpp v45, v36, v36 quad_perm:[2,3,0,1] row_mask:0xf bank_mask:0xf bound_ctrl:1
	global_load_dwordx4 v[36:39], v[48:49], off offset:16
	global_load_dwordx4 v[40:43], v[48:49], off
	v_max_u32_dpp v45, v45, v45 row_half_mirror row_mask:0xf bank_mask:0xf bound_ctrl:1
	s_waitcnt vmcnt(1)
	v_lshlrev_b32_e32 v132, 16, v36
	v_max_u32_dpp v45, v45, v45 row_mirror row_mask:0xf bank_mask:0xf bound_ctrl:1
	s_waitcnt vmcnt(0)
	v_lshlrev_b32_e32 v124, 16, v40
	v_readlane_b32 s49, v45, 32
	v_readlane_b32 s50, v45, 48
	v_readlane_b32 s48, v45, 16
	s_max_u32 s49, s49, s50
	v_readlane_b32 s40, v45, 0
	v_mov_b32_e32 v45, s48
	v_mov_b32_e32 v46, s49
	v_max3_u32 v45, s40, v45, v46
	v_cmp_ne_u32_e32 vcc, v35, v45
	v_cndmask_b32_e64 v52, v44, v45, s[34:35]
	global_load_dwordx4 v[44:47], v[48:49], off offset:2064
	s_nop 0
	global_load_dwordx4 v[48:51], v[48:49], off offset:2048
	v_cndmask_b32_e32 v35, 0, v35, vcc
	v_and_b32_e32 v125, 0xffff0000, v40
	v_lshlrev_b32_e32 v126, 16, v41
	v_max_u32_dpp v53, v35, v35 quad_perm:[1,0,3,2] row_mask:0xf bank_mask:0xf bound_ctrl:1
	v_and_b32_e32 v127, 0xffff0000, v41
	v_lshlrev_b32_e32 v128, 16, v42
	v_max_u32_dpp v53, v53, v53 quad_perm:[2,3,0,1] row_mask:0xf bank_mask:0xf bound_ctrl:1
	v_and_b32_e32 v129, 0xffff0000, v42
	v_lshlrev_b32_e32 v130, 16, v43
	v_max_u32_dpp v53, v53, v53 row_half_mirror row_mask:0xf bank_mask:0xf bound_ctrl:1
	v_and_b32_e32 v131, 0xffff0000, v43
	v_and_b32_e32 v133, 0xffff0000, v36
	v_max_u32_dpp v53, v53, v53 row_mirror row_mask:0xf bank_mask:0xf bound_ctrl:1
	v_lshlrev_b32_e32 v134, 16, v37
	v_readlane_b32 s49, v53, 32
	v_readlane_b32 s50, v53, 48
	v_readlane_b32 s48, v53, 16
	s_max_u32 s49, s49, s50
	v_readlane_b32 s40, v53, 0
	v_mov_b32_e32 v53, s48
	v_mov_b32_e32 v54, s49
	v_max3_u32 v53, s40, v53, v54
	v_cmp_ne_u32_e32 vcc, v35, v53
	v_cndmask_b32_e64 v52, v52, v53, s[36:37]
	v_bitop3_b32 v54, v33, s54, v33 bitop3:0xc
	v_cndmask_b32_e32 v35, 0, v35, vcc
	v_and_b32_e32 v135, 0xffff0000, v37
	v_lshlrev_b32_e32 v136, 16, v38
	v_max_u32_dpp v35, v35, v35 quad_perm:[1,0,3,2] row_mask:0xf bank_mask:0xf bound_ctrl:1
	v_and_b32_e32 v137, 0xffff0000, v38
	v_lshlrev_b32_e32 v138, 16, v39
	v_max_u32_dpp v35, v35, v35 quad_perm:[2,3,0,1] row_mask:0xf bank_mask:0xf bound_ctrl:1
	v_and_b32_e32 v139, 0xffff0000, v39
	v_mov_b32_e32 v38, v34
	v_max_u32_dpp v35, v35, v35 row_half_mirror row_mask:0xf bank_mask:0xf bound_ctrl:1
	v_mov_b32_e32 v39, v34
	v_mov_b32_e32 v36, v34
	v_max_u32_dpp v35, v35, v35 row_mirror row_mask:0xf bank_mask:0xf bound_ctrl:1
	v_mov_b32_e32 v37, v34
	v_readlane_b32 s49, v35, 32
	v_readlane_b32 s50, v35, 48
	v_readlane_b32 s48, v35, 16
	s_max_u32 s49, s49, s50
	v_readlane_b32 s40, v35, 0
	v_mov_b32_e32 v35, s48
	v_mov_b32_e32 v53, s49
	v_max3_u32 v35, s40, v35, v53
	v_cndmask_b32_e64 v35, v52, v35, s[38:39]
	v_and_or_b32 v33, v35, 63, v162
	v_lshlrev_b32_e32 v33, 2, v33
	v_xor_b32_e32 v33, 0xfc, v33
	v_cmp_lt_i32_e32 vcc, -1, v35
	ds_bpermute_b32 v52, v33, v161
	ds_bpermute_b32 v33, v33, v157
	v_cndmask_b32_e64 v53, v159, -1, vcc
	v_bitop3_b32 v35, v53, v35, s33 bitop3:0x78
	ds_bpermute_b32 v53, v166, v35
	s_waitcnt lgkmcnt(2)
	v_and_or_b32 v52, v52, 63, v162
	v_lshlrev_b32_e32 v52, 2, v52
	ds_bpermute_b32 v55, v52, v32
	s_waitcnt lgkmcnt(2)
	v_and_or_b32 v56, v33, 63, v162
	s_waitcnt lgkmcnt(1)
	v_sub_f32_e32 v32, v35, v53
	v_mul_f32_e32 v32, 0x3fb8aa3b, v32
	v_exp_f32_e32 v35, v32
	v_lshlrev_b64 v[32:33], 2, v[122:123]
	v_lshl_add_u64 v[52:53], s[42:43], 0, v[32:33]
	v_lshl_add_u64 v[32:33], s[44:45], 0, v[32:33]
	global_load_dword v175, v[52:53], off
	global_load_dword v176, v[32:33], off
	v_lshlrev_b32_e32 v32, 2, v56
	ds_bpermute_b32 v32, v32, v54
	v_cndmask_b32_e64 v123, 0, v35, s[4:5]
	v_mov_b32_e32 v35, v34
	v_mov_b32_e32 v42, v34
	v_add_f32_dpp v33, v123, v123 quad_perm:[1,0,3,2] row_mask:0xf bank_mask:0xf bound_ctrl:1
	s_waitcnt lgkmcnt(0)
	v_lshl_add_u32 v32, v55, 7, v32
	v_and_b32_e32 v32, 0x3fff, v32
	ds_bpermute_b32 v174, v165, v32
	v_add_f32_dpp v33, v33, v33 quad_perm:[2,3,0,1] row_mask:0xf bank_mask:0xf bound_ctrl:1
	s_waitcnt vmcnt(3)
	v_lshlrev_b32_e32 v148, 16, v44
	s_waitcnt vmcnt(2)
	v_lshlrev_b32_e32 v140, 16, v48
	v_add_f32_dpp v33, v33, v33 row_half_mirror row_mask:0xf bank_mask:0xf bound_ctrl:1
	v_and_b32_e32 v141, 0xffff0000, v48
	v_lshlrev_b32_e32 v142, 16, v49
	v_add_f32_dpp v33, v33, v33 row_mirror row_mask:0xf bank_mask:0xf bound_ctrl:1
	v_and_b32_e32 v143, 0xffff0000, v49
	v_readlane_b32 s66, v33, 0
	v_readlane_b32 s68, v33, 16
	v_readlane_b32 s67, v33, 32
	v_readlane_b32 s69, v33, 48
	v_lshlrev_b32_e32 v144, 16, v50
	v_and_b32_e32 v145, 0xffff0000, v50
	v_lshlrev_b32_e32 v146, 16, v51
	v_and_b32_e32 v147, 0xffff0000, v51
	v_and_b32_e32 v149, 0xffff0000, v44
	v_lshlrev_b32_e32 v150, 16, v45
	v_and_b32_e32 v151, 0xffff0000, v45
	v_lshlrev_b32_e32 v152, 16, v46
	v_and_b32_e32 v153, 0xffff0000, v46
	v_lshlrev_b32_e32 v154, 16, v47
	v_and_b32_e32 v155, 0xffff0000, v47
	v_mov_b32_e32 v32, v34
	v_mov_b32_e32 v33, v34
	v_mov_b32_e32 v43, v34
	v_mov_b32_e32 v40, v34
	v_mov_b32_e32 v41, v34
	v_mov_b32_e32 v46, v34
	v_mov_b32_e32 v47, v34
	v_mov_b32_e32 v44, v34
	v_mov_b32_e32 v45, v34
	v_mov_b32_e32 v50, v34
	v_mov_b32_e32 v51, v34
	v_mov_b32_e32 v48, v34
	v_mov_b32_e32 v49, v34
	v_mov_b32_e32 v54, v34
	v_mov_b32_e32 v55, v34
	v_mov_b32_e32 v52, v34
	v_mov_b32_e32 v53, v34
	v_mov_b32_e32 v56, v34
	s_waitcnt vmcnt(0) lgkmcnt(0)
	v_subrev_u32_e32 v178, s96, v114
	s_nop 1
	v_readlane_b32 s100, v122, 6
	s_nop 0
	s_lshl_b32 s100, s100, 11
	s_add_u32 s100, s96, s100
	s_addc_u32 s101, s97, 0
	global_load_dwordx4 v[12:15], v178, s[100:101]
	global_load_dwordx4 v[20:23], v178, s[100:101] offset:1024
	s_waitcnt vmcnt(2)
	v_cvt_pk_f32_fp8_e32 v[64:65], v0
	v_pk_fma_f32 v[72:73], v[64:65], v[124:125], 0 op_sel_hi:[1,1,0]
	v_cvt_pk_f32_fp8_sdwa v[66:67], v0 src0_sel:WORD_1
	v_pk_fma_f32 v[72:73], v[66:67], v[126:127], v[72:73]
	v_cvt_pk_f32_fp8_e32 v[68:69], v1
	v_pk_fma_f32 v[72:73], v[68:69], v[128:129], v[72:73]
	v_cvt_pk_f32_fp8_sdwa v[70:71], v1 src0_sel:WORD_1
	v_pk_fma_f32 v[72:73], v[70:71], v[130:131], v[72:73]
	v_cvt_pk_f32_fp8_e32 v[64:65], v2
	v_pk_fma_f32 v[72:73], v[64:65], v[132:133], v[72:73]
	v_cvt_pk_f32_fp8_sdwa v[66:67], v2 src0_sel:WORD_1
	v_pk_fma_f32 v[72:73], v[66:67], v[134:135], v[72:73]
	v_cvt_pk_f32_fp8_e32 v[68:69], v3
	v_pk_fma_f32 v[72:73], v[68:69], v[136:137], v[72:73]
	v_cvt_pk_f32_fp8_sdwa v[70:71], v3 src0_sel:WORD_1
	v_pk_fma_f32 v[72:73], v[70:71], v[138:139], v[72:73]
	v_cvt_pk_f32_fp8_e32 v[64:65], v4
	v_pk_fma_f32 v[72:73], v[64:65], v[140:141], v[72:73]
	v_cvt_pk_f32_fp8_sdwa v[66:67], v4 src0_sel:WORD_1
	v_pk_fma_f32 v[72:73], v[66:67], v[142:143], v[72:73]
	v_cvt_pk_f32_fp8_e32 v[68:69], v5
	v_pk_fma_f32 v[72:73], v[68:69], v[144:145], v[72:73]
	v_cvt_pk_f32_fp8_sdwa v[70:71], v5 src0_sel:WORD_1
	v_pk_fma_f32 v[72:73], v[70:71], v[146:147], v[72:73]
	v_cvt_pk_f32_fp8_e32 v[64:65], v6
	v_pk_fma_f32 v[72:73], v[64:65], v[148:149], v[72:73]
	v_cvt_pk_f32_fp8_sdwa v[66:67], v6 src0_sel:WORD_1
	v_pk_fma_f32 v[72:73], v[66:67], v[150:151], v[72:73]
	v_cvt_pk_f32_fp8_e32 v[68:69], v7
	v_pk_fma_f32 v[72:73], v[68:69], v[152:153], v[72:73]
	v_cvt_pk_f32_fp8_sdwa v[70:71], v7 src0_sel:WORD_1
	v_pk_fma_f32 v[72:73], v[70:71], v[154:155], v[72:73]
	s_nop 1
	v_readlane_b32 s100, v122, 7
	v_add_f32_e32 v72, v72, v73
	s_lshl_b32 s100, s100, 11
	s_add_u32 s100, s96, s100
	s_addc_u32 s101, s97, 0
	global_load_dwordx4 v[24:27], v178, s[100:101]
	global_load_dwordx4 v[28:31], v178, s[100:101] offset:1024
	s_waitcnt vmcnt(4)
	v_cvt_pk_f32_fp8_e32 v[64:65], v8
	v_pk_fma_f32 v[74:75], v[64:65], v[124:125], 0 op_sel_hi:[1,1,0]
	v_cvt_pk_f32_fp8_sdwa v[66:67], v8 src0_sel:WORD_1
	v_pk_fma_f32 v[74:75], v[66:67], v[126:127], v[74:75]
	v_cvt_pk_f32_fp8_e32 v[68:69], v9
	v_pk_fma_f32 v[74:75], v[68:69], v[128:129], v[74:75]
	v_cvt_pk_f32_fp8_sdwa v[70:71], v9 src0_sel:WORD_1
	v_pk_fma_f32 v[74:75], v[70:71], v[130:131], v[74:75]
	v_cvt_pk_f32_fp8_e32 v[64:65], v10
	v_pk_fma_f32 v[74:75], v[64:65], v[132:133], v[74:75]
	v_cvt_pk_f32_fp8_sdwa v[66:67], v10 src0_sel:WORD_1
	v_pk_fma_f32 v[74:75], v[66:67], v[134:135], v[74:75]
	v_add_f32_dpp v72, v72, v72 quad_perm:[1,0,3,2] row_mask:0xf bank_mask:0xf bound_ctrl:1
	v_cvt_pk_f32_fp8_e32 v[68:69], v11
	v_pk_fma_f32 v[74:75], v[68:69], v[136:137], v[74:75]
	v_cvt_pk_f32_fp8_sdwa v[70:71], v11 src0_sel:WORD_1
	v_add_f32_dpp v72, v72, v72 quad_perm:[2,3,0,1] row_mask:0xf bank_mask:0xf bound_ctrl:1
	v_pk_fma_f32 v[74:75], v[70:71], v[138:139], v[74:75]
	v_cvt_pk_f32_fp8_e32 v[64:65], v16
	v_pk_fma_f32 v[74:75], v[64:65], v[140:141], v[74:75]
	v_add_f32_dpp v72, v72, v72 row_half_mirror row_mask:0xf bank_mask:0xf bound_ctrl:1
	v_cvt_pk_f32_fp8_sdwa v[66:67], v16 src0_sel:WORD_1
	v_pk_fma_f32 v[74:75], v[66:67], v[142:143], v[74:75]
	v_cvt_pk_f32_fp8_e32 v[68:69], v17
	v_add_f32_dpp v72, v72, v72 row_mirror row_mask:0xf bank_mask:0xf bound_ctrl:1
	v_pk_fma_f32 v[74:75], v[68:69], v[144:145], v[74:75]
	v_cvt_pk_f32_fp8_sdwa v[70:71], v17 src0_sel:WORD_1
	v_pk_fma_f32 v[74:75], v[70:71], v[146:147], v[74:75]
	v_add_f32_dpp v72, v72, v72 row_bcast:15 row_mask:0xa bank_mask:0xf
	v_cvt_pk_f32_fp8_e32 v[64:65], v18
	v_pk_fma_f32 v[74:75], v[64:65], v[148:149], v[74:75]
	v_cvt_pk_f32_fp8_sdwa v[66:67], v18 src0_sel:WORD_1
	v_add_f32_dpp v72, v72, v72 row_bcast:31 row_mask:0xc bank_mask:0xf
	v_pk_fma_f32 v[74:75], v[66:67], v[150:151], v[74:75]
	v_cvt_pk_f32_fp8_e32 v[68:69], v19
	v_readlane_b32 s50, v72, 63
	v_pk_fma_f32 v[74:75], v[68:69], v[152:153], v[74:75]
	v_cvt_pk_f32_fp8_sdwa v[70:71], v19 src0_sel:WORD_1
	v_pk_fma_f32 v[74:75], v[70:71], v[154:155], v[74:75]
	v_writelane_b32 v177, s50, 0
	s_nop 1
	v_readlane_b32 s100, v122, 8
	v_add_f32_e32 v74, v74, v75
	s_lshl_b32 s100, s100, 11
	s_add_u32 s100, s96, s100
	s_addc_u32 s101, s97, 0
	global_load_dwordx4 v[0:3], v178, s[100:101]
	global_load_dwordx4 v[4:7], v178, s[100:101] offset:1024
	s_waitcnt vmcnt(6)
	v_cvt_pk_f32_fp8_e32 v[64:65], v80
	v_pk_fma_f32 v[72:73], v[64:65], v[124:125], 0 op_sel_hi:[1,1,0]
	v_cvt_pk_f32_fp8_sdwa v[66:67], v80 src0_sel:WORD_1
	v_pk_fma_f32 v[72:73], v[66:67], v[126:127], v[72:73]
	v_cvt_pk_f32_fp8_e32 v[68:69], v81
	v_pk_fma_f32 v[72:73], v[68:69], v[128:129], v[72:73]
	v_cvt_pk_f32_fp8_sdwa v[70:71], v81 src0_sel:WORD_1
	v_pk_fma_f32 v[72:73], v[70:71], v[130:131], v[72:73]
	v_cvt_pk_f32_fp8_e32 v[64:65], v82
	v_pk_fma_f32 v[72:73], v[64:65], v[132:133], v[72:73]
	v_cvt_pk_f32_fp8_sdwa v[66:67], v82 src0_sel:WORD_1
	v_pk_fma_f32 v[72:73], v[66:67], v[134:135], v[72:73]
	v_add_f32_dpp v74, v74, v74 quad_perm:[1,0,3,2] row_mask:0xf bank_mask:0xf bound_ctrl:1
	v_cvt_pk_f32_fp8_e32 v[68:69], v83
	v_pk_fma_f32 v[72:73], v[68:69], v[136:137], v[72:73]
	v_cvt_pk_f32_fp8_sdwa v[70:71], v83 src0_sel:WORD_1
	v_add_f32_dpp v74, v74, v74 quad_perm:[2,3,0,1] row_mask:0xf bank_mask:0xf bound_ctrl:1
	v_pk_fma_f32 v[72:73], v[70:71], v[138:139], v[72:73]
	v_cvt_pk_f32_fp8_e32 v[64:65], v84
	v_pk_fma_f32 v[72:73], v[64:65], v[140:141], v[72:73]
	v_add_f32_dpp v74, v74, v74 row_half_mirror row_mask:0xf bank_mask:0xf bound_ctrl:1
	v_cvt_pk_f32_fp8_sdwa v[66:67], v84 src0_sel:WORD_1
	v_pk_fma_f32 v[72:73], v[66:67], v[142:143], v[72:73]
	v_cvt_pk_f32_fp8_e32 v[68:69], v85
	v_add_f32_dpp v74, v74, v74 row_mirror row_mask:0xf bank_mask:0xf bound_ctrl:1
	v_pk_fma_f32 v[72:73], v[68:69], v[144:145], v[72:73]
	v_cvt_pk_f32_fp8_sdwa v[70:71], v85 src0_sel:WORD_1
	v_pk_fma_f32 v[72:73], v[70:71], v[146:147], v[72:73]
	v_add_f32_dpp v74, v74, v74 row_bcast:15 row_mask:0xa bank_mask:0xf
	v_cvt_pk_f32_fp8_e32 v[64:65], v86
	v_pk_fma_f32 v[72:73], v[64:65], v[148:149], v[72:73]
	v_cvt_pk_f32_fp8_sdwa v[66:67], v86 src0_sel:WORD_1
	v_add_f32_dpp v74, v74, v74 row_bcast:31 row_mask:0xc bank_mask:0xf
	v_pk_fma_f32 v[72:73], v[66:67], v[150:151], v[72:73]
	v_cvt_pk_f32_fp8_e32 v[68:69], v87
	v_readlane_b32 s50, v74, 63
	v_pk_fma_f32 v[72:73], v[68:69], v[152:153], v[72:73]
	v_cvt_pk_f32_fp8_sdwa v[70:71], v87 src0_sel:WORD_1
	v_pk_fma_f32 v[72:73], v[70:71], v[154:155], v[72:73]
	v_writelane_b32 v177, s50, 1
	s_nop 1
	v_readlane_b32 s100, v122, 9
	v_add_f32_e32 v72, v72, v73
	s_lshl_b32 s100, s100, 11
	s_add_u32 s100, s96, s100
	s_addc_u32 s101, s97, 0
	global_load_dwordx4 v[8:11], v178, s[100:101]
	global_load_dwordx4 v[16:19], v178, s[100:101] offset:1024
	s_waitcnt vmcnt(8)
	v_cvt_pk_f32_fp8_e32 v[64:65], v88
	v_pk_fma_f32 v[74:75], v[64:65], v[124:125], 0 op_sel_hi:[1,1,0]
	v_cvt_pk_f32_fp8_sdwa v[66:67], v88 src0_sel:WORD_1
	v_pk_fma_f32 v[74:75], v[66:67], v[126:127], v[74:75]
	v_cvt_pk_f32_fp8_e32 v[68:69], v89
	v_pk_fma_f32 v[74:75], v[68:69], v[128:129], v[74:75]
	v_cvt_pk_f32_fp8_sdwa v[70:71], v89 src0_sel:WORD_1
	v_pk_fma_f32 v[74:75], v[70:71], v[130:131], v[74:75]
	v_cvt_pk_f32_fp8_e32 v[64:65], v90
	v_pk_fma_f32 v[74:75], v[64:65], v[132:133], v[74:75]
	v_cvt_pk_f32_fp8_sdwa v[66:67], v90 src0_sel:WORD_1
	v_pk_fma_f32 v[74:75], v[66:67], v[134:135], v[74:75]
	v_add_f32_dpp v72, v72, v72 quad_perm:[1,0,3,2] row_mask:0xf bank_mask:0xf bound_ctrl:1
	v_cvt_pk_f32_fp8_e32 v[68:69], v91
	v_pk_fma_f32 v[74:75], v[68:69], v[136:137], v[74:75]
	v_cvt_pk_f32_fp8_sdwa v[70:71], v91 src0_sel:WORD_1
	v_add_f32_dpp v72, v72, v72 quad_perm:[2,3,0,1] row_mask:0xf bank_mask:0xf bound_ctrl:1
	v_pk_fma_f32 v[74:75], v[70:71], v[138:139], v[74:75]
	v_cvt_pk_f32_fp8_e32 v[64:65], v92
	v_pk_fma_f32 v[74:75], v[64:65], v[140:141], v[74:75]
	v_add_f32_dpp v72, v72, v72 row_half_mirror row_mask:0xf bank_mask:0xf bound_ctrl:1
	v_cvt_pk_f32_fp8_sdwa v[66:67], v92 src0_sel:WORD_1
	v_pk_fma_f32 v[74:75], v[66:67], v[142:143], v[74:75]
	v_cvt_pk_f32_fp8_e32 v[68:69], v93
	v_add_f32_dpp v72, v72, v72 row_mirror row_mask:0xf bank_mask:0xf bound_ctrl:1
	v_pk_fma_f32 v[74:75], v[68:69], v[144:145], v[74:75]
	v_cvt_pk_f32_fp8_sdwa v[70:71], v93 src0_sel:WORD_1
	v_pk_fma_f32 v[74:75], v[70:71], v[146:147], v[74:75]
	v_add_f32_dpp v72, v72, v72 row_bcast:15 row_mask:0xa bank_mask:0xf
	v_cvt_pk_f32_fp8_e32 v[64:65], v94
	v_pk_fma_f32 v[74:75], v[64:65], v[148:149], v[74:75]
	v_cvt_pk_f32_fp8_sdwa v[66:67], v94 src0_sel:WORD_1
	v_add_f32_dpp v72, v72, v72 row_bcast:31 row_mask:0xc bank_mask:0xf
	v_pk_fma_f32 v[74:75], v[66:67], v[150:151], v[74:75]
	v_cvt_pk_f32_fp8_e32 v[68:69], v95
	v_readlane_b32 s50, v72, 63
	v_pk_fma_f32 v[74:75], v[68:69], v[152:153], v[74:75]
	v_cvt_pk_f32_fp8_sdwa v[70:71], v95 src0_sel:WORD_1
	v_pk_fma_f32 v[74:75], v[70:71], v[154:155], v[74:75]
	v_writelane_b32 v177, s50, 2
	s_nop 1
	v_readlane_b32 s100, v122, 10
	v_add_f32_e32 v74, v74, v75
	s_lshl_b32 s100, s100, 11
	s_add_u32 s100, s96, s100
	s_addc_u32 s101, s97, 0
	global_load_dwordx4 v[80:83], v178, s[100:101]
	global_load_dwordx4 v[84:87], v178, s[100:101] offset:1024
	s_waitcnt vmcnt(10)
	v_cvt_pk_f32_fp8_e32 v[64:65], v96
	v_pk_fma_f32 v[72:73], v[64:65], v[124:125], 0 op_sel_hi:[1,1,0]
	v_cvt_pk_f32_fp8_sdwa v[66:67], v96 src0_sel:WORD_1
	v_pk_fma_f32 v[72:73], v[66:67], v[126:127], v[72:73]
	v_cvt_pk_f32_fp8_e32 v[68:69], v97
	v_pk_fma_f32 v[72:73], v[68:69], v[128:129], v[72:73]
	v_cvt_pk_f32_fp8_sdwa v[70:71], v97 src0_sel:WORD_1
	v_pk_fma_f32 v[72:73], v[70:71], v[130:131], v[72:73]
	v_cvt_pk_f32_fp8_e32 v[64:65], v98
	v_pk_fma_f32 v[72:73], v[64:65], v[132:133], v[72:73]
	v_cvt_pk_f32_fp8_sdwa v[66:67], v98 src0_sel:WORD_1
	v_pk_fma_f32 v[72:73], v[66:67], v[134:135], v[72:73]
	v_add_f32_dpp v74, v74, v74 quad_perm:[1,0,3,2] row_mask:0xf bank_mask:0xf bound_ctrl:1
	v_cvt_pk_f32_fp8_e32 v[68:69], v99
	v_pk_fma_f32 v[72:73], v[68:69], v[136:137], v[72:73]
	v_cvt_pk_f32_fp8_sdwa v[70:71], v99 src0_sel:WORD_1
	v_add_f32_dpp v74, v74, v74 quad_perm:[2,3,0,1] row_mask:0xf bank_mask:0xf bound_ctrl:1
	v_pk_fma_f32 v[72:73], v[70:71], v[138:139], v[72:73]
	v_cvt_pk_f32_fp8_e32 v[64:65], v100
	v_pk_fma_f32 v[72:73], v[64:65], v[140:141], v[72:73]
	v_add_f32_dpp v74, v74, v74 row_half_mirror row_mask:0xf bank_mask:0xf bound_ctrl:1
	v_cvt_pk_f32_fp8_sdwa v[66:67], v100 src0_sel:WORD_1
	v_pk_fma_f32 v[72:73], v[66:67], v[142:143], v[72:73]
	v_cvt_pk_f32_fp8_e32 v[68:69], v101
	v_add_f32_dpp v74, v74, v74 row_mirror row_mask:0xf bank_mask:0xf bound_ctrl:1
	v_pk_fma_f32 v[72:73], v[68:69], v[144:145], v[72:73]
	v_cvt_pk_f32_fp8_sdwa v[70:71], v101 src0_sel:WORD_1
	v_pk_fma_f32 v[72:73], v[70:71], v[146:147], v[72:73]
	v_add_f32_dpp v74, v74, v74 row_bcast:15 row_mask:0xa bank_mask:0xf
	v_cvt_pk_f32_fp8_e32 v[64:65], v102
	v_pk_fma_f32 v[72:73], v[64:65], v[148:149], v[72:73]
	v_cvt_pk_f32_fp8_sdwa v[66:67], v102 src0_sel:WORD_1
	v_add_f32_dpp v74, v74, v74 row_bcast:31 row_mask:0xc bank_mask:0xf
	v_pk_fma_f32 v[72:73], v[66:67], v[150:151], v[72:73]
	v_cvt_pk_f32_fp8_e32 v[68:69], v103
	v_readlane_b32 s50, v74, 63
	v_pk_fma_f32 v[72:73], v[68:69], v[152:153], v[72:73]
	v_cvt_pk_f32_fp8_sdwa v[70:71], v103 src0_sel:WORD_1
	v_pk_fma_f32 v[72:73], v[70:71], v[154:155], v[72:73]
	v_writelane_b32 v177, s50, 3
	s_nop 1
	v_readlane_b32 s100, v122, 11
	v_add_f32_e32 v72, v72, v73
	s_lshl_b32 s100, s100, 11
	s_add_u32 s100, s96, s100
	s_addc_u32 s101, s97, 0
	global_load_dwordx4 v[88:91], v178, s[100:101]
	global_load_dwordx4 v[92:95], v178, s[100:101] offset:1024
	s_waitcnt vmcnt(12)
	v_cvt_pk_f32_fp8_e32 v[64:65], v104
	v_pk_fma_f32 v[74:75], v[64:65], v[124:125], 0 op_sel_hi:[1,1,0]
	v_cvt_pk_f32_fp8_sdwa v[66:67], v104 src0_sel:WORD_1
	v_pk_fma_f32 v[74:75], v[66:67], v[126:127], v[74:75]
	v_cvt_pk_f32_fp8_e32 v[68:69], v105
	v_pk_fma_f32 v[74:75], v[68:69], v[128:129], v[74:75]
	v_cvt_pk_f32_fp8_sdwa v[70:71], v105 src0_sel:WORD_1
	v_pk_fma_f32 v[74:75], v[70:71], v[130:131], v[74:75]
	v_cvt_pk_f32_fp8_e32 v[64:65], v106
	v_pk_fma_f32 v[74:75], v[64:65], v[132:133], v[74:75]
	v_cvt_pk_f32_fp8_sdwa v[66:67], v106 src0_sel:WORD_1
	v_pk_fma_f32 v[74:75], v[66:67], v[134:135], v[74:75]
	v_add_f32_dpp v72, v72, v72 quad_perm:[1,0,3,2] row_mask:0xf bank_mask:0xf bound_ctrl:1
	v_cvt_pk_f32_fp8_e32 v[68:69], v107
	v_pk_fma_f32 v[74:75], v[68:69], v[136:137], v[74:75]
	v_cvt_pk_f32_fp8_sdwa v[70:71], v107 src0_sel:WORD_1
	v_add_f32_dpp v72, v72, v72 quad_perm:[2,3,0,1] row_mask:0xf bank_mask:0xf bound_ctrl:1
	v_pk_fma_f32 v[74:75], v[70:71], v[138:139], v[74:75]
	v_cvt_pk_f32_fp8_e32 v[64:65], v108
	v_pk_fma_f32 v[74:75], v[64:65], v[140:141], v[74:75]
	v_add_f32_dpp v72, v72, v72 row_half_mirror row_mask:0xf bank_mask:0xf bound_ctrl:1
	v_cvt_pk_f32_fp8_sdwa v[66:67], v108 src0_sel:WORD_1
	v_pk_fma_f32 v[74:75], v[66:67], v[142:143], v[74:75]
	v_cvt_pk_f32_fp8_e32 v[68:69], v109
	v_add_f32_dpp v72, v72, v72 row_mirror row_mask:0xf bank_mask:0xf bound_ctrl:1
	v_pk_fma_f32 v[74:75], v[68:69], v[144:145], v[74:75]
	v_cvt_pk_f32_fp8_sdwa v[70:71], v109 src0_sel:WORD_1
	v_pk_fma_f32 v[74:75], v[70:71], v[146:147], v[74:75]
	v_add_f32_dpp v72, v72, v72 row_bcast:15 row_mask:0xa bank_mask:0xf
	v_cvt_pk_f32_fp8_e32 v[64:65], v110
	v_pk_fma_f32 v[74:75], v[64:65], v[148:149], v[74:75]
	v_cvt_pk_f32_fp8_sdwa v[66:67], v110 src0_sel:WORD_1
	v_add_f32_dpp v72, v72, v72 row_bcast:31 row_mask:0xc bank_mask:0xf
	v_pk_fma_f32 v[74:75], v[66:67], v[150:151], v[74:75]
	v_cvt_pk_f32_fp8_e32 v[68:69], v111
	v_readlane_b32 s50, v72, 63
	v_pk_fma_f32 v[74:75], v[68:69], v[152:153], v[74:75]
	v_cvt_pk_f32_fp8_sdwa v[70:71], v111 src0_sel:WORD_1
	v_pk_fma_f32 v[74:75], v[70:71], v[154:155], v[74:75]
	v_writelane_b32 v177, s50, 4
	s_nop 1
	v_readlane_b32 s100, v122, 12
	v_add_f32_e32 v74, v74, v75
	s_lshl_b32 s100, s100, 11
	s_add_u32 s100, s96, s100
	s_addc_u32 s101, s97, 0
	global_load_dwordx4 v[96:99], v178, s[100:101]
	global_load_dwordx4 v[100:103], v178, s[100:101] offset:1024
	s_waitcnt vmcnt(12)
	v_cvt_pk_f32_fp8_e32 v[64:65], v12
	v_pk_fma_f32 v[72:73], v[64:65], v[124:125], 0 op_sel_hi:[1,1,0]
	v_cvt_pk_f32_fp8_sdwa v[66:67], v12 src0_sel:WORD_1
	v_pk_fma_f32 v[72:73], v[66:67], v[126:127], v[72:73]
	v_cvt_pk_f32_fp8_e32 v[68:69], v13
	v_pk_fma_f32 v[72:73], v[68:69], v[128:129], v[72:73]
	v_cvt_pk_f32_fp8_sdwa v[70:71], v13 src0_sel:WORD_1
	v_pk_fma_f32 v[72:73], v[70:71], v[130:131], v[72:73]
	v_cvt_pk_f32_fp8_e32 v[64:65], v14
	v_pk_fma_f32 v[72:73], v[64:65], v[132:133], v[72:73]
	v_cvt_pk_f32_fp8_sdwa v[66:67], v14 src0_sel:WORD_1
	v_pk_fma_f32 v[72:73], v[66:67], v[134:135], v[72:73]
	v_add_f32_dpp v74, v74, v74 quad_perm:[1,0,3,2] row_mask:0xf bank_mask:0xf bound_ctrl:1
	v_cvt_pk_f32_fp8_e32 v[68:69], v15
	v_pk_fma_f32 v[72:73], v[68:69], v[136:137], v[72:73]
	v_cvt_pk_f32_fp8_sdwa v[70:71], v15 src0_sel:WORD_1
	v_add_f32_dpp v74, v74, v74 quad_perm:[2,3,0,1] row_mask:0xf bank_mask:0xf bound_ctrl:1
	v_pk_fma_f32 v[72:73], v[70:71], v[138:139], v[72:73]
	v_cvt_pk_f32_fp8_e32 v[64:65], v20
	v_pk_fma_f32 v[72:73], v[64:65], v[140:141], v[72:73]
	v_add_f32_dpp v74, v74, v74 row_half_mirror row_mask:0xf bank_mask:0xf bound_ctrl:1
	v_cvt_pk_f32_fp8_sdwa v[66:67], v20 src0_sel:WORD_1
	v_pk_fma_f32 v[72:73], v[66:67], v[142:143], v[72:73]
	v_cvt_pk_f32_fp8_e32 v[68:69], v21
	v_add_f32_dpp v74, v74, v74 row_mirror row_mask:0xf bank_mask:0xf bound_ctrl:1
	v_pk_fma_f32 v[72:73], v[68:69], v[144:145], v[72:73]
	v_cvt_pk_f32_fp8_sdwa v[70:71], v21 src0_sel:WORD_1
	v_pk_fma_f32 v[72:73], v[70:71], v[146:147], v[72:73]
	v_add_f32_dpp v74, v74, v74 row_bcast:15 row_mask:0xa bank_mask:0xf
	v_cvt_pk_f32_fp8_e32 v[64:65], v22
	v_pk_fma_f32 v[72:73], v[64:65], v[148:149], v[72:73]
	v_cvt_pk_f32_fp8_sdwa v[66:67], v22 src0_sel:WORD_1
	v_add_f32_dpp v74, v74, v74 row_bcast:31 row_mask:0xc bank_mask:0xf
	v_pk_fma_f32 v[72:73], v[66:67], v[150:151], v[72:73]
	v_cvt_pk_f32_fp8_e32 v[68:69], v23
	v_readlane_b32 s50, v74, 63
	v_pk_fma_f32 v[72:73], v[68:69], v[152:153], v[72:73]
	v_cvt_pk_f32_fp8_sdwa v[70:71], v23 src0_sel:WORD_1
	v_pk_fma_f32 v[72:73], v[70:71], v[154:155], v[72:73]
	v_writelane_b32 v177, s50, 5
	s_nop 1
	v_readlane_b32 s100, v122, 13
	v_add_f32_e32 v72, v72, v73
	s_lshl_b32 s100, s100, 11
	s_add_u32 s100, s96, s100
	s_addc_u32 s101, s97, 0
	global_load_dwordx4 v[104:107], v178, s[100:101]
	global_load_dwordx4 v[108:111], v178, s[100:101] offset:1024
	s_waitcnt vmcnt(12)
	v_cvt_pk_f32_fp8_e32 v[64:65], v24
	v_pk_fma_f32 v[74:75], v[64:65], v[124:125], 0 op_sel_hi:[1,1,0]
	v_cvt_pk_f32_fp8_sdwa v[66:67], v24 src0_sel:WORD_1
	v_pk_fma_f32 v[74:75], v[66:67], v[126:127], v[74:75]
	v_cvt_pk_f32_fp8_e32 v[68:69], v25
	v_pk_fma_f32 v[74:75], v[68:69], v[128:129], v[74:75]
	v_cvt_pk_f32_fp8_sdwa v[70:71], v25 src0_sel:WORD_1
	v_pk_fma_f32 v[74:75], v[70:71], v[130:131], v[74:75]
	v_cvt_pk_f32_fp8_e32 v[64:65], v26
	v_pk_fma_f32 v[74:75], v[64:65], v[132:133], v[74:75]
	v_cvt_pk_f32_fp8_sdwa v[66:67], v26 src0_sel:WORD_1
	v_pk_fma_f32 v[74:75], v[66:67], v[134:135], v[74:75]
	v_add_f32_dpp v72, v72, v72 quad_perm:[1,0,3,2] row_mask:0xf bank_mask:0xf bound_ctrl:1
	v_cvt_pk_f32_fp8_e32 v[68:69], v27
	v_pk_fma_f32 v[74:75], v[68:69], v[136:137], v[74:75]
	v_cvt_pk_f32_fp8_sdwa v[70:71], v27 src0_sel:WORD_1
	v_add_f32_dpp v72, v72, v72 quad_perm:[2,3,0,1] row_mask:0xf bank_mask:0xf bound_ctrl:1
	v_pk_fma_f32 v[74:75], v[70:71], v[138:139], v[74:75]
	v_cvt_pk_f32_fp8_e32 v[64:65], v28
	v_pk_fma_f32 v[74:75], v[64:65], v[140:141], v[74:75]
	v_add_f32_dpp v72, v72, v72 row_half_mirror row_mask:0xf bank_mask:0xf bound_ctrl:1
	v_cvt_pk_f32_fp8_sdwa v[66:67], v28 src0_sel:WORD_1
	v_pk_fma_f32 v[74:75], v[66:67], v[142:143], v[74:75]
	v_cvt_pk_f32_fp8_e32 v[68:69], v29
	v_add_f32_dpp v72, v72, v72 row_mirror row_mask:0xf bank_mask:0xf bound_ctrl:1
	v_pk_fma_f32 v[74:75], v[68:69], v[144:145], v[74:75]
	v_cvt_pk_f32_fp8_sdwa v[70:71], v29 src0_sel:WORD_1
	v_pk_fma_f32 v[74:75], v[70:71], v[146:147], v[74:75]
	v_add_f32_dpp v72, v72, v72 row_bcast:15 row_mask:0xa bank_mask:0xf
	v_cvt_pk_f32_fp8_e32 v[64:65], v30
	v_pk_fma_f32 v[74:75], v[64:65], v[148:149], v[74:75]
	v_cvt_pk_f32_fp8_sdwa v[66:67], v30 src0_sel:WORD_1
	v_add_f32_dpp v72, v72, v72 row_bcast:31 row_mask:0xc bank_mask:0xf
	v_pk_fma_f32 v[74:75], v[66:67], v[150:151], v[74:75]
	v_cvt_pk_f32_fp8_e32 v[68:69], v31
	v_readlane_b32 s50, v72, 63
	v_pk_fma_f32 v[74:75], v[68:69], v[152:153], v[74:75]
	v_cvt_pk_f32_fp8_sdwa v[70:71], v31 src0_sel:WORD_1
	v_pk_fma_f32 v[74:75], v[70:71], v[154:155], v[74:75]
	v_writelane_b32 v177, s50, 6
	s_nop 1
	v_readlane_b32 s100, v122, 14
	v_add_f32_e32 v74, v74, v75
	s_lshl_b32 s100, s100, 11
	s_add_u32 s100, s96, s100
	s_addc_u32 s101, s97, 0
	global_load_dwordx4 v[12:15], v178, s[100:101]
	global_load_dwordx4 v[20:23], v178, s[100:101] offset:1024
	s_waitcnt vmcnt(12)
	v_cvt_pk_f32_fp8_e32 v[64:65], v0
	v_pk_fma_f32 v[72:73], v[64:65], v[124:125], 0 op_sel_hi:[1,1,0]
	v_cvt_pk_f32_fp8_sdwa v[66:67], v0 src0_sel:WORD_1
	v_pk_fma_f32 v[72:73], v[66:67], v[126:127], v[72:73]
	v_cvt_pk_f32_fp8_e32 v[68:69], v1
	v_pk_fma_f32 v[72:73], v[68:69], v[128:129], v[72:73]
	v_cvt_pk_f32_fp8_sdwa v[70:71], v1 src0_sel:WORD_1
	v_pk_fma_f32 v[72:73], v[70:71], v[130:131], v[72:73]
	v_cvt_pk_f32_fp8_e32 v[64:65], v2
	v_pk_fma_f32 v[72:73], v[64:65], v[132:133], v[72:73]
	v_cvt_pk_f32_fp8_sdwa v[66:67], v2 src0_sel:WORD_1
	v_pk_fma_f32 v[72:73], v[66:67], v[134:135], v[72:73]
	v_add_f32_dpp v74, v74, v74 quad_perm:[1,0,3,2] row_mask:0xf bank_mask:0xf bound_ctrl:1
	v_cvt_pk_f32_fp8_e32 v[68:69], v3
	v_pk_fma_f32 v[72:73], v[68:69], v[136:137], v[72:73]
	v_cvt_pk_f32_fp8_sdwa v[70:71], v3 src0_sel:WORD_1
	v_add_f32_dpp v74, v74, v74 quad_perm:[2,3,0,1] row_mask:0xf bank_mask:0xf bound_ctrl:1
	v_pk_fma_f32 v[72:73], v[70:71], v[138:139], v[72:73]
	v_cvt_pk_f32_fp8_e32 v[64:65], v4
	v_pk_fma_f32 v[72:73], v[64:65], v[140:141], v[72:73]
	v_add_f32_dpp v74, v74, v74 row_half_mirror row_mask:0xf bank_mask:0xf bound_ctrl:1
	v_cvt_pk_f32_fp8_sdwa v[66:67], v4 src0_sel:WORD_1
	v_pk_fma_f32 v[72:73], v[66:67], v[142:143], v[72:73]
	v_cvt_pk_f32_fp8_e32 v[68:69], v5
	v_add_f32_dpp v74, v74, v74 row_mirror row_mask:0xf bank_mask:0xf bound_ctrl:1
	v_pk_fma_f32 v[72:73], v[68:69], v[144:145], v[72:73]
	v_cvt_pk_f32_fp8_sdwa v[70:71], v5 src0_sel:WORD_1
	v_pk_fma_f32 v[72:73], v[70:71], v[146:147], v[72:73]
	v_add_f32_dpp v74, v74, v74 row_bcast:15 row_mask:0xa bank_mask:0xf
	v_cvt_pk_f32_fp8_e32 v[64:65], v6
	v_pk_fma_f32 v[72:73], v[64:65], v[148:149], v[72:73]
	v_cvt_pk_f32_fp8_sdwa v[66:67], v6 src0_sel:WORD_1
	v_add_f32_dpp v74, v74, v74 row_bcast:31 row_mask:0xc bank_mask:0xf
	v_pk_fma_f32 v[72:73], v[66:67], v[150:151], v[72:73]
	v_cvt_pk_f32_fp8_e32 v[68:69], v7
	v_readlane_b32 s50, v74, 63
	v_pk_fma_f32 v[72:73], v[68:69], v[152:153], v[72:73]
	v_cvt_pk_f32_fp8_sdwa v[70:71], v7 src0_sel:WORD_1
	v_pk_fma_f32 v[72:73], v[70:71], v[154:155], v[72:73]
	v_writelane_b32 v177, s50, 7
	s_nop 1
	v_readlane_b32 s100, v122, 15
	v_add_f32_e32 v72, v72, v73
	s_lshl_b32 s100, s100, 11
	s_add_u32 s100, s96, s100
	s_addc_u32 s101, s97, 0
	global_load_dwordx4 v[24:27], v178, s[100:101]
	global_load_dwordx4 v[28:31], v178, s[100:101] offset:1024
	s_waitcnt vmcnt(12)
	v_cvt_pk_f32_fp8_e32 v[64:65], v8
	v_pk_fma_f32 v[74:75], v[64:65], v[124:125], 0 op_sel_hi:[1,1,0]
	v_cvt_pk_f32_fp8_sdwa v[66:67], v8 src0_sel:WORD_1
	v_pk_fma_f32 v[74:75], v[66:67], v[126:127], v[74:75]
	v_cvt_pk_f32_fp8_e32 v[68:69], v9
	v_pk_fma_f32 v[74:75], v[68:69], v[128:129], v[74:75]
	v_cvt_pk_f32_fp8_sdwa v[70:71], v9 src0_sel:WORD_1
	v_pk_fma_f32 v[74:75], v[70:71], v[130:131], v[74:75]
	v_cvt_pk_f32_fp8_e32 v[64:65], v10
	v_pk_fma_f32 v[74:75], v[64:65], v[132:133], v[74:75]
	v_cvt_pk_f32_fp8_sdwa v[66:67], v10 src0_sel:WORD_1
	v_pk_fma_f32 v[74:75], v[66:67], v[134:135], v[74:75]
	v_add_f32_dpp v72, v72, v72 quad_perm:[1,0,3,2] row_mask:0xf bank_mask:0xf bound_ctrl:1
	v_cvt_pk_f32_fp8_e32 v[68:69], v11
	v_pk_fma_f32 v[74:75], v[68:69], v[136:137], v[74:75]
	v_cvt_pk_f32_fp8_sdwa v[70:71], v11 src0_sel:WORD_1
	v_add_f32_dpp v72, v72, v72 quad_perm:[2,3,0,1] row_mask:0xf bank_mask:0xf bound_ctrl:1
	v_pk_fma_f32 v[74:75], v[70:71], v[138:139], v[74:75]
	v_cvt_pk_f32_fp8_e32 v[64:65], v16
	v_pk_fma_f32 v[74:75], v[64:65], v[140:141], v[74:75]
	v_add_f32_dpp v72, v72, v72 row_half_mirror row_mask:0xf bank_mask:0xf bound_ctrl:1
	v_cvt_pk_f32_fp8_sdwa v[66:67], v16 src0_sel:WORD_1
	v_pk_fma_f32 v[74:75], v[66:67], v[142:143], v[74:75]
	v_cvt_pk_f32_fp8_e32 v[68:69], v17
	v_add_f32_dpp v72, v72, v72 row_mirror row_mask:0xf bank_mask:0xf bound_ctrl:1
	v_pk_fma_f32 v[74:75], v[68:69], v[144:145], v[74:75]
	v_cvt_pk_f32_fp8_sdwa v[70:71], v17 src0_sel:WORD_1
	v_pk_fma_f32 v[74:75], v[70:71], v[146:147], v[74:75]
	v_add_f32_dpp v72, v72, v72 row_bcast:15 row_mask:0xa bank_mask:0xf
	v_cvt_pk_f32_fp8_e32 v[64:65], v18
	v_pk_fma_f32 v[74:75], v[64:65], v[148:149], v[74:75]
	v_cvt_pk_f32_fp8_sdwa v[66:67], v18 src0_sel:WORD_1
	v_add_f32_dpp v72, v72, v72 row_bcast:31 row_mask:0xc bank_mask:0xf
	v_pk_fma_f32 v[74:75], v[66:67], v[150:151], v[74:75]
	v_cvt_pk_f32_fp8_e32 v[68:69], v19
	v_readlane_b32 s50, v72, 63
	v_pk_fma_f32 v[74:75], v[68:69], v[152:153], v[74:75]
	v_cvt_pk_f32_fp8_sdwa v[70:71], v19 src0_sel:WORD_1
	v_pk_fma_f32 v[74:75], v[70:71], v[154:155], v[74:75]
	v_writelane_b32 v177, s50, 8
	s_nop 1
	v_readlane_b32 s100, v122, 0
	v_add_f32_e32 v74, v74, v75
	s_lshl_b32 s100, s100, 11
	s_add_u32 s100, s98, s100
	s_addc_u32 s101, s99, 0
	global_load_dwordx4 v[192:195], v178, s[100:101]
	global_load_dwordx4 v[196:199], v178, s[100:101] offset:1024
	s_waitcnt vmcnt(12)
	v_cvt_pk_f32_fp8_e32 v[64:65], v80
	v_pk_fma_f32 v[72:73], v[64:65], v[124:125], 0 op_sel_hi:[1,1,0]
	v_cvt_pk_f32_fp8_sdwa v[66:67], v80 src0_sel:WORD_1
	v_pk_fma_f32 v[72:73], v[66:67], v[126:127], v[72:73]
	v_cvt_pk_f32_fp8_e32 v[68:69], v81
	v_pk_fma_f32 v[72:73], v[68:69], v[128:129], v[72:73]
	v_cvt_pk_f32_fp8_sdwa v[70:71], v81 src0_sel:WORD_1
	v_pk_fma_f32 v[72:73], v[70:71], v[130:131], v[72:73]
	v_cvt_pk_f32_fp8_e32 v[64:65], v82
	v_pk_fma_f32 v[72:73], v[64:65], v[132:133], v[72:73]
	v_cvt_pk_f32_fp8_sdwa v[66:67], v82 src0_sel:WORD_1
	v_pk_fma_f32 v[72:73], v[66:67], v[134:135], v[72:73]
	v_add_f32_dpp v74, v74, v74 quad_perm:[1,0,3,2] row_mask:0xf bank_mask:0xf bound_ctrl:1
	v_cvt_pk_f32_fp8_e32 v[68:69], v83
	v_pk_fma_f32 v[72:73], v[68:69], v[136:137], v[72:73]
	v_cvt_pk_f32_fp8_sdwa v[70:71], v83 src0_sel:WORD_1
	v_add_f32_dpp v74, v74, v74 quad_perm:[2,3,0,1] row_mask:0xf bank_mask:0xf bound_ctrl:1
	v_pk_fma_f32 v[72:73], v[70:71], v[138:139], v[72:73]
	v_cvt_pk_f32_fp8_e32 v[64:65], v84
	v_pk_fma_f32 v[72:73], v[64:65], v[140:141], v[72:73]
	v_add_f32_dpp v74, v74, v74 row_half_mirror row_mask:0xf bank_mask:0xf bound_ctrl:1
	v_cvt_pk_f32_fp8_sdwa v[66:67], v84 src0_sel:WORD_1
	v_pk_fma_f32 v[72:73], v[66:67], v[142:143], v[72:73]
	v_cvt_pk_f32_fp8_e32 v[68:69], v85
	v_add_f32_dpp v74, v74, v74 row_mirror row_mask:0xf bank_mask:0xf bound_ctrl:1
	v_pk_fma_f32 v[72:73], v[68:69], v[144:145], v[72:73]
	v_cvt_pk_f32_fp8_sdwa v[70:71], v85 src0_sel:WORD_1
	v_pk_fma_f32 v[72:73], v[70:71], v[146:147], v[72:73]
	v_add_f32_dpp v74, v74, v74 row_bcast:15 row_mask:0xa bank_mask:0xf
	v_cvt_pk_f32_fp8_e32 v[64:65], v86
	v_pk_fma_f32 v[72:73], v[64:65], v[148:149], v[72:73]
	v_cvt_pk_f32_fp8_sdwa v[66:67], v86 src0_sel:WORD_1
	v_add_f32_dpp v74, v74, v74 row_bcast:31 row_mask:0xc bank_mask:0xf
	v_pk_fma_f32 v[72:73], v[66:67], v[150:151], v[72:73]
	v_cvt_pk_f32_fp8_e32 v[68:69], v87
	v_readlane_b32 s50, v74, 63
	v_pk_fma_f32 v[72:73], v[68:69], v[152:153], v[72:73]
	v_cvt_pk_f32_fp8_sdwa v[70:71], v87 src0_sel:WORD_1
	v_pk_fma_f32 v[72:73], v[70:71], v[154:155], v[72:73]
	v_writelane_b32 v177, s50, 9
	s_nop 1
	v_readlane_b32 s100, v122, 1
	v_add_f32_e32 v72, v72, v73
	s_lshl_b32 s100, s100, 11
	s_add_u32 s100, s98, s100
	s_addc_u32 s101, s99, 0
	global_load_dwordx4 v[200:203], v178, s[100:101]
	global_load_dwordx4 v[204:207], v178, s[100:101] offset:1024
	s_waitcnt vmcnt(12)
	v_cvt_pk_f32_fp8_e32 v[64:65], v88
	v_pk_fma_f32 v[74:75], v[64:65], v[124:125], 0 op_sel_hi:[1,1,0]
	v_cvt_pk_f32_fp8_sdwa v[66:67], v88 src0_sel:WORD_1
	v_pk_fma_f32 v[74:75], v[66:67], v[126:127], v[74:75]
	v_cvt_pk_f32_fp8_e32 v[68:69], v89
	v_pk_fma_f32 v[74:75], v[68:69], v[128:129], v[74:75]
	v_cvt_pk_f32_fp8_sdwa v[70:71], v89 src0_sel:WORD_1
	v_pk_fma_f32 v[74:75], v[70:71], v[130:131], v[74:75]
	v_cvt_pk_f32_fp8_e32 v[64:65], v90
	v_pk_fma_f32 v[74:75], v[64:65], v[132:133], v[74:75]
	v_cvt_pk_f32_fp8_sdwa v[66:67], v90 src0_sel:WORD_1
	v_pk_fma_f32 v[74:75], v[66:67], v[134:135], v[74:75]
	v_add_f32_dpp v72, v72, v72 quad_perm:[1,0,3,2] row_mask:0xf bank_mask:0xf bound_ctrl:1
	v_cvt_pk_f32_fp8_e32 v[68:69], v91
	v_pk_fma_f32 v[74:75], v[68:69], v[136:137], v[74:75]
	v_cvt_pk_f32_fp8_sdwa v[70:71], v91 src0_sel:WORD_1
	v_add_f32_dpp v72, v72, v72 quad_perm:[2,3,0,1] row_mask:0xf bank_mask:0xf bound_ctrl:1
	v_pk_fma_f32 v[74:75], v[70:71], v[138:139], v[74:75]
	v_cvt_pk_f32_fp8_e32 v[64:65], v92
	v_pk_fma_f32 v[74:75], v[64:65], v[140:141], v[74:75]
	v_add_f32_dpp v72, v72, v72 row_half_mirror row_mask:0xf bank_mask:0xf bound_ctrl:1
	v_cvt_pk_f32_fp8_sdwa v[66:67], v92 src0_sel:WORD_1
	v_pk_fma_f32 v[74:75], v[66:67], v[142:143], v[74:75]
	v_cvt_pk_f32_fp8_e32 v[68:69], v93
	v_add_f32_dpp v72, v72, v72 row_mirror row_mask:0xf bank_mask:0xf bound_ctrl:1
	v_pk_fma_f32 v[74:75], v[68:69], v[144:145], v[74:75]
	v_cvt_pk_f32_fp8_sdwa v[70:71], v93 src0_sel:WORD_1
	v_pk_fma_f32 v[74:75], v[70:71], v[146:147], v[74:75]
	v_add_f32_dpp v72, v72, v72 row_bcast:15 row_mask:0xa bank_mask:0xf
	v_cvt_pk_f32_fp8_e32 v[64:65], v94
	v_pk_fma_f32 v[74:75], v[64:65], v[148:149], v[74:75]
	v_cvt_pk_f32_fp8_sdwa v[66:67], v94 src0_sel:WORD_1
	v_add_f32_dpp v72, v72, v72 row_bcast:31 row_mask:0xc bank_mask:0xf
	v_pk_fma_f32 v[74:75], v[66:67], v[150:151], v[74:75]
	v_cvt_pk_f32_fp8_e32 v[68:69], v95
	v_readlane_b32 s50, v72, 63
	v_pk_fma_f32 v[74:75], v[68:69], v[152:153], v[74:75]
	v_cvt_pk_f32_fp8_sdwa v[70:71], v95 src0_sel:WORD_1
	v_pk_fma_f32 v[74:75], v[70:71], v[154:155], v[74:75]
	v_writelane_b32 v177, s50, 10
	s_nop 1
	v_readlane_b32 s100, v122, 2
	v_add_f32_e32 v74, v74, v75
	s_lshl_b32 s100, s100, 11
	s_add_u32 s100, s98, s100
	s_addc_u32 s101, s99, 0
	global_load_dwordx4 v[208:211], v178, s[100:101]
	global_load_dwordx4 v[212:215], v178, s[100:101] offset:1024
	s_waitcnt vmcnt(12)
	v_cvt_pk_f32_fp8_e32 v[64:65], v96
	v_pk_fma_f32 v[72:73], v[64:65], v[124:125], 0 op_sel_hi:[1,1,0]
	v_cvt_pk_f32_fp8_sdwa v[66:67], v96 src0_sel:WORD_1
	v_pk_fma_f32 v[72:73], v[66:67], v[126:127], v[72:73]
	v_cvt_pk_f32_fp8_e32 v[68:69], v97
	v_pk_fma_f32 v[72:73], v[68:69], v[128:129], v[72:73]
	v_cvt_pk_f32_fp8_sdwa v[70:71], v97 src0_sel:WORD_1
	v_pk_fma_f32 v[72:73], v[70:71], v[130:131], v[72:73]
	v_cvt_pk_f32_fp8_e32 v[64:65], v98
	v_pk_fma_f32 v[72:73], v[64:65], v[132:133], v[72:73]
	v_cvt_pk_f32_fp8_sdwa v[66:67], v98 src0_sel:WORD_1
	v_pk_fma_f32 v[72:73], v[66:67], v[134:135], v[72:73]
	v_add_f32_dpp v74, v74, v74 quad_perm:[1,0,3,2] row_mask:0xf bank_mask:0xf bound_ctrl:1
	v_cvt_pk_f32_fp8_e32 v[68:69], v99
	v_pk_fma_f32 v[72:73], v[68:69], v[136:137], v[72:73]
	v_cvt_pk_f32_fp8_sdwa v[70:71], v99 src0_sel:WORD_1
	v_add_f32_dpp v74, v74, v74 quad_perm:[2,3,0,1] row_mask:0xf bank_mask:0xf bound_ctrl:1
	v_pk_fma_f32 v[72:73], v[70:71], v[138:139], v[72:73]
	v_cvt_pk_f32_fp8_e32 v[64:65], v100
	v_pk_fma_f32 v[72:73], v[64:65], v[140:141], v[72:73]
	v_add_f32_dpp v74, v74, v74 row_half_mirror row_mask:0xf bank_mask:0xf bound_ctrl:1
	v_cvt_pk_f32_fp8_sdwa v[66:67], v100 src0_sel:WORD_1
	v_pk_fma_f32 v[72:73], v[66:67], v[142:143], v[72:73]
	v_cvt_pk_f32_fp8_e32 v[68:69], v101
	v_add_f32_dpp v74, v74, v74 row_mirror row_mask:0xf bank_mask:0xf bound_ctrl:1
	v_pk_fma_f32 v[72:73], v[68:69], v[144:145], v[72:73]
	v_cvt_pk_f32_fp8_sdwa v[70:71], v101 src0_sel:WORD_1
	v_pk_fma_f32 v[72:73], v[70:71], v[146:147], v[72:73]
	v_add_f32_dpp v74, v74, v74 row_bcast:15 row_mask:0xa bank_mask:0xf
	v_cvt_pk_f32_fp8_e32 v[64:65], v102
	v_pk_fma_f32 v[72:73], v[64:65], v[148:149], v[72:73]
	v_cvt_pk_f32_fp8_sdwa v[66:67], v102 src0_sel:WORD_1
	v_add_f32_dpp v74, v74, v74 row_bcast:31 row_mask:0xc bank_mask:0xf
	v_pk_fma_f32 v[72:73], v[66:67], v[150:151], v[72:73]
	v_cvt_pk_f32_fp8_e32 v[68:69], v103
	v_readlane_b32 s50, v74, 63
	v_pk_fma_f32 v[72:73], v[68:69], v[152:153], v[72:73]
	v_cvt_pk_f32_fp8_sdwa v[70:71], v103 src0_sel:WORD_1
	v_pk_fma_f32 v[72:73], v[70:71], v[154:155], v[72:73]
	v_writelane_b32 v177, s50, 11
	s_nop 1
	v_readlane_b32 s100, v122, 3
	v_add_f32_e32 v72, v72, v73
	s_lshl_b32 s100, s100, 11
	s_add_u32 s100, s98, s100
	s_addc_u32 s101, s99, 0
	global_load_dwordx4 v[216:219], v178, s[100:101]
	global_load_dwordx4 v[220:223], v178, s[100:101] offset:1024
	s_waitcnt vmcnt(12)
	v_cvt_pk_f32_fp8_e32 v[64:65], v104
	v_pk_fma_f32 v[74:75], v[64:65], v[124:125], 0 op_sel_hi:[1,1,0]
	v_cvt_pk_f32_fp8_sdwa v[66:67], v104 src0_sel:WORD_1
	v_pk_fma_f32 v[74:75], v[66:67], v[126:127], v[74:75]
	v_cvt_pk_f32_fp8_e32 v[68:69], v105
	v_pk_fma_f32 v[74:75], v[68:69], v[128:129], v[74:75]
	v_cvt_pk_f32_fp8_sdwa v[70:71], v105 src0_sel:WORD_1
	v_pk_fma_f32 v[74:75], v[70:71], v[130:131], v[74:75]
	v_cvt_pk_f32_fp8_e32 v[64:65], v106
	v_pk_fma_f32 v[74:75], v[64:65], v[132:133], v[74:75]
	v_cvt_pk_f32_fp8_sdwa v[66:67], v106 src0_sel:WORD_1
	v_pk_fma_f32 v[74:75], v[66:67], v[134:135], v[74:75]
	v_add_f32_dpp v72, v72, v72 quad_perm:[1,0,3,2] row_mask:0xf bank_mask:0xf bound_ctrl:1
	v_cvt_pk_f32_fp8_e32 v[68:69], v107
	v_pk_fma_f32 v[74:75], v[68:69], v[136:137], v[74:75]
	v_cvt_pk_f32_fp8_sdwa v[70:71], v107 src0_sel:WORD_1
	v_add_f32_dpp v72, v72, v72 quad_perm:[2,3,0,1] row_mask:0xf bank_mask:0xf bound_ctrl:1
	v_pk_fma_f32 v[74:75], v[70:71], v[138:139], v[74:75]
	v_cvt_pk_f32_fp8_e32 v[64:65], v108
	v_pk_fma_f32 v[74:75], v[64:65], v[140:141], v[74:75]
	v_add_f32_dpp v72, v72, v72 row_half_mirror row_mask:0xf bank_mask:0xf bound_ctrl:1
	v_cvt_pk_f32_fp8_sdwa v[66:67], v108 src0_sel:WORD_1
	v_pk_fma_f32 v[74:75], v[66:67], v[142:143], v[74:75]
	v_cvt_pk_f32_fp8_e32 v[68:69], v109
	v_add_f32_dpp v72, v72, v72 row_mirror row_mask:0xf bank_mask:0xf bound_ctrl:1
	v_pk_fma_f32 v[74:75], v[68:69], v[144:145], v[74:75]
	v_cvt_pk_f32_fp8_sdwa v[70:71], v109 src0_sel:WORD_1
	v_pk_fma_f32 v[74:75], v[70:71], v[146:147], v[74:75]
	v_add_f32_dpp v72, v72, v72 row_bcast:15 row_mask:0xa bank_mask:0xf
	v_cvt_pk_f32_fp8_e32 v[64:65], v110
	v_pk_fma_f32 v[74:75], v[64:65], v[148:149], v[74:75]
	v_cvt_pk_f32_fp8_sdwa v[66:67], v110 src0_sel:WORD_1
	v_add_f32_dpp v72, v72, v72 row_bcast:31 row_mask:0xc bank_mask:0xf
	v_pk_fma_f32 v[74:75], v[66:67], v[150:151], v[74:75]
	v_cvt_pk_f32_fp8_e32 v[68:69], v111
	v_readlane_b32 s50, v72, 63
	v_pk_fma_f32 v[74:75], v[68:69], v[152:153], v[74:75]
	v_cvt_pk_f32_fp8_sdwa v[70:71], v111 src0_sel:WORD_1
	v_pk_fma_f32 v[74:75], v[70:71], v[154:155], v[74:75]
	v_writelane_b32 v177, s50, 12
	s_nop 1
	v_readlane_b32 s100, v122, 4
	v_add_f32_e32 v74, v74, v75
	s_lshl_b32 s100, s100, 11
	s_add_u32 s100, s98, s100
	s_addc_u32 s101, s99, 0
	global_load_dwordx4 v[224:227], v178, s[100:101]
	global_load_dwordx4 v[228:231], v178, s[100:101] offset:1024
	s_waitcnt vmcnt(12)
	v_cvt_pk_f32_fp8_e32 v[64:65], v12
	v_pk_fma_f32 v[72:73], v[64:65], v[124:125], 0 op_sel_hi:[1,1,0]
	v_cvt_pk_f32_fp8_sdwa v[66:67], v12 src0_sel:WORD_1
	v_pk_fma_f32 v[72:73], v[66:67], v[126:127], v[72:73]
	v_cvt_pk_f32_fp8_e32 v[68:69], v13
	v_pk_fma_f32 v[72:73], v[68:69], v[128:129], v[72:73]
	v_cvt_pk_f32_fp8_sdwa v[70:71], v13 src0_sel:WORD_1
	v_pk_fma_f32 v[72:73], v[70:71], v[130:131], v[72:73]
	v_cvt_pk_f32_fp8_e32 v[64:65], v14
	v_pk_fma_f32 v[72:73], v[64:65], v[132:133], v[72:73]
	v_cvt_pk_f32_fp8_sdwa v[66:67], v14 src0_sel:WORD_1
	v_pk_fma_f32 v[72:73], v[66:67], v[134:135], v[72:73]
	v_add_f32_dpp v74, v74, v74 quad_perm:[1,0,3,2] row_mask:0xf bank_mask:0xf bound_ctrl:1
	v_cvt_pk_f32_fp8_e32 v[68:69], v15
	v_pk_fma_f32 v[72:73], v[68:69], v[136:137], v[72:73]
	v_cvt_pk_f32_fp8_sdwa v[70:71], v15 src0_sel:WORD_1
	v_add_f32_dpp v74, v74, v74 quad_perm:[2,3,0,1] row_mask:0xf bank_mask:0xf bound_ctrl:1
	v_pk_fma_f32 v[72:73], v[70:71], v[138:139], v[72:73]
	v_cvt_pk_f32_fp8_e32 v[64:65], v20
	v_pk_fma_f32 v[72:73], v[64:65], v[140:141], v[72:73]
	v_add_f32_dpp v74, v74, v74 row_half_mirror row_mask:0xf bank_mask:0xf bound_ctrl:1
	v_cvt_pk_f32_fp8_sdwa v[66:67], v20 src0_sel:WORD_1
	v_pk_fma_f32 v[72:73], v[66:67], v[142:143], v[72:73]
	v_cvt_pk_f32_fp8_e32 v[68:69], v21
	v_add_f32_dpp v74, v74, v74 row_mirror row_mask:0xf bank_mask:0xf bound_ctrl:1
	v_pk_fma_f32 v[72:73], v[68:69], v[144:145], v[72:73]
	v_cvt_pk_f32_fp8_sdwa v[70:71], v21 src0_sel:WORD_1
	v_pk_fma_f32 v[72:73], v[70:71], v[146:147], v[72:73]
	v_add_f32_dpp v74, v74, v74 row_bcast:15 row_mask:0xa bank_mask:0xf
	v_cvt_pk_f32_fp8_e32 v[64:65], v22
	v_pk_fma_f32 v[72:73], v[64:65], v[148:149], v[72:73]
	v_cvt_pk_f32_fp8_sdwa v[66:67], v22 src0_sel:WORD_1
	v_add_f32_dpp v74, v74, v74 row_bcast:31 row_mask:0xc bank_mask:0xf
	v_pk_fma_f32 v[72:73], v[66:67], v[150:151], v[72:73]
	v_cvt_pk_f32_fp8_e32 v[68:69], v23
	v_readlane_b32 s50, v74, 63
	v_pk_fma_f32 v[72:73], v[68:69], v[152:153], v[72:73]
	v_cvt_pk_f32_fp8_sdwa v[70:71], v23 src0_sel:WORD_1
	v_pk_fma_f32 v[72:73], v[70:71], v[154:155], v[72:73]
	v_writelane_b32 v177, s50, 13
	s_nop 1
	v_readlane_b32 s100, v122, 5
	v_add_f32_e32 v72, v72, v73
	s_lshl_b32 s100, s100, 11
	s_add_u32 s100, s98, s100
	s_addc_u32 s101, s99, 0
	global_load_dwordx4 v[232:235], v178, s[100:101]
	global_load_dwordx4 v[236:239], v178, s[100:101] offset:1024
	s_waitcnt vmcnt(12)
	v_cvt_pk_f32_fp8_e32 v[64:65], v24
	v_pk_fma_f32 v[74:75], v[64:65], v[124:125], 0 op_sel_hi:[1,1,0]
	v_cvt_pk_f32_fp8_sdwa v[66:67], v24 src0_sel:WORD_1
	v_pk_fma_f32 v[74:75], v[66:67], v[126:127], v[74:75]
	v_cvt_pk_f32_fp8_e32 v[68:69], v25
	v_pk_fma_f32 v[74:75], v[68:69], v[128:129], v[74:75]
	v_cvt_pk_f32_fp8_sdwa v[70:71], v25 src0_sel:WORD_1
	v_pk_fma_f32 v[74:75], v[70:71], v[130:131], v[74:75]
	v_cvt_pk_f32_fp8_e32 v[64:65], v26
	v_pk_fma_f32 v[74:75], v[64:65], v[132:133], v[74:75]
	v_cvt_pk_f32_fp8_sdwa v[66:67], v26 src0_sel:WORD_1
	v_pk_fma_f32 v[74:75], v[66:67], v[134:135], v[74:75]
	v_add_f32_dpp v72, v72, v72 quad_perm:[1,0,3,2] row_mask:0xf bank_mask:0xf bound_ctrl:1
	v_cvt_pk_f32_fp8_e32 v[68:69], v27
	v_pk_fma_f32 v[74:75], v[68:69], v[136:137], v[74:75]
	v_cvt_pk_f32_fp8_sdwa v[70:71], v27 src0_sel:WORD_1
	v_add_f32_dpp v72, v72, v72 quad_perm:[2,3,0,1] row_mask:0xf bank_mask:0xf bound_ctrl:1
	v_pk_fma_f32 v[74:75], v[70:71], v[138:139], v[74:75]
	v_cvt_pk_f32_fp8_e32 v[64:65], v28
	v_pk_fma_f32 v[74:75], v[64:65], v[140:141], v[74:75]
	v_add_f32_dpp v72, v72, v72 row_half_mirror row_mask:0xf bank_mask:0xf bound_ctrl:1
	v_cvt_pk_f32_fp8_sdwa v[66:67], v28 src0_sel:WORD_1
	v_pk_fma_f32 v[74:75], v[66:67], v[142:143], v[74:75]
	v_cvt_pk_f32_fp8_e32 v[68:69], v29
	v_add_f32_dpp v72, v72, v72 row_mirror row_mask:0xf bank_mask:0xf bound_ctrl:1
	v_pk_fma_f32 v[74:75], v[68:69], v[144:145], v[74:75]
	v_cvt_pk_f32_fp8_sdwa v[70:71], v29 src0_sel:WORD_1
	v_pk_fma_f32 v[74:75], v[70:71], v[146:147], v[74:75]
	v_add_f32_dpp v72, v72, v72 row_bcast:15 row_mask:0xa bank_mask:0xf
	v_cvt_pk_f32_fp8_e32 v[64:65], v30
	v_pk_fma_f32 v[74:75], v[64:65], v[148:149], v[74:75]
	v_cvt_pk_f32_fp8_sdwa v[66:67], v30 src0_sel:WORD_1
	v_add_f32_dpp v72, v72, v72 row_bcast:31 row_mask:0xc bank_mask:0xf
	v_pk_fma_f32 v[74:75], v[66:67], v[150:151], v[74:75]
	v_cvt_pk_f32_fp8_e32 v[68:69], v31
	v_readlane_b32 s50, v72, 63
	v_pk_fma_f32 v[74:75], v[68:69], v[152:153], v[74:75]
	v_cvt_pk_f32_fp8_sdwa v[70:71], v31 src0_sel:WORD_1
	v_pk_fma_f32 v[74:75], v[70:71], v[154:155], v[74:75]
	v_writelane_b32 v177, s50, 14
	s_nop 1
	v_add_f32_e32 v74, v74, v75
	v_mul_f32_e32 v179, v173, v176
	v_mul_f32_e32 v179, 0.5, v179
	v_add_f32_dpp v74, v74, v74 quad_perm:[1,0,3,2] row_mask:0xf bank_mask:0xf bound_ctrl:1
	s_nop 0
	s_nop 0
	v_add_f32_dpp v74, v74, v74 quad_perm:[2,3,0,1] row_mask:0xf bank_mask:0xf bound_ctrl:1
	s_nop 0
	s_nop 0
	v_add_f32_dpp v74, v74, v74 row_half_mirror row_mask:0xf bank_mask:0xf bound_ctrl:1
	s_nop 0
	s_nop 0
	v_add_f32_dpp v74, v74, v74 row_mirror row_mask:0xf bank_mask:0xf bound_ctrl:1
	s_nop 0
	s_nop 0
	v_add_f32_dpp v74, v74, v74 row_bcast:15 row_mask:0xa bank_mask:0xf
	s_nop 0
	s_nop 0
	v_add_f32_dpp v74, v74, v74 row_bcast:31 row_mask:0xc bank_mask:0xf
	s_nop 0
	v_readlane_b32 s50, v74, 63
	s_nop 0
	s_nop 0
	v_writelane_b32 v177, s50, 15
	v_mul_f32_e32 v64, v175, v177
	v_mul_f32_e32 v65, 0x3f3504f3, v64
	v_fma_f32 v66, |v65|, s55, v171
	v_fma_f32 v66, |v65|, v66, s56
	v_fma_f32 v66, |v65|, v66, s57
	v_fma_f32 v66, |v65|, v66, s58
	v_fma_f32 v66, |v65|, v66, s59
	v_fma_f32 v66, |v65|, v66, s60
	v_fma_f32 v66, |v65|, v66, |v65|
	v_mul_f32_e32 v67, 0xbfb8aa3b, v66
	v_fma_f32 v68, v66, s61, -v67
	v_rndne_f32_e32 v69, v67
	v_fmac_f32_e32 v68, 0xb2a5705f, v66
	v_sub_f32_e32 v67, v67, v69
	v_add_f32_e32 v67, v67, v68
	v_exp_f32_e32 v67, v67
	v_cmp_nlt_f32_e32 vcc, s62, v66
	v_cvt_i32_f32_e32 v68, v69
	v_ldexp_f32 v67, v67, v68
	v_cndmask_b32_e32 v67, 0, v67, vcc
	v_cmp_ngt_f32_e32 vcc, s63, v66
	v_mul_f32_e32 v68, v65, v65
	v_fmamk_f32 v69, v68, 0xba1345e1, v169
	v_fmaak_f32 v69, v68, v69, 0xbcdac9b8
	v_cndmask_b32_e32 v66, v172, v67, vcc
	v_fmaak_f32 v69, v68, v69, 0x3de703be
	v_fmaak_f32 v69, v68, v69, 0xbec09330
	v_cmp_nlt_f32_e64 vcc, |v65|, 1.0
	v_fmaak_f32 v68, v68, v69, 0x3e0375d0
	v_sub_f32_e32 v70, 1.0, v66
	v_fma_f32 v71, |v65|, v68, |v65|
	v_cndmask_b32_e32 v70, v71, v70, vcc
	v_bfi_b32 v71, s64, v70, v65
	v_mul_f32_e32 v179, v64, v179
	v_add_f32_e32 v71, 1.0, v71
	v_mul_f32_e32 v179, v179, v71
	s_nop 1
	v_readlane_b32 s100, v122, 6
	v_readlane_b32 s50, v179, 0
	s_lshl_b32 s100, s100, 11
	s_add_u32 s100, s98, s100
	s_addc_u32 s101, s99, 0
	global_load_dwordx4 v[242:245], v178, s[100:101]
	global_load_dwordx4 v[246:249], v178, s[100:101] offset:1024
	s_waitcnt vmcnt(12)
	v_mov_b32_e32 v182, s50
	v_cvt_pk_f32_fp8_e32 v[64:65], v192
	v_cvt_pk_f32_fp8_sdwa v[66:67], v192 src0_sel:WORD_1
	v_cvt_pk_f32_fp8_e32 v[68:69], v193
	v_cvt_pk_f32_fp8_sdwa v[70:71], v193 src0_sel:WORD_1
	v_pk_fma_f32 v[60:61], v[182:183], v[64:65], 0 op_sel_hi:[0,1,0]
	v_pk_fma_f32 v[62:63], v[182:183], v[66:67], 0 op_sel_hi:[0,1,0]
	v_pk_fma_f32 v[56:57], v[182:183], v[68:69], 0 op_sel_hi:[0,1,0]
	v_pk_fma_f32 v[58:59], v[182:183], v[70:71], 0 op_sel_hi:[0,1,0]
	v_cvt_pk_f32_fp8_e32 v[64:65], v194
	v_cvt_pk_f32_fp8_sdwa v[66:67], v194 src0_sel:WORD_1
	v_cvt_pk_f32_fp8_e32 v[68:69], v195
	v_cvt_pk_f32_fp8_sdwa v[70:71], v195 src0_sel:WORD_1
	v_pk_fma_f32 v[52:53], v[182:183], v[64:65], 0 op_sel_hi:[0,1,0]
	v_pk_fma_f32 v[54:55], v[182:183], v[66:67], 0 op_sel_hi:[0,1,0]
	v_pk_fma_f32 v[48:49], v[182:183], v[68:69], 0 op_sel_hi:[0,1,0]
	v_pk_fma_f32 v[50:51], v[182:183], v[70:71], 0 op_sel_hi:[0,1,0]
	v_cvt_pk_f32_fp8_e32 v[64:65], v196
	v_cvt_pk_f32_fp8_sdwa v[66:67], v196 src0_sel:WORD_1
	v_cvt_pk_f32_fp8_e32 v[68:69], v197
	v_cvt_pk_f32_fp8_sdwa v[70:71], v197 src0_sel:WORD_1
	v_pk_fma_f32 v[44:45], v[182:183], v[64:65], 0 op_sel_hi:[0,1,0]
	v_pk_fma_f32 v[46:47], v[182:183], v[66:67], 0 op_sel_hi:[0,1,0]
	v_pk_fma_f32 v[40:41], v[182:183], v[68:69], 0 op_sel_hi:[0,1,0]
	v_pk_fma_f32 v[42:43], v[182:183], v[70:71], 0 op_sel_hi:[0,1,0]
	v_cvt_pk_f32_fp8_e32 v[64:65], v198
	v_cvt_pk_f32_fp8_sdwa v[66:67], v198 src0_sel:WORD_1
	v_cvt_pk_f32_fp8_e32 v[68:69], v199
	v_cvt_pk_f32_fp8_sdwa v[70:71], v199 src0_sel:WORD_1
	v_pk_fma_f32 v[36:37], v[182:183], v[64:65], 0 op_sel_hi:[0,1,0]
	v_pk_fma_f32 v[38:39], v[182:183], v[66:67], 0 op_sel_hi:[0,1,0]
	v_pk_fma_f32 v[32:33], v[182:183], v[68:69], 0 op_sel_hi:[0,1,0]
	v_pk_fma_f32 v[34:35], v[182:183], v[70:71], 0 op_sel_hi:[0,1,0]
	s_nop 1
	v_readlane_b32 s100, v122, 7
	v_readlane_b32 s50, v179, 1
	s_lshl_b32 s100, s100, 11
	s_add_u32 s100, s98, s100
	s_addc_u32 s101, s99, 0
	global_load_dwordx4 v[250:253], v178, s[100:101]
	global_load_dwordx4 v[76:79], v178, s[100:101] offset:1024
	s_waitcnt vmcnt(12)
	v_mov_b32_e32 v182, s50
	v_cvt_pk_f32_fp8_e32 v[64:65], v200
	v_cvt_pk_f32_fp8_sdwa v[66:67], v200 src0_sel:WORD_1
	v_cvt_pk_f32_fp8_e32 v[68:69], v201
	v_cvt_pk_f32_fp8_sdwa v[70:71], v201 src0_sel:WORD_1
	v_pk_fma_f32 v[60:61], v[182:183], v[64:65], v[60:61] op_sel_hi:[0,1,1]
	v_pk_fma_f32 v[62:63], v[182:183], v[66:67], v[62:63] op_sel_hi:[0,1,1]
	v_pk_fma_f32 v[56:57], v[182:183], v[68:69], v[56:57] op_sel_hi:[0,1,1]
	v_pk_fma_f32 v[58:59], v[182:183], v[70:71], v[58:59] op_sel_hi:[0,1,1]
	v_cvt_pk_f32_fp8_e32 v[64:65], v202
	v_cvt_pk_f32_fp8_sdwa v[66:67], v202 src0_sel:WORD_1
	v_cvt_pk_f32_fp8_e32 v[68:69], v203
	v_cvt_pk_f32_fp8_sdwa v[70:71], v203 src0_sel:WORD_1
	v_pk_fma_f32 v[52:53], v[182:183], v[64:65], v[52:53] op_sel_hi:[0,1,1]
	v_pk_fma_f32 v[54:55], v[182:183], v[66:67], v[54:55] op_sel_hi:[0,1,1]
	v_pk_fma_f32 v[48:49], v[182:183], v[68:69], v[48:49] op_sel_hi:[0,1,1]
	v_pk_fma_f32 v[50:51], v[182:183], v[70:71], v[50:51] op_sel_hi:[0,1,1]
	v_cvt_pk_f32_fp8_e32 v[64:65], v204
	v_cvt_pk_f32_fp8_sdwa v[66:67], v204 src0_sel:WORD_1
	v_cvt_pk_f32_fp8_e32 v[68:69], v205
	v_cvt_pk_f32_fp8_sdwa v[70:71], v205 src0_sel:WORD_1
	v_pk_fma_f32 v[44:45], v[182:183], v[64:65], v[44:45] op_sel_hi:[0,1,1]
	v_pk_fma_f32 v[46:47], v[182:183], v[66:67], v[46:47] op_sel_hi:[0,1,1]
	v_pk_fma_f32 v[40:41], v[182:183], v[68:69], v[40:41] op_sel_hi:[0,1,1]
	v_pk_fma_f32 v[42:43], v[182:183], v[70:71], v[42:43] op_sel_hi:[0,1,1]
	v_cvt_pk_f32_fp8_e32 v[64:65], v206
	v_cvt_pk_f32_fp8_sdwa v[66:67], v206 src0_sel:WORD_1
	v_cvt_pk_f32_fp8_e32 v[68:69], v207
	v_cvt_pk_f32_fp8_sdwa v[70:71], v207 src0_sel:WORD_1
	v_pk_fma_f32 v[36:37], v[182:183], v[64:65], v[36:37] op_sel_hi:[0,1,1]
	v_pk_fma_f32 v[38:39], v[182:183], v[66:67], v[38:39] op_sel_hi:[0,1,1]
	v_pk_fma_f32 v[32:33], v[182:183], v[68:69], v[32:33] op_sel_hi:[0,1,1]
	v_pk_fma_f32 v[34:35], v[182:183], v[70:71], v[34:35] op_sel_hi:[0,1,1]
	s_nop 1
	v_readlane_b32 s100, v122, 8
	v_readlane_b32 s50, v179, 2
	s_lshl_b32 s100, s100, 11
	s_add_u32 s100, s98, s100
	s_addc_u32 s101, s99, 0
	global_load_dwordx4 v[192:195], v178, s[100:101]
	global_load_dwordx4 v[196:199], v178, s[100:101] offset:1024
	s_waitcnt vmcnt(12)
	v_mov_b32_e32 v182, s50
	v_cvt_pk_f32_fp8_e32 v[64:65], v208
	v_cvt_pk_f32_fp8_sdwa v[66:67], v208 src0_sel:WORD_1
	v_cvt_pk_f32_fp8_e32 v[68:69], v209
	v_cvt_pk_f32_fp8_sdwa v[70:71], v209 src0_sel:WORD_1
	v_pk_fma_f32 v[60:61], v[182:183], v[64:65], v[60:61] op_sel_hi:[0,1,1]
	v_pk_fma_f32 v[62:63], v[182:183], v[66:67], v[62:63] op_sel_hi:[0,1,1]
	v_pk_fma_f32 v[56:57], v[182:183], v[68:69], v[56:57] op_sel_hi:[0,1,1]
	v_pk_fma_f32 v[58:59], v[182:183], v[70:71], v[58:59] op_sel_hi:[0,1,1]
	v_cvt_pk_f32_fp8_e32 v[64:65], v210
	v_cvt_pk_f32_fp8_sdwa v[66:67], v210 src0_sel:WORD_1
	v_cvt_pk_f32_fp8_e32 v[68:69], v211
	v_cvt_pk_f32_fp8_sdwa v[70:71], v211 src0_sel:WORD_1
	v_pk_fma_f32 v[52:53], v[182:183], v[64:65], v[52:53] op_sel_hi:[0,1,1]
	v_pk_fma_f32 v[54:55], v[182:183], v[66:67], v[54:55] op_sel_hi:[0,1,1]
	v_pk_fma_f32 v[48:49], v[182:183], v[68:69], v[48:49] op_sel_hi:[0,1,1]
	v_pk_fma_f32 v[50:51], v[182:183], v[70:71], v[50:51] op_sel_hi:[0,1,1]
	v_cvt_pk_f32_fp8_e32 v[64:65], v212
	v_cvt_pk_f32_fp8_sdwa v[66:67], v212 src0_sel:WORD_1
	v_cvt_pk_f32_fp8_e32 v[68:69], v213
	v_cvt_pk_f32_fp8_sdwa v[70:71], v213 src0_sel:WORD_1
	v_pk_fma_f32 v[44:45], v[182:183], v[64:65], v[44:45] op_sel_hi:[0,1,1]
	v_pk_fma_f32 v[46:47], v[182:183], v[66:67], v[46:47] op_sel_hi:[0,1,1]
	v_pk_fma_f32 v[40:41], v[182:183], v[68:69], v[40:41] op_sel_hi:[0,1,1]
	v_pk_fma_f32 v[42:43], v[182:183], v[70:71], v[42:43] op_sel_hi:[0,1,1]
	v_cvt_pk_f32_fp8_e32 v[64:65], v214
	v_cvt_pk_f32_fp8_sdwa v[66:67], v214 src0_sel:WORD_1
	v_cvt_pk_f32_fp8_e32 v[68:69], v215
	v_cvt_pk_f32_fp8_sdwa v[70:71], v215 src0_sel:WORD_1
	v_pk_fma_f32 v[36:37], v[182:183], v[64:65], v[36:37] op_sel_hi:[0,1,1]
	v_pk_fma_f32 v[38:39], v[182:183], v[66:67], v[38:39] op_sel_hi:[0,1,1]
	v_pk_fma_f32 v[32:33], v[182:183], v[68:69], v[32:33] op_sel_hi:[0,1,1]
	v_pk_fma_f32 v[34:35], v[182:183], v[70:71], v[34:35] op_sel_hi:[0,1,1]
	s_nop 1
	v_readlane_b32 s100, v122, 9
	v_readlane_b32 s50, v179, 3
	s_lshl_b32 s100, s100, 11
	s_add_u32 s100, s98, s100
	s_addc_u32 s101, s99, 0
	global_load_dwordx4 v[200:203], v178, s[100:101]
	global_load_dwordx4 v[204:207], v178, s[100:101] offset:1024
	s_waitcnt vmcnt(12)
	v_mov_b32_e32 v182, s50
	v_cvt_pk_f32_fp8_e32 v[64:65], v216
	v_cvt_pk_f32_fp8_sdwa v[66:67], v216 src0_sel:WORD_1
	v_cvt_pk_f32_fp8_e32 v[68:69], v217
	v_cvt_pk_f32_fp8_sdwa v[70:71], v217 src0_sel:WORD_1
	v_pk_fma_f32 v[60:61], v[182:183], v[64:65], v[60:61] op_sel_hi:[0,1,1]
	v_pk_fma_f32 v[62:63], v[182:183], v[66:67], v[62:63] op_sel_hi:[0,1,1]
	v_pk_fma_f32 v[56:57], v[182:183], v[68:69], v[56:57] op_sel_hi:[0,1,1]
	v_pk_fma_f32 v[58:59], v[182:183], v[70:71], v[58:59] op_sel_hi:[0,1,1]
	v_cvt_pk_f32_fp8_e32 v[64:65], v218
	v_cvt_pk_f32_fp8_sdwa v[66:67], v218 src0_sel:WORD_1
	v_cvt_pk_f32_fp8_e32 v[68:69], v219
	v_cvt_pk_f32_fp8_sdwa v[70:71], v219 src0_sel:WORD_1
	v_pk_fma_f32 v[52:53], v[182:183], v[64:65], v[52:53] op_sel_hi:[0,1,1]
	v_pk_fma_f32 v[54:55], v[182:183], v[66:67], v[54:55] op_sel_hi:[0,1,1]
	v_pk_fma_f32 v[48:49], v[182:183], v[68:69], v[48:49] op_sel_hi:[0,1,1]
	v_pk_fma_f32 v[50:51], v[182:183], v[70:71], v[50:51] op_sel_hi:[0,1,1]
	v_cvt_pk_f32_fp8_e32 v[64:65], v220
	v_cvt_pk_f32_fp8_sdwa v[66:67], v220 src0_sel:WORD_1
	v_cvt_pk_f32_fp8_e32 v[68:69], v221
	v_cvt_pk_f32_fp8_sdwa v[70:71], v221 src0_sel:WORD_1
	v_pk_fma_f32 v[44:45], v[182:183], v[64:65], v[44:45] op_sel_hi:[0,1,1]
	v_pk_fma_f32 v[46:47], v[182:183], v[66:67], v[46:47] op_sel_hi:[0,1,1]
	v_pk_fma_f32 v[40:41], v[182:183], v[68:69], v[40:41] op_sel_hi:[0,1,1]
	v_pk_fma_f32 v[42:43], v[182:183], v[70:71], v[42:43] op_sel_hi:[0,1,1]
	v_cvt_pk_f32_fp8_e32 v[64:65], v222
	v_cvt_pk_f32_fp8_sdwa v[66:67], v222 src0_sel:WORD_1
	v_cvt_pk_f32_fp8_e32 v[68:69], v223
	v_cvt_pk_f32_fp8_sdwa v[70:71], v223 src0_sel:WORD_1
	v_pk_fma_f32 v[36:37], v[182:183], v[64:65], v[36:37] op_sel_hi:[0,1,1]
	v_pk_fma_f32 v[38:39], v[182:183], v[66:67], v[38:39] op_sel_hi:[0,1,1]
	v_pk_fma_f32 v[32:33], v[182:183], v[68:69], v[32:33] op_sel_hi:[0,1,1]
	v_pk_fma_f32 v[34:35], v[182:183], v[70:71], v[34:35] op_sel_hi:[0,1,1]
	s_nop 1
	v_readlane_b32 s100, v122, 10
	v_readlane_b32 s50, v179, 4
	s_lshl_b32 s100, s100, 11
	s_add_u32 s100, s98, s100
	s_addc_u32 s101, s99, 0
	global_load_dwordx4 v[208:211], v178, s[100:101]
	global_load_dwordx4 v[212:215], v178, s[100:101] offset:1024
	s_waitcnt vmcnt(12)
	v_mov_b32_e32 v182, s50
	v_cvt_pk_f32_fp8_e32 v[64:65], v224
	v_cvt_pk_f32_fp8_sdwa v[66:67], v224 src0_sel:WORD_1
	v_cvt_pk_f32_fp8_e32 v[68:69], v225
	v_cvt_pk_f32_fp8_sdwa v[70:71], v225 src0_sel:WORD_1
	v_pk_fma_f32 v[60:61], v[182:183], v[64:65], v[60:61] op_sel_hi:[0,1,1]
	v_pk_fma_f32 v[62:63], v[182:183], v[66:67], v[62:63] op_sel_hi:[0,1,1]
	v_pk_fma_f32 v[56:57], v[182:183], v[68:69], v[56:57] op_sel_hi:[0,1,1]
	v_pk_fma_f32 v[58:59], v[182:183], v[70:71], v[58:59] op_sel_hi:[0,1,1]
	v_cvt_pk_f32_fp8_e32 v[64:65], v226
	v_cvt_pk_f32_fp8_sdwa v[66:67], v226 src0_sel:WORD_1
	v_cvt_pk_f32_fp8_e32 v[68:69], v227
	v_cvt_pk_f32_fp8_sdwa v[70:71], v227 src0_sel:WORD_1
	v_pk_fma_f32 v[52:53], v[182:183], v[64:65], v[52:53] op_sel_hi:[0,1,1]
	v_pk_fma_f32 v[54:55], v[182:183], v[66:67], v[54:55] op_sel_hi:[0,1,1]
	v_pk_fma_f32 v[48:49], v[182:183], v[68:69], v[48:49] op_sel_hi:[0,1,1]
	v_pk_fma_f32 v[50:51], v[182:183], v[70:71], v[50:51] op_sel_hi:[0,1,1]
	v_cvt_pk_f32_fp8_e32 v[64:65], v228
	v_cvt_pk_f32_fp8_sdwa v[66:67], v228 src0_sel:WORD_1
	v_cvt_pk_f32_fp8_e32 v[68:69], v229
	v_cvt_pk_f32_fp8_sdwa v[70:71], v229 src0_sel:WORD_1
	v_pk_fma_f32 v[44:45], v[182:183], v[64:65], v[44:45] op_sel_hi:[0,1,1]
	v_pk_fma_f32 v[46:47], v[182:183], v[66:67], v[46:47] op_sel_hi:[0,1,1]
	v_pk_fma_f32 v[40:41], v[182:183], v[68:69], v[40:41] op_sel_hi:[0,1,1]
	v_pk_fma_f32 v[42:43], v[182:183], v[70:71], v[42:43] op_sel_hi:[0,1,1]
	v_cvt_pk_f32_fp8_e32 v[64:65], v230
	v_cvt_pk_f32_fp8_sdwa v[66:67], v230 src0_sel:WORD_1
	v_cvt_pk_f32_fp8_e32 v[68:69], v231
	v_cvt_pk_f32_fp8_sdwa v[70:71], v231 src0_sel:WORD_1
	v_pk_fma_f32 v[36:37], v[182:183], v[64:65], v[36:37] op_sel_hi:[0,1,1]
	v_pk_fma_f32 v[38:39], v[182:183], v[66:67], v[38:39] op_sel_hi:[0,1,1]
	v_pk_fma_f32 v[32:33], v[182:183], v[68:69], v[32:33] op_sel_hi:[0,1,1]
	v_pk_fma_f32 v[34:35], v[182:183], v[70:71], v[34:35] op_sel_hi:[0,1,1]
	s_nop 1
	v_readlane_b32 s100, v122, 11
	v_readlane_b32 s50, v179, 5
	s_lshl_b32 s100, s100, 11
	s_add_u32 s100, s98, s100
	s_addc_u32 s101, s99, 0
	global_load_dwordx4 v[216:219], v178, s[100:101]
	global_load_dwordx4 v[220:223], v178, s[100:101] offset:1024
	s_waitcnt vmcnt(12)
	v_mov_b32_e32 v182, s50
	v_cvt_pk_f32_fp8_e32 v[64:65], v232
	v_cvt_pk_f32_fp8_sdwa v[66:67], v232 src0_sel:WORD_1
	v_cvt_pk_f32_fp8_e32 v[68:69], v233
	v_cvt_pk_f32_fp8_sdwa v[70:71], v233 src0_sel:WORD_1
	v_pk_fma_f32 v[60:61], v[182:183], v[64:65], v[60:61] op_sel_hi:[0,1,1]
	v_pk_fma_f32 v[62:63], v[182:183], v[66:67], v[62:63] op_sel_hi:[0,1,1]
	v_pk_fma_f32 v[56:57], v[182:183], v[68:69], v[56:57] op_sel_hi:[0,1,1]
	v_pk_fma_f32 v[58:59], v[182:183], v[70:71], v[58:59] op_sel_hi:[0,1,1]
	v_cvt_pk_f32_fp8_e32 v[64:65], v234
	v_cvt_pk_f32_fp8_sdwa v[66:67], v234 src0_sel:WORD_1
	v_cvt_pk_f32_fp8_e32 v[68:69], v235
	v_cvt_pk_f32_fp8_sdwa v[70:71], v235 src0_sel:WORD_1
	v_pk_fma_f32 v[52:53], v[182:183], v[64:65], v[52:53] op_sel_hi:[0,1,1]
	v_pk_fma_f32 v[54:55], v[182:183], v[66:67], v[54:55] op_sel_hi:[0,1,1]
	v_pk_fma_f32 v[48:49], v[182:183], v[68:69], v[48:49] op_sel_hi:[0,1,1]
	v_pk_fma_f32 v[50:51], v[182:183], v[70:71], v[50:51] op_sel_hi:[0,1,1]
	v_cvt_pk_f32_fp8_e32 v[64:65], v236
	v_cvt_pk_f32_fp8_sdwa v[66:67], v236 src0_sel:WORD_1
	v_cvt_pk_f32_fp8_e32 v[68:69], v237
	v_cvt_pk_f32_fp8_sdwa v[70:71], v237 src0_sel:WORD_1
	v_pk_fma_f32 v[44:45], v[182:183], v[64:65], v[44:45] op_sel_hi:[0,1,1]
	v_pk_fma_f32 v[46:47], v[182:183], v[66:67], v[46:47] op_sel_hi:[0,1,1]
	v_pk_fma_f32 v[40:41], v[182:183], v[68:69], v[40:41] op_sel_hi:[0,1,1]
	v_pk_fma_f32 v[42:43], v[182:183], v[70:71], v[42:43] op_sel_hi:[0,1,1]
	v_cvt_pk_f32_fp8_e32 v[64:65], v238
	v_cvt_pk_f32_fp8_sdwa v[66:67], v238 src0_sel:WORD_1
	v_cvt_pk_f32_fp8_e32 v[68:69], v239
	v_cvt_pk_f32_fp8_sdwa v[70:71], v239 src0_sel:WORD_1
	v_pk_fma_f32 v[36:37], v[182:183], v[64:65], v[36:37] op_sel_hi:[0,1,1]
	v_pk_fma_f32 v[38:39], v[182:183], v[66:67], v[38:39] op_sel_hi:[0,1,1]
	v_pk_fma_f32 v[32:33], v[182:183], v[68:69], v[32:33] op_sel_hi:[0,1,1]
	v_pk_fma_f32 v[34:35], v[182:183], v[70:71], v[34:35] op_sel_hi:[0,1,1]
	s_nop 1
	v_readlane_b32 s100, v122, 12
	v_readlane_b32 s50, v179, 6
	s_lshl_b32 s100, s100, 11
	s_add_u32 s100, s98, s100
	s_addc_u32 s101, s99, 0
	global_load_dwordx4 v[224:227], v178, s[100:101]
	global_load_dwordx4 v[228:231], v178, s[100:101] offset:1024
	s_waitcnt vmcnt(12)
	v_mov_b32_e32 v182, s50
	v_cvt_pk_f32_fp8_e32 v[64:65], v242
	v_cvt_pk_f32_fp8_sdwa v[66:67], v242 src0_sel:WORD_1
	v_cvt_pk_f32_fp8_e32 v[68:69], v243
	v_cvt_pk_f32_fp8_sdwa v[70:71], v243 src0_sel:WORD_1
	v_pk_fma_f32 v[60:61], v[182:183], v[64:65], v[60:61] op_sel_hi:[0,1,1]
	v_pk_fma_f32 v[62:63], v[182:183], v[66:67], v[62:63] op_sel_hi:[0,1,1]
	v_pk_fma_f32 v[56:57], v[182:183], v[68:69], v[56:57] op_sel_hi:[0,1,1]
	v_pk_fma_f32 v[58:59], v[182:183], v[70:71], v[58:59] op_sel_hi:[0,1,1]
	v_cvt_pk_f32_fp8_e32 v[64:65], v244
	v_cvt_pk_f32_fp8_sdwa v[66:67], v244 src0_sel:WORD_1
	v_cvt_pk_f32_fp8_e32 v[68:69], v245
	v_cvt_pk_f32_fp8_sdwa v[70:71], v245 src0_sel:WORD_1
	v_pk_fma_f32 v[52:53], v[182:183], v[64:65], v[52:53] op_sel_hi:[0,1,1]
	v_pk_fma_f32 v[54:55], v[182:183], v[66:67], v[54:55] op_sel_hi:[0,1,1]
	v_pk_fma_f32 v[48:49], v[182:183], v[68:69], v[48:49] op_sel_hi:[0,1,1]
	v_pk_fma_f32 v[50:51], v[182:183], v[70:71], v[50:51] op_sel_hi:[0,1,1]
	v_cvt_pk_f32_fp8_e32 v[64:65], v246
	v_cvt_pk_f32_fp8_sdwa v[66:67], v246 src0_sel:WORD_1
	v_cvt_pk_f32_fp8_e32 v[68:69], v247
	v_cvt_pk_f32_fp8_sdwa v[70:71], v247 src0_sel:WORD_1
	v_pk_fma_f32 v[44:45], v[182:183], v[64:65], v[44:45] op_sel_hi:[0,1,1]
	v_pk_fma_f32 v[46:47], v[182:183], v[66:67], v[46:47] op_sel_hi:[0,1,1]
	v_pk_fma_f32 v[40:41], v[182:183], v[68:69], v[40:41] op_sel_hi:[0,1,1]
	v_pk_fma_f32 v[42:43], v[182:183], v[70:71], v[42:43] op_sel_hi:[0,1,1]
	v_cvt_pk_f32_fp8_e32 v[64:65], v248
	v_cvt_pk_f32_fp8_sdwa v[66:67], v248 src0_sel:WORD_1
	v_cvt_pk_f32_fp8_e32 v[68:69], v249
	v_cvt_pk_f32_fp8_sdwa v[70:71], v249 src0_sel:WORD_1
	v_pk_fma_f32 v[36:37], v[182:183], v[64:65], v[36:37] op_sel_hi:[0,1,1]
	v_pk_fma_f32 v[38:39], v[182:183], v[66:67], v[38:39] op_sel_hi:[0,1,1]
	v_pk_fma_f32 v[32:33], v[182:183], v[68:69], v[32:33] op_sel_hi:[0,1,1]
	v_pk_fma_f32 v[34:35], v[182:183], v[70:71], v[34:35] op_sel_hi:[0,1,1]
	s_nop 1
	v_readlane_b32 s100, v122, 13
	v_readlane_b32 s50, v179, 7
	s_lshl_b32 s100, s100, 11
	s_add_u32 s100, s98, s100
	s_addc_u32 s101, s99, 0
	global_load_dwordx4 v[232:235], v178, s[100:101]
	global_load_dwordx4 v[236:239], v178, s[100:101] offset:1024
	s_waitcnt vmcnt(12)
	v_mov_b32_e32 v182, s50
	v_cvt_pk_f32_fp8_e32 v[64:65], v250
	v_cvt_pk_f32_fp8_sdwa v[66:67], v250 src0_sel:WORD_1
	v_cvt_pk_f32_fp8_e32 v[68:69], v251
	v_cvt_pk_f32_fp8_sdwa v[70:71], v251 src0_sel:WORD_1
	v_pk_fma_f32 v[60:61], v[182:183], v[64:65], v[60:61] op_sel_hi:[0,1,1]
	v_pk_fma_f32 v[62:63], v[182:183], v[66:67], v[62:63] op_sel_hi:[0,1,1]
	v_pk_fma_f32 v[56:57], v[182:183], v[68:69], v[56:57] op_sel_hi:[0,1,1]
	v_pk_fma_f32 v[58:59], v[182:183], v[70:71], v[58:59] op_sel_hi:[0,1,1]
	v_cvt_pk_f32_fp8_e32 v[64:65], v252
	v_cvt_pk_f32_fp8_sdwa v[66:67], v252 src0_sel:WORD_1
	v_cvt_pk_f32_fp8_e32 v[68:69], v253
	v_cvt_pk_f32_fp8_sdwa v[70:71], v253 src0_sel:WORD_1
	v_pk_fma_f32 v[52:53], v[182:183], v[64:65], v[52:53] op_sel_hi:[0,1,1]
	v_pk_fma_f32 v[54:55], v[182:183], v[66:67], v[54:55] op_sel_hi:[0,1,1]
	v_pk_fma_f32 v[48:49], v[182:183], v[68:69], v[48:49] op_sel_hi:[0,1,1]
	v_pk_fma_f32 v[50:51], v[182:183], v[70:71], v[50:51] op_sel_hi:[0,1,1]
	v_cvt_pk_f32_fp8_e32 v[64:65], v76
	v_cvt_pk_f32_fp8_sdwa v[66:67], v76 src0_sel:WORD_1
	v_cvt_pk_f32_fp8_e32 v[68:69], v77
	v_cvt_pk_f32_fp8_sdwa v[70:71], v77 src0_sel:WORD_1
	v_pk_fma_f32 v[44:45], v[182:183], v[64:65], v[44:45] op_sel_hi:[0,1,1]
	v_pk_fma_f32 v[46:47], v[182:183], v[66:67], v[46:47] op_sel_hi:[0,1,1]
	v_pk_fma_f32 v[40:41], v[182:183], v[68:69], v[40:41] op_sel_hi:[0,1,1]
	v_pk_fma_f32 v[42:43], v[182:183], v[70:71], v[42:43] op_sel_hi:[0,1,1]
	v_cvt_pk_f32_fp8_e32 v[64:65], v78
	v_cvt_pk_f32_fp8_sdwa v[66:67], v78 src0_sel:WORD_1
	v_cvt_pk_f32_fp8_e32 v[68:69], v79
	v_cvt_pk_f32_fp8_sdwa v[70:71], v79 src0_sel:WORD_1
	v_pk_fma_f32 v[36:37], v[182:183], v[64:65], v[36:37] op_sel_hi:[0,1,1]
	v_pk_fma_f32 v[38:39], v[182:183], v[66:67], v[38:39] op_sel_hi:[0,1,1]
	v_pk_fma_f32 v[32:33], v[182:183], v[68:69], v[32:33] op_sel_hi:[0,1,1]
	v_pk_fma_f32 v[34:35], v[182:183], v[70:71], v[34:35] op_sel_hi:[0,1,1]
	s_nop 1
	v_readlane_b32 s100, v122, 14
	v_readlane_b32 s50, v179, 8
	s_lshl_b32 s100, s100, 11
	s_add_u32 s100, s98, s100
	s_addc_u32 s101, s99, 0
	global_load_dwordx4 v[242:245], v178, s[100:101]
	global_load_dwordx4 v[246:249], v178, s[100:101] offset:1024
	s_waitcnt vmcnt(12)
	v_mov_b32_e32 v182, s50
	v_cvt_pk_f32_fp8_e32 v[64:65], v192
	v_cvt_pk_f32_fp8_sdwa v[66:67], v192 src0_sel:WORD_1
	v_cvt_pk_f32_fp8_e32 v[68:69], v193
	v_cvt_pk_f32_fp8_sdwa v[70:71], v193 src0_sel:WORD_1
	v_pk_fma_f32 v[60:61], v[182:183], v[64:65], v[60:61] op_sel_hi:[0,1,1]
	v_pk_fma_f32 v[62:63], v[182:183], v[66:67], v[62:63] op_sel_hi:[0,1,1]
	v_pk_fma_f32 v[56:57], v[182:183], v[68:69], v[56:57] op_sel_hi:[0,1,1]
	v_pk_fma_f32 v[58:59], v[182:183], v[70:71], v[58:59] op_sel_hi:[0,1,1]
	v_cvt_pk_f32_fp8_e32 v[64:65], v194
	v_cvt_pk_f32_fp8_sdwa v[66:67], v194 src0_sel:WORD_1
	v_cvt_pk_f32_fp8_e32 v[68:69], v195
	v_cvt_pk_f32_fp8_sdwa v[70:71], v195 src0_sel:WORD_1
	v_pk_fma_f32 v[52:53], v[182:183], v[64:65], v[52:53] op_sel_hi:[0,1,1]
	v_pk_fma_f32 v[54:55], v[182:183], v[66:67], v[54:55] op_sel_hi:[0,1,1]
	v_pk_fma_f32 v[48:49], v[182:183], v[68:69], v[48:49] op_sel_hi:[0,1,1]
	v_pk_fma_f32 v[50:51], v[182:183], v[70:71], v[50:51] op_sel_hi:[0,1,1]
	v_cvt_pk_f32_fp8_e32 v[64:65], v196
	v_cvt_pk_f32_fp8_sdwa v[66:67], v196 src0_sel:WORD_1
	v_cvt_pk_f32_fp8_e32 v[68:69], v197
	v_cvt_pk_f32_fp8_sdwa v[70:71], v197 src0_sel:WORD_1
	v_pk_fma_f32 v[44:45], v[182:183], v[64:65], v[44:45] op_sel_hi:[0,1,1]
	v_pk_fma_f32 v[46:47], v[182:183], v[66:67], v[46:47] op_sel_hi:[0,1,1]
	v_pk_fma_f32 v[40:41], v[182:183], v[68:69], v[40:41] op_sel_hi:[0,1,1]
	v_pk_fma_f32 v[42:43], v[182:183], v[70:71], v[42:43] op_sel_hi:[0,1,1]
	v_cvt_pk_f32_fp8_e32 v[64:65], v198
	v_cvt_pk_f32_fp8_sdwa v[66:67], v198 src0_sel:WORD_1
	v_cvt_pk_f32_fp8_e32 v[68:69], v199
	v_cvt_pk_f32_fp8_sdwa v[70:71], v199 src0_sel:WORD_1
	v_pk_fma_f32 v[36:37], v[182:183], v[64:65], v[36:37] op_sel_hi:[0,1,1]
	v_pk_fma_f32 v[38:39], v[182:183], v[66:67], v[38:39] op_sel_hi:[0,1,1]
	v_pk_fma_f32 v[32:33], v[182:183], v[68:69], v[32:33] op_sel_hi:[0,1,1]
	v_pk_fma_f32 v[34:35], v[182:183], v[70:71], v[34:35] op_sel_hi:[0,1,1]
	s_nop 1
	v_readlane_b32 s100, v122, 15
	v_readlane_b32 s50, v179, 9
	s_lshl_b32 s100, s100, 11
	s_add_u32 s100, s98, s100
	s_addc_u32 s101, s99, 0
	global_load_dwordx4 v[250:253], v178, s[100:101]
	global_load_dwordx4 v[76:79], v178, s[100:101] offset:1024
	s_waitcnt vmcnt(12)
	v_mov_b32_e32 v182, s50
	v_cvt_pk_f32_fp8_e32 v[64:65], v200
	v_cvt_pk_f32_fp8_sdwa v[66:67], v200 src0_sel:WORD_1
	v_cvt_pk_f32_fp8_e32 v[68:69], v201
	v_cvt_pk_f32_fp8_sdwa v[70:71], v201 src0_sel:WORD_1
	v_pk_fma_f32 v[60:61], v[182:183], v[64:65], v[60:61] op_sel_hi:[0,1,1]
	v_pk_fma_f32 v[62:63], v[182:183], v[66:67], v[62:63] op_sel_hi:[0,1,1]
	v_pk_fma_f32 v[56:57], v[182:183], v[68:69], v[56:57] op_sel_hi:[0,1,1]
	v_pk_fma_f32 v[58:59], v[182:183], v[70:71], v[58:59] op_sel_hi:[0,1,1]
	v_cvt_pk_f32_fp8_e32 v[64:65], v202
	v_cvt_pk_f32_fp8_sdwa v[66:67], v202 src0_sel:WORD_1
	v_cvt_pk_f32_fp8_e32 v[68:69], v203
	v_cvt_pk_f32_fp8_sdwa v[70:71], v203 src0_sel:WORD_1
	v_pk_fma_f32 v[52:53], v[182:183], v[64:65], v[52:53] op_sel_hi:[0,1,1]
	v_pk_fma_f32 v[54:55], v[182:183], v[66:67], v[54:55] op_sel_hi:[0,1,1]
	v_pk_fma_f32 v[48:49], v[182:183], v[68:69], v[48:49] op_sel_hi:[0,1,1]
	v_pk_fma_f32 v[50:51], v[182:183], v[70:71], v[50:51] op_sel_hi:[0,1,1]
	v_cvt_pk_f32_fp8_e32 v[64:65], v204
	v_cvt_pk_f32_fp8_sdwa v[66:67], v204 src0_sel:WORD_1
	v_cvt_pk_f32_fp8_e32 v[68:69], v205
	v_cvt_pk_f32_fp8_sdwa v[70:71], v205 src0_sel:WORD_1
	v_pk_fma_f32 v[44:45], v[182:183], v[64:65], v[44:45] op_sel_hi:[0,1,1]
	v_pk_fma_f32 v[46:47], v[182:183], v[66:67], v[46:47] op_sel_hi:[0,1,1]
	v_pk_fma_f32 v[40:41], v[182:183], v[68:69], v[40:41] op_sel_hi:[0,1,1]
	v_pk_fma_f32 v[42:43], v[182:183], v[70:71], v[42:43] op_sel_hi:[0,1,1]
	v_cvt_pk_f32_fp8_e32 v[64:65], v206
	v_cvt_pk_f32_fp8_sdwa v[66:67], v206 src0_sel:WORD_1
	v_cvt_pk_f32_fp8_e32 v[68:69], v207
	v_cvt_pk_f32_fp8_sdwa v[70:71], v207 src0_sel:WORD_1
	v_pk_fma_f32 v[36:37], v[182:183], v[64:65], v[36:37] op_sel_hi:[0,1,1]
	v_pk_fma_f32 v[38:39], v[182:183], v[66:67], v[38:39] op_sel_hi:[0,1,1]
	v_pk_fma_f32 v[32:33], v[182:183], v[68:69], v[32:33] op_sel_hi:[0,1,1]
	v_pk_fma_f32 v[34:35], v[182:183], v[70:71], v[34:35] op_sel_hi:[0,1,1]
	s_nop 1
	v_readlane_b32 s100, v174, 0
	v_readlane_b32 s50, v179, 10
	s_lshl_b32 s100, s100, 11
	s_add_u32 s100, s96, s100
	s_addc_u32 s101, s97, 0
	global_load_dwordx4 v[0:3], v178, s[100:101]
	global_load_dwordx4 v[4:7], v178, s[100:101] offset:1024
	s_waitcnt vmcnt(12)
	v_mov_b32_e32 v182, s50
	v_cvt_pk_f32_fp8_e32 v[64:65], v208
	v_cvt_pk_f32_fp8_sdwa v[66:67], v208 src0_sel:WORD_1
	v_cvt_pk_f32_fp8_e32 v[68:69], v209
	v_cvt_pk_f32_fp8_sdwa v[70:71], v209 src0_sel:WORD_1
	v_pk_fma_f32 v[60:61], v[182:183], v[64:65], v[60:61] op_sel_hi:[0,1,1]
	v_pk_fma_f32 v[62:63], v[182:183], v[66:67], v[62:63] op_sel_hi:[0,1,1]
	v_pk_fma_f32 v[56:57], v[182:183], v[68:69], v[56:57] op_sel_hi:[0,1,1]
	v_pk_fma_f32 v[58:59], v[182:183], v[70:71], v[58:59] op_sel_hi:[0,1,1]
	v_cvt_pk_f32_fp8_e32 v[64:65], v210
	v_cvt_pk_f32_fp8_sdwa v[66:67], v210 src0_sel:WORD_1
	v_cvt_pk_f32_fp8_e32 v[68:69], v211
	v_cvt_pk_f32_fp8_sdwa v[70:71], v211 src0_sel:WORD_1
	v_pk_fma_f32 v[52:53], v[182:183], v[64:65], v[52:53] op_sel_hi:[0,1,1]
	v_pk_fma_f32 v[54:55], v[182:183], v[66:67], v[54:55] op_sel_hi:[0,1,1]
	v_pk_fma_f32 v[48:49], v[182:183], v[68:69], v[48:49] op_sel_hi:[0,1,1]
	v_pk_fma_f32 v[50:51], v[182:183], v[70:71], v[50:51] op_sel_hi:[0,1,1]
	v_cvt_pk_f32_fp8_e32 v[64:65], v212
	v_cvt_pk_f32_fp8_sdwa v[66:67], v212 src0_sel:WORD_1
	v_cvt_pk_f32_fp8_e32 v[68:69], v213
	v_cvt_pk_f32_fp8_sdwa v[70:71], v213 src0_sel:WORD_1
	v_pk_fma_f32 v[44:45], v[182:183], v[64:65], v[44:45] op_sel_hi:[0,1,1]
	v_pk_fma_f32 v[46:47], v[182:183], v[66:67], v[46:47] op_sel_hi:[0,1,1]
	v_pk_fma_f32 v[40:41], v[182:183], v[68:69], v[40:41] op_sel_hi:[0,1,1]
	v_pk_fma_f32 v[42:43], v[182:183], v[70:71], v[42:43] op_sel_hi:[0,1,1]
	v_cvt_pk_f32_fp8_e32 v[64:65], v214
	v_cvt_pk_f32_fp8_sdwa v[66:67], v214 src0_sel:WORD_1
	v_cvt_pk_f32_fp8_e32 v[68:69], v215
	v_cvt_pk_f32_fp8_sdwa v[70:71], v215 src0_sel:WORD_1
	v_pk_fma_f32 v[36:37], v[182:183], v[64:65], v[36:37] op_sel_hi:[0,1,1]
	v_pk_fma_f32 v[38:39], v[182:183], v[66:67], v[38:39] op_sel_hi:[0,1,1]
	v_pk_fma_f32 v[32:33], v[182:183], v[68:69], v[32:33] op_sel_hi:[0,1,1]
	v_pk_fma_f32 v[34:35], v[182:183], v[70:71], v[34:35] op_sel_hi:[0,1,1]
	s_nop 1
	v_readlane_b32 s100, v174, 1
	v_readlane_b32 s50, v179, 11
	s_lshl_b32 s100, s100, 11
	s_add_u32 s100, s96, s100
	s_addc_u32 s101, s97, 0
	global_load_dwordx4 v[8:11], v178, s[100:101]
	global_load_dwordx4 v[16:19], v178, s[100:101] offset:1024
	s_waitcnt vmcnt(12)
	v_mov_b32_e32 v182, s50
	v_cvt_pk_f32_fp8_e32 v[64:65], v216
	v_cvt_pk_f32_fp8_sdwa v[66:67], v216 src0_sel:WORD_1
	v_cvt_pk_f32_fp8_e32 v[68:69], v217
	v_cvt_pk_f32_fp8_sdwa v[70:71], v217 src0_sel:WORD_1
	v_pk_fma_f32 v[60:61], v[182:183], v[64:65], v[60:61] op_sel_hi:[0,1,1]
	v_pk_fma_f32 v[62:63], v[182:183], v[66:67], v[62:63] op_sel_hi:[0,1,1]
	v_pk_fma_f32 v[56:57], v[182:183], v[68:69], v[56:57] op_sel_hi:[0,1,1]
	v_pk_fma_f32 v[58:59], v[182:183], v[70:71], v[58:59] op_sel_hi:[0,1,1]
	v_cvt_pk_f32_fp8_e32 v[64:65], v218
	v_cvt_pk_f32_fp8_sdwa v[66:67], v218 src0_sel:WORD_1
	v_cvt_pk_f32_fp8_e32 v[68:69], v219
	v_cvt_pk_f32_fp8_sdwa v[70:71], v219 src0_sel:WORD_1
	v_pk_fma_f32 v[52:53], v[182:183], v[64:65], v[52:53] op_sel_hi:[0,1,1]
	v_pk_fma_f32 v[54:55], v[182:183], v[66:67], v[54:55] op_sel_hi:[0,1,1]
	v_pk_fma_f32 v[48:49], v[182:183], v[68:69], v[48:49] op_sel_hi:[0,1,1]
	v_pk_fma_f32 v[50:51], v[182:183], v[70:71], v[50:51] op_sel_hi:[0,1,1]
	v_cvt_pk_f32_fp8_e32 v[64:65], v220
	v_cvt_pk_f32_fp8_sdwa v[66:67], v220 src0_sel:WORD_1
	v_cvt_pk_f32_fp8_e32 v[68:69], v221
	v_cvt_pk_f32_fp8_sdwa v[70:71], v221 src0_sel:WORD_1
	v_pk_fma_f32 v[44:45], v[182:183], v[64:65], v[44:45] op_sel_hi:[0,1,1]
	v_pk_fma_f32 v[46:47], v[182:183], v[66:67], v[46:47] op_sel_hi:[0,1,1]
	v_pk_fma_f32 v[40:41], v[182:183], v[68:69], v[40:41] op_sel_hi:[0,1,1]
	v_pk_fma_f32 v[42:43], v[182:183], v[70:71], v[42:43] op_sel_hi:[0,1,1]
	v_cvt_pk_f32_fp8_e32 v[64:65], v222
	v_cvt_pk_f32_fp8_sdwa v[66:67], v222 src0_sel:WORD_1
	v_cvt_pk_f32_fp8_e32 v[68:69], v223
	v_cvt_pk_f32_fp8_sdwa v[70:71], v223 src0_sel:WORD_1
	v_pk_fma_f32 v[36:37], v[182:183], v[64:65], v[36:37] op_sel_hi:[0,1,1]
	v_pk_fma_f32 v[38:39], v[182:183], v[66:67], v[38:39] op_sel_hi:[0,1,1]
	v_pk_fma_f32 v[32:33], v[182:183], v[68:69], v[32:33] op_sel_hi:[0,1,1]
	v_pk_fma_f32 v[34:35], v[182:183], v[70:71], v[34:35] op_sel_hi:[0,1,1]
	s_nop 1
	v_readlane_b32 s100, v174, 2
	v_readlane_b32 s50, v179, 12
	s_lshl_b32 s100, s100, 11
	s_add_u32 s100, s96, s100
	s_addc_u32 s101, s97, 0
	global_load_dwordx4 v[80:83], v178, s[100:101]
	global_load_dwordx4 v[84:87], v178, s[100:101] offset:1024
	s_waitcnt vmcnt(12)
	v_mov_b32_e32 v182, s50
	v_cvt_pk_f32_fp8_e32 v[64:65], v224
	v_cvt_pk_f32_fp8_sdwa v[66:67], v224 src0_sel:WORD_1
	v_cvt_pk_f32_fp8_e32 v[68:69], v225
	v_cvt_pk_f32_fp8_sdwa v[70:71], v225 src0_sel:WORD_1
	v_pk_fma_f32 v[60:61], v[182:183], v[64:65], v[60:61] op_sel_hi:[0,1,1]
	v_pk_fma_f32 v[62:63], v[182:183], v[66:67], v[62:63] op_sel_hi:[0,1,1]
	v_pk_fma_f32 v[56:57], v[182:183], v[68:69], v[56:57] op_sel_hi:[0,1,1]
	v_pk_fma_f32 v[58:59], v[182:183], v[70:71], v[58:59] op_sel_hi:[0,1,1]
	v_cvt_pk_f32_fp8_e32 v[64:65], v226
	v_cvt_pk_f32_fp8_sdwa v[66:67], v226 src0_sel:WORD_1
	v_cvt_pk_f32_fp8_e32 v[68:69], v227
	v_cvt_pk_f32_fp8_sdwa v[70:71], v227 src0_sel:WORD_1
	v_pk_fma_f32 v[52:53], v[182:183], v[64:65], v[52:53] op_sel_hi:[0,1,1]
	v_pk_fma_f32 v[54:55], v[182:183], v[66:67], v[54:55] op_sel_hi:[0,1,1]
	v_pk_fma_f32 v[48:49], v[182:183], v[68:69], v[48:49] op_sel_hi:[0,1,1]
	v_pk_fma_f32 v[50:51], v[182:183], v[70:71], v[50:51] op_sel_hi:[0,1,1]
	v_cvt_pk_f32_fp8_e32 v[64:65], v228
	v_cvt_pk_f32_fp8_sdwa v[66:67], v228 src0_sel:WORD_1
	v_cvt_pk_f32_fp8_e32 v[68:69], v229
	v_cvt_pk_f32_fp8_sdwa v[70:71], v229 src0_sel:WORD_1
	v_pk_fma_f32 v[44:45], v[182:183], v[64:65], v[44:45] op_sel_hi:[0,1,1]
	v_pk_fma_f32 v[46:47], v[182:183], v[66:67], v[46:47] op_sel_hi:[0,1,1]
	v_pk_fma_f32 v[40:41], v[182:183], v[68:69], v[40:41] op_sel_hi:[0,1,1]
	v_pk_fma_f32 v[42:43], v[182:183], v[70:71], v[42:43] op_sel_hi:[0,1,1]
	v_cvt_pk_f32_fp8_e32 v[64:65], v230
	v_cvt_pk_f32_fp8_sdwa v[66:67], v230 src0_sel:WORD_1
	v_cvt_pk_f32_fp8_e32 v[68:69], v231
	v_cvt_pk_f32_fp8_sdwa v[70:71], v231 src0_sel:WORD_1
	v_pk_fma_f32 v[36:37], v[182:183], v[64:65], v[36:37] op_sel_hi:[0,1,1]
	v_pk_fma_f32 v[38:39], v[182:183], v[66:67], v[38:39] op_sel_hi:[0,1,1]
	v_pk_fma_f32 v[32:33], v[182:183], v[68:69], v[32:33] op_sel_hi:[0,1,1]
	v_pk_fma_f32 v[34:35], v[182:183], v[70:71], v[34:35] op_sel_hi:[0,1,1]
	s_nop 1
	v_readlane_b32 s100, v174, 3
	v_readlane_b32 s50, v179, 13
	s_lshl_b32 s100, s100, 11
	s_add_u32 s100, s96, s100
	s_addc_u32 s101, s97, 0
	global_load_dwordx4 v[88:91], v178, s[100:101]
	global_load_dwordx4 v[92:95], v178, s[100:101] offset:1024
	s_waitcnt vmcnt(12)
	v_mov_b32_e32 v182, s50
	v_cvt_pk_f32_fp8_e32 v[64:65], v232
	v_cvt_pk_f32_fp8_sdwa v[66:67], v232 src0_sel:WORD_1
	v_cvt_pk_f32_fp8_e32 v[68:69], v233
	v_cvt_pk_f32_fp8_sdwa v[70:71], v233 src0_sel:WORD_1
	v_pk_fma_f32 v[60:61], v[182:183], v[64:65], v[60:61] op_sel_hi:[0,1,1]
	v_pk_fma_f32 v[62:63], v[182:183], v[66:67], v[62:63] op_sel_hi:[0,1,1]
	v_pk_fma_f32 v[56:57], v[182:183], v[68:69], v[56:57] op_sel_hi:[0,1,1]
	v_pk_fma_f32 v[58:59], v[182:183], v[70:71], v[58:59] op_sel_hi:[0,1,1]
	v_cvt_pk_f32_fp8_e32 v[64:65], v234
	v_cvt_pk_f32_fp8_sdwa v[66:67], v234 src0_sel:WORD_1
	v_cvt_pk_f32_fp8_e32 v[68:69], v235
	v_cvt_pk_f32_fp8_sdwa v[70:71], v235 src0_sel:WORD_1
	v_pk_fma_f32 v[52:53], v[182:183], v[64:65], v[52:53] op_sel_hi:[0,1,1]
	v_pk_fma_f32 v[54:55], v[182:183], v[66:67], v[54:55] op_sel_hi:[0,1,1]
	v_pk_fma_f32 v[48:49], v[182:183], v[68:69], v[48:49] op_sel_hi:[0,1,1]
	v_pk_fma_f32 v[50:51], v[182:183], v[70:71], v[50:51] op_sel_hi:[0,1,1]
	v_cvt_pk_f32_fp8_e32 v[64:65], v236
	v_cvt_pk_f32_fp8_sdwa v[66:67], v236 src0_sel:WORD_1
	v_cvt_pk_f32_fp8_e32 v[68:69], v237
	v_cvt_pk_f32_fp8_sdwa v[70:71], v237 src0_sel:WORD_1
	v_pk_fma_f32 v[44:45], v[182:183], v[64:65], v[44:45] op_sel_hi:[0,1,1]
	v_pk_fma_f32 v[46:47], v[182:183], v[66:67], v[46:47] op_sel_hi:[0,1,1]
	v_pk_fma_f32 v[40:41], v[182:183], v[68:69], v[40:41] op_sel_hi:[0,1,1]
	v_pk_fma_f32 v[42:43], v[182:183], v[70:71], v[42:43] op_sel_hi:[0,1,1]
	v_cvt_pk_f32_fp8_e32 v[64:65], v238
	v_cvt_pk_f32_fp8_sdwa v[66:67], v238 src0_sel:WORD_1
	v_cvt_pk_f32_fp8_e32 v[68:69], v239
	v_cvt_pk_f32_fp8_sdwa v[70:71], v239 src0_sel:WORD_1
	v_pk_fma_f32 v[36:37], v[182:183], v[64:65], v[36:37] op_sel_hi:[0,1,1]
	v_pk_fma_f32 v[38:39], v[182:183], v[66:67], v[38:39] op_sel_hi:[0,1,1]
	v_pk_fma_f32 v[32:33], v[182:183], v[68:69], v[32:33] op_sel_hi:[0,1,1]
	v_pk_fma_f32 v[34:35], v[182:183], v[70:71], v[34:35] op_sel_hi:[0,1,1]
	s_nop 1
	v_readlane_b32 s100, v174, 4
	v_readlane_b32 s50, v179, 14
	s_lshl_b32 s100, s100, 11
	s_add_u32 s100, s96, s100
	s_addc_u32 s101, s97, 0
	global_load_dwordx4 v[96:99], v178, s[100:101]
	global_load_dwordx4 v[100:103], v178, s[100:101] offset:1024
	s_waitcnt vmcnt(12)
	v_mov_b32_e32 v182, s50
	v_cvt_pk_f32_fp8_e32 v[64:65], v242
	v_cvt_pk_f32_fp8_sdwa v[66:67], v242 src0_sel:WORD_1
	v_cvt_pk_f32_fp8_e32 v[68:69], v243
	v_cvt_pk_f32_fp8_sdwa v[70:71], v243 src0_sel:WORD_1
	v_pk_fma_f32 v[60:61], v[182:183], v[64:65], v[60:61] op_sel_hi:[0,1,1]
	v_pk_fma_f32 v[62:63], v[182:183], v[66:67], v[62:63] op_sel_hi:[0,1,1]
	v_pk_fma_f32 v[56:57], v[182:183], v[68:69], v[56:57] op_sel_hi:[0,1,1]
	v_pk_fma_f32 v[58:59], v[182:183], v[70:71], v[58:59] op_sel_hi:[0,1,1]
	v_cvt_pk_f32_fp8_e32 v[64:65], v244
	v_cvt_pk_f32_fp8_sdwa v[66:67], v244 src0_sel:WORD_1
	v_cvt_pk_f32_fp8_e32 v[68:69], v245
	v_cvt_pk_f32_fp8_sdwa v[70:71], v245 src0_sel:WORD_1
	v_pk_fma_f32 v[52:53], v[182:183], v[64:65], v[52:53] op_sel_hi:[0,1,1]
	v_pk_fma_f32 v[54:55], v[182:183], v[66:67], v[54:55] op_sel_hi:[0,1,1]
	v_pk_fma_f32 v[48:49], v[182:183], v[68:69], v[48:49] op_sel_hi:[0,1,1]
	v_pk_fma_f32 v[50:51], v[182:183], v[70:71], v[50:51] op_sel_hi:[0,1,1]
	v_cvt_pk_f32_fp8_e32 v[64:65], v246
	v_cvt_pk_f32_fp8_sdwa v[66:67], v246 src0_sel:WORD_1
	v_cvt_pk_f32_fp8_e32 v[68:69], v247
	v_cvt_pk_f32_fp8_sdwa v[70:71], v247 src0_sel:WORD_1
	v_pk_fma_f32 v[44:45], v[182:183], v[64:65], v[44:45] op_sel_hi:[0,1,1]
	v_pk_fma_f32 v[46:47], v[182:183], v[66:67], v[46:47] op_sel_hi:[0,1,1]
	v_pk_fma_f32 v[40:41], v[182:183], v[68:69], v[40:41] op_sel_hi:[0,1,1]
	v_pk_fma_f32 v[42:43], v[182:183], v[70:71], v[42:43] op_sel_hi:[0,1,1]
	v_cvt_pk_f32_fp8_e32 v[64:65], v248
	v_cvt_pk_f32_fp8_sdwa v[66:67], v248 src0_sel:WORD_1
	v_cvt_pk_f32_fp8_e32 v[68:69], v249
	v_cvt_pk_f32_fp8_sdwa v[70:71], v249 src0_sel:WORD_1
	v_pk_fma_f32 v[36:37], v[182:183], v[64:65], v[36:37] op_sel_hi:[0,1,1]
	v_pk_fma_f32 v[38:39], v[182:183], v[66:67], v[38:39] op_sel_hi:[0,1,1]
	v_pk_fma_f32 v[32:33], v[182:183], v[68:69], v[32:33] op_sel_hi:[0,1,1]
	v_pk_fma_f32 v[34:35], v[182:183], v[70:71], v[34:35] op_sel_hi:[0,1,1]
	s_nop 1
	v_readlane_b32 s100, v174, 5
	v_readlane_b32 s50, v179, 15
	s_lshl_b32 s100, s100, 11
	s_add_u32 s100, s96, s100
	s_addc_u32 s101, s97, 0
	global_load_dwordx4 v[104:107], v178, s[100:101]
	global_load_dwordx4 v[108:111], v178, s[100:101] offset:1024
	s_waitcnt vmcnt(12)
	v_mov_b32_e32 v182, s50
	v_cvt_pk_f32_fp8_e32 v[64:65], v250
	v_cvt_pk_f32_fp8_sdwa v[66:67], v250 src0_sel:WORD_1
	v_cvt_pk_f32_fp8_e32 v[68:69], v251
	v_cvt_pk_f32_fp8_sdwa v[70:71], v251 src0_sel:WORD_1
	v_pk_fma_f32 v[60:61], v[182:183], v[64:65], v[60:61] op_sel_hi:[0,1,1]
	v_pk_fma_f32 v[62:63], v[182:183], v[66:67], v[62:63] op_sel_hi:[0,1,1]
	v_pk_fma_f32 v[56:57], v[182:183], v[68:69], v[56:57] op_sel_hi:[0,1,1]
	v_pk_fma_f32 v[58:59], v[182:183], v[70:71], v[58:59] op_sel_hi:[0,1,1]
	v_cvt_pk_f32_fp8_e32 v[64:65], v252
	v_cvt_pk_f32_fp8_sdwa v[66:67], v252 src0_sel:WORD_1
	v_cvt_pk_f32_fp8_e32 v[68:69], v253
	v_cvt_pk_f32_fp8_sdwa v[70:71], v253 src0_sel:WORD_1
	v_pk_fma_f32 v[52:53], v[182:183], v[64:65], v[52:53] op_sel_hi:[0,1,1]
	v_pk_fma_f32 v[54:55], v[182:183], v[66:67], v[54:55] op_sel_hi:[0,1,1]
	v_pk_fma_f32 v[48:49], v[182:183], v[68:69], v[48:49] op_sel_hi:[0,1,1]
	v_pk_fma_f32 v[50:51], v[182:183], v[70:71], v[50:51] op_sel_hi:[0,1,1]
	v_cvt_pk_f32_fp8_e32 v[64:65], v76
	v_cvt_pk_f32_fp8_sdwa v[66:67], v76 src0_sel:WORD_1
	v_cvt_pk_f32_fp8_e32 v[68:69], v77
	v_cvt_pk_f32_fp8_sdwa v[70:71], v77 src0_sel:WORD_1
	v_pk_fma_f32 v[44:45], v[182:183], v[64:65], v[44:45] op_sel_hi:[0,1,1]
	v_pk_fma_f32 v[46:47], v[182:183], v[66:67], v[46:47] op_sel_hi:[0,1,1]
	v_pk_fma_f32 v[40:41], v[182:183], v[68:69], v[40:41] op_sel_hi:[0,1,1]
	v_pk_fma_f32 v[42:43], v[182:183], v[70:71], v[42:43] op_sel_hi:[0,1,1]
	v_cvt_pk_f32_fp8_e32 v[64:65], v78
	v_cvt_pk_f32_fp8_sdwa v[66:67], v78 src0_sel:WORD_1
	v_cvt_pk_f32_fp8_e32 v[68:69], v79
	v_cvt_pk_f32_fp8_sdwa v[70:71], v79 src0_sel:WORD_1
	v_pk_fma_f32 v[36:37], v[182:183], v[64:65], v[36:37] op_sel_hi:[0,1,1]
	v_pk_fma_f32 v[38:39], v[182:183], v[66:67], v[38:39] op_sel_hi:[0,1,1]
	v_pk_fma_f32 v[32:33], v[182:183], v[68:69], v[32:33] op_sel_hi:[0,1,1]
	v_pk_fma_f32 v[34:35], v[182:183], v[70:71], v[34:35] op_sel_hi:[0,1,1]
	s_branch .LBB0_2776
